# bf16 pair packing via v_cvt_pk_bf16_f32 in the remaining conversion/LN/fixup sites and the LRU y_b epilogue
# baseline (speedup 1.0000x reference)
;     if (ldw == 0) ldw = K;
;     const int nblk = N / 32, kb = item / nblk, nb = item % nblk, k0 = 64 * kb, n0 = 32 * nb;
;     float tv_[32];
; #pragma unroll
;     for (int i = 0; i < 32; ++i) tv_[i] = W[(size_t)(k0 + 2 * i + (lane >> 5)) * N + n0 + (lane & 31)];
; #pragma unroll
;     for (int i = 0; i < 32; ++i) scr[(2 * i + (lane >> 5)) * 33 + (lane & 31)] = tv_[i];
; __device__ __forceinline__ void convert_range(LAS unsigned char* lds, const Params& p, const int lo, const int hi, const int gw, const int NGW) {
;     ...
;     for (int it = lo + gw; it < hi; it += NGW) {
;         int r = it;
;         if (r < 2 * I_IN) { const int l = r / I_IN; r -= l * I_IN; p0_transpose_item(p.in[5] + (size_t)l * DM * NC, DM, NC, (bf16*)(ws + WS_WIN + l * SZ_WIN), scr, r, lane); continue; } r -= 2 * I_IN;
;         if (r < 2 * I_PA) { const int l = r / I_PA; r -= l * I_PA; p0_transpose_item(p.in[16] + (size_t)l * PW * DM, PW, DM, (bf16*)(ws + WS_WCAT + l * SZ_WCAT), scr, r, lane, KCAT, 0); continue; } r -= 2 * I_PA;
;         if (r < 2 * I_PB) { const int l = r / I_PB; r -= l * I_PB; p0_transpose_item(p.in[17] + (size_t)l * LW * DM, LW, DM, (bf16*)(ws + WS_WCAT + l * SZ_WCAT), scr, r, lane, KCAT, PW); continue; } r -= 2 * I_PB;
.LBB0_275:
	s_movk_i32 s6, 0x4fff
	v_cmp_lt_i32_e32 vcc, s6, v5
	v_lshlrev_b32_e32 v0, 2, v2
	s_waitcnt lgkmcnt(0)
	v_add_u32_e32 v26, 0x400, v19
	v_add_u32_e32 v25, 0x800, v19
	v_add_u32_e32 v24, 0xc00, v19
	v_add_u32_e32 v23, 0x1000, v19
	v_add_u32_e32 v22, 0x1400, v19
	v_add_u32_e32 v21, 0x1800, v19
	v_add_u32_e32 v9, 0x1c00, v19
	v_lshlrev_b32_e32 v8, 1, v4
	s_and_saveexec_b64 s[6:7], vcc
	s_xor_b64 s[40:41], exec, s[6:7]
	s_cbranch_execz .LBB0_277
	v_add_u32_e32 v6, 0xffffb000, v5
	v_lshrrev_b32_e32 v6, 10, v6
	v_mov_b32_e32 v7, v1
	v_readlane_b32 s44, v251, 9
	v_lshlrev_b64 v[10:11], 23, v[6:7]
	v_readlane_b32 s45, v251, 10
	v_mov_b64_e32 v[28:29], s[18:19]
	s_mov_b32 s6, 0xc00000
	v_and_b32_e32 v20, 0x7e0, v18
	v_lshl_add_u64 v[10:11], s[44:45], 0, v[10:11]
	v_mad_u64_u32 v[6:7], s[6:7], v6, s6, v[28:29]
	v_and_b32_e32 v27, 0x3c0, v5
	v_lshlrev_b32_e32 v28, 2, v20
	v_mov_b32_e32 v29, v1
	v_or_b32_e32 v30, v27, v12
	v_lshl_add_u64 v[10:11], v[10:11], 0, v[28:29]
	v_lshl_add_u64 v[10:11], v[10:11], 0, v[0:1]
	v_lshlrev_b32_e32 v0, 13, v30
	v_lshl_add_u64 v[10:11], v[10:11], 0, v[0:1]
	v_add_co_u32_e32 v28, vcc, s22, v10
	s_mov_b32 s6, 0x8000
	s_nop 0
	v_addc_co_u32_e32 v29, vcc, 0, v11, vcc
	global_load_dword v0, v[10:11], off
	global_load_dword v30, v[28:29], off
	v_add_co_u32_e32 v28, vcc, s6, v10
	s_mov_b32 s6, 0xc000
	s_nop 0
	v_addc_co_u32_e32 v29, vcc, 0, v11, vcc
	global_load_dword v31, v[28:29], off
	v_add_co_u32_e32 v28, vcc, s6, v10
	s_mov_b32 s6, 0x14000
	s_nop 0
	v_addc_co_u32_e32 v29, vcc, 0, v11, vcc
	global_load_dword v32, v[28:29], off
	v_add_co_u32_e32 v28, vcc, s15, v10
	v_readlane_b32 s46, v251, 11
	s_nop 0
	v_addc_co_u32_e32 v29, vcc, 0, v11, vcc
	global_load_dword v33, v[28:29], off
	v_add_co_u32_e32 v28, vcc, s6, v10
	s_mov_b32 s6, 0x18000
	s_nop 0
	v_addc_co_u32_e32 v29, vcc, 0, v11, vcc
	global_load_dword v34, v[28:29], off
	v_add_co_u32_e32 v28, vcc, s6, v10
	s_mov_b32 s6, 0x1c000
	s_nop 0
	v_addc_co_u32_e32 v29, vcc, 0, v11, vcc
	global_load_dword v35, v[28:29], off
	v_add_co_u32_e32 v28, vcc, s6, v10
	s_mov_b32 s6, 0x20000
	s_nop 0
	v_addc_co_u32_e32 v29, vcc, 0, v11, vcc
	global_load_dword v36, v[28:29], off
	v_add_co_u32_e32 v28, vcc, s6, v10
	s_mov_b32 s6, 0x24000
	s_nop 0
	v_addc_co_u32_e32 v29, vcc, 0, v11, vcc
	global_load_dword v37, v[28:29], off
	v_add_co_u32_e32 v28, vcc, s6, v10
	s_mov_b32 s6, 0x28000
	s_nop 0
	v_addc_co_u32_e32 v29, vcc, 0, v11, vcc
	global_load_dword v38, v[28:29], off
	v_add_co_u32_e32 v28, vcc, s6, v10
	s_mov_b32 s6, 0x2c000
	s_nop 0
	v_addc_co_u32_e32 v29, vcc, 0, v11, vcc
	global_load_dword v39, v[28:29], off
	v_add_co_u32_e32 v28, vcc, s6, v10
	s_mov_b32 s6, 0x30000
	s_nop 0
	v_addc_co_u32_e32 v29, vcc, 0, v11, vcc
	global_load_dword v40, v[28:29], off
	v_add_co_u32_e32 v28, vcc, s6, v10
	s_mov_b32 s6, 0x34000
	s_nop 0
	v_addc_co_u32_e32 v29, vcc, 0, v11, vcc
	global_load_dword v41, v[28:29], off
	v_add_co_u32_e32 v28, vcc, s6, v10
	s_mov_b32 s6, 0x38000
	s_nop 0
	v_addc_co_u32_e32 v29, vcc, 0, v11, vcc
	global_load_dword v42, v[28:29], off
	v_add_co_u32_e32 v28, vcc, s6, v10
	s_mov_b32 s6, 0x3c000
	s_nop 0
	v_addc_co_u32_e32 v29, vcc, 0, v11, vcc
	global_load_dword v43, v[28:29], off
	v_add_co_u32_e32 v28, vcc, s6, v10
	s_mov_b32 s6, 0x44000
	s_nop 0
	v_addc_co_u32_e32 v29, vcc, 0, v11, vcc
	global_load_dword v44, v[28:29], off
	v_add_co_u32_e32 v28, vcc, s14, v10
	v_readlane_b32 s47, v251, 12
	s_nop 0
	v_addc_co_u32_e32 v29, vcc, 0, v11, vcc
	global_load_dword v45, v[28:29], off
	v_add_co_u32_e32 v28, vcc, s6, v10
	s_mov_b32 s6, 0x48000
	s_nop 0
	v_addc_co_u32_e32 v29, vcc, 0, v11, vcc
	global_load_dword v46, v[28:29], off
	v_add_co_u32_e32 v28, vcc, s6, v10
	s_mov_b32 s6, 0x4c000
	s_nop 0
	v_addc_co_u32_e32 v29, vcc, 0, v11, vcc
	global_load_dword v47, v[28:29], off
	v_add_co_u32_e32 v28, vcc, s6, v10
	s_mov_b32 s6, 0x50000
	s_nop 0
	v_addc_co_u32_e32 v29, vcc, 0, v11, vcc
	global_load_dword v48, v[28:29], off
	v_add_co_u32_e32 v28, vcc, s6, v10
	s_mov_b32 s6, 0x54000
	s_nop 0
	v_addc_co_u32_e32 v29, vcc, 0, v11, vcc
	global_load_dword v49, v[28:29], off
	v_add_co_u32_e32 v28, vcc, s6, v10
	s_mov_b32 s6, 0x58000
	s_nop 0
	v_addc_co_u32_e32 v29, vcc, 0, v11, vcc
	global_load_dword v50, v[28:29], off
	v_add_co_u32_e32 v28, vcc, s6, v10
	s_mov_b32 s6, 0x5c000
	s_nop 0
	v_addc_co_u32_e32 v29, vcc, 0, v11, vcc
	global_load_dword v51, v[28:29], off
	v_add_co_u32_e32 v28, vcc, s6, v10
	s_mov_b32 s6, 0x60000
	s_nop 0
	v_addc_co_u32_e32 v29, vcc, 0, v11, vcc
	global_load_dword v52, v[28:29], off
	v_add_co_u32_e32 v28, vcc, s6, v10
	s_mov_b32 s6, 0x64000
	s_nop 0
	v_addc_co_u32_e32 v29, vcc, 0, v11, vcc
	global_load_dword v53, v[28:29], off
	v_add_co_u32_e32 v28, vcc, s6, v10
	s_mov_b32 s6, 0x68000
	s_nop 0
	v_addc_co_u32_e32 v29, vcc, 0, v11, vcc
	global_load_dword v54, v[28:29], off
	v_add_co_u32_e32 v28, vcc, s6, v10
	s_mov_b32 s6, 0x6c000
	s_nop 0
	v_addc_co_u32_e32 v29, vcc, 0, v11, vcc
	global_load_dword v55, v[28:29], off
	v_add_co_u32_e32 v28, vcc, s6, v10
	s_mov_b32 s6, 0x70000
	s_nop 0
	v_addc_co_u32_e32 v29, vcc, 0, v11, vcc
	global_load_dword v56, v[28:29], off
	v_add_co_u32_e32 v28, vcc, s6, v10
	s_mov_b32 s6, 0x74000
	s_nop 0
	v_addc_co_u32_e32 v29, vcc, 0, v11, vcc
	global_load_dword v57, v[28:29], off
	v_add_co_u32_e32 v28, vcc, s6, v10
	s_mov_b32 s6, 0x78000
	s_nop 0
	v_addc_co_u32_e32 v29, vcc, 0, v11, vcc
	global_load_dword v58, v[28:29], off
	v_add_co_u32_e32 v28, vcc, s6, v10
	s_mov_b32 s6, 0x7c000
	s_nop 0
	v_addc_co_u32_e32 v29, vcc, 0, v11, vcc
	v_add_co_u32_e32 v10, vcc, s6, v10
	global_load_dword v28, v[28:29], off
	s_nop 0
	v_addc_co_u32_e32 v11, vcc, 0, v11, vcc
	global_load_dword v10, v[10:11], off
	s_waitcnt vmcnt(30)
; #define LAS __attribute__((address_space(3)))
; #define LDS_WAIT() asm volatile("s_waitcnt lgkmcnt(0)" ::: "memory")
; __device__ __forceinline__ unsigned pk2(float lo, float hi) { return f2bf(lo) | (f2bf(hi) << 16); }
;     ...
;     for (int i = 0; i < 32; ++i) scr[(2 * i + (lane >> 5)) * 33 + (lane & 31)] = tv_[i];
;     LDS_WAIT(); asm volatile("" ::: "memory");
;     const int c = lane & 7;
; #pragma unroll
;     for (int j = 0; j < 4; ++j) { const int n = (lane >> 3) + 8 * j; const LAS float* s = scr + (8 * c) * 33 + n;
;         v4u o; o.x = pk2(s[0 * 33], s[1 * 33]); o.y = pk2(s[2 * 33], s[3 * 33]); o.z = pk2(s[4 * 33], s[5 * 33]); o.w = pk2(s[6 * 33], s[7 * 33]);
;         *(v4u*)(WT + (size_t)(n0 + n) * ldw + koff + k0 + 8 * c) = o; }
;     LDS_WAIT(); asm volatile("" ::: "memory");
	ds_write2_b32 v19, v0, v30 offset1:66
	s_waitcnt vmcnt(28)
	ds_write2_b32 v19, v31, v32 offset0:132 offset1:198
	s_waitcnt vmcnt(26)
	ds_write2_b32 v26, v33, v34 offset0:8 offset1:74
	s_waitcnt vmcnt(24)
	ds_write2_b32 v26, v35, v36 offset0:140 offset1:206
	s_waitcnt vmcnt(22)
	ds_write2_b32 v25, v37, v38 offset0:16 offset1:82
	s_waitcnt vmcnt(20)
	ds_write2_b32 v25, v39, v40 offset0:148 offset1:214
	s_waitcnt vmcnt(18)
	ds_write2_b32 v24, v41, v42 offset0:24 offset1:90
	s_waitcnt vmcnt(16)
	ds_write2_b32 v24, v43, v44 offset0:156 offset1:222
	s_waitcnt vmcnt(14)
	ds_write2_b32 v23, v45, v46 offset0:32 offset1:98
	s_waitcnt vmcnt(12)
	ds_write2_b32 v23, v47, v48 offset0:164 offset1:230
	s_waitcnt vmcnt(10)
	ds_write2_b32 v22, v49, v50 offset0:40 offset1:106
	s_waitcnt vmcnt(8)
	ds_write2_b32 v22, v51, v52 offset0:172 offset1:238
	s_waitcnt vmcnt(6)
	ds_write2_b32 v21, v53, v54 offset0:48 offset1:114
	s_waitcnt vmcnt(4)
	ds_write2_b32 v21, v55, v56 offset0:180 offset1:246
	s_waitcnt vmcnt(2)
	ds_write2_b32 v9, v57, v58 offset0:56 offset1:122
	s_waitcnt vmcnt(0)
	ds_write2_b32 v9, v28, v10 offset0:188 offset1:254
	s_waitcnt lgkmcnt(0)
	v_lshlrev_b32_e32 v0, 1, v27
	v_lshl_add_u64 v[6:7], v[6:7], 0, v[0:1]
	v_mov_b32_e32 v9, v1
	v_lshl_add_u64 v[6:7], v[6:7], 0, v[8:9]
	ds_read_b32 v0, v14
	ds_read_b32 v8, v14 offset:132
	v_readlane_b32 s48, v251, 13
	v_readlane_b32 s49, v251, 14
	v_readlane_b32 s50, v251, 15
	s_waitcnt lgkmcnt(0)
	v_cvt_pk_bf16_f32 v8, v0, v8
	ds_read_b32 v0, v14 offset:264
	ds_read_b32 v9, v14 offset:396
	v_readlane_b32 s51, v251, 16
	s_waitcnt lgkmcnt(1)
	s_waitcnt lgkmcnt(0)
	v_cvt_pk_bf16_f32 v9, v0, v9
	ds_read_b32 v0, v14 offset:528
	ds_read_b32 v10, v14 offset:660
	s_waitcnt lgkmcnt(1)
	s_waitcnt lgkmcnt(0)
	v_cvt_pk_bf16_f32 v10, v0, v10
	ds_read_b32 v0, v14 offset:792
	ds_read_b32 v11, v14 offset:924
	s_waitcnt lgkmcnt(1)
	s_waitcnt lgkmcnt(0)
	v_cvt_pk_bf16_f32 v11, v0, v11
	v_or_b32_e32 v0, v20, v13
	v_mul_u32_u24_e32 v0, 0xc00, v0
	v_lshlrev_b32_e32 v0, 1, v0
	v_lshl_add_u64 v[22:23], v[6:7], 0, v[0:1]
	global_store_dwordx4 v[22:23], v[8:11], off
	ds_read_b32 v0, v14 offset:32
	ds_read_b32 v8, v14 offset:164
	s_waitcnt lgkmcnt(0)
	v_cvt_pk_bf16_f32 v8, v0, v8
	ds_read_b32 v0, v14 offset:296
	ds_read_b32 v9, v14 offset:428
	s_waitcnt lgkmcnt(0)
	v_cvt_pk_bf16_f32 v9, v0, v9
	ds_read_b32 v0, v14 offset:560
	ds_read_b32 v10, v14 offset:692
	s_waitcnt lgkmcnt(0)
	v_cvt_pk_bf16_f32 v10, v0, v10
	ds_read_b32 v0, v14 offset:824
	ds_read_b32 v11, v14 offset:956
	s_waitcnt lgkmcnt(0)
	v_cvt_pk_bf16_f32 v11, v0, v11
	v_or_b32_e32 v0, v20, v15
	v_mul_u32_u24_e32 v0, 0xc00, v0
	v_lshlrev_b32_e32 v0, 1, v0
	v_lshl_add_u64 v[22:23], v[6:7], 0, v[0:1]
	global_store_dwordx4 v[22:23], v[8:11], off
	ds_read_b32 v0, v14 offset:64
	ds_read_b32 v8, v14 offset:196
	s_waitcnt lgkmcnt(0)
	v_cvt_pk_bf16_f32 v8, v0, v8
	ds_read_b32 v0, v14 offset:328
	ds_read_b32 v9, v14 offset:460
	s_waitcnt lgkmcnt(0)
	v_cvt_pk_bf16_f32 v9, v0, v9
	ds_read_b32 v0, v14 offset:592
	ds_read_b32 v10, v14 offset:724
	s_waitcnt lgkmcnt(0)
	v_cvt_pk_bf16_f32 v10, v0, v10
	ds_read_b32 v0, v14 offset:856
	ds_read_b32 v11, v14 offset:988
	s_waitcnt lgkmcnt(0)
	v_cvt_pk_bf16_f32 v11, v0, v11
	v_or_b32_e32 v0, v20, v16
	v_mul_u32_u24_e32 v0, 0xc00, v0
	v_lshlrev_b32_e32 v0, 1, v0
	v_lshl_add_u64 v[22:23], v[6:7], 0, v[0:1]
	global_store_dwordx4 v[22:23], v[8:11], off
	ds_read_b32 v0, v14 offset:96
	ds_read_b32 v8, v14 offset:228
	s_waitcnt lgkmcnt(0)
	v_cvt_pk_bf16_f32 v8, v0, v8
	ds_read_b32 v0, v14 offset:360
	ds_read_b32 v9, v14 offset:492
	s_waitcnt lgkmcnt(0)
	v_cvt_pk_bf16_f32 v9, v0, v9
	ds_read_b32 v0, v14 offset:624
	ds_read_b32 v10, v14 offset:756
	s_waitcnt lgkmcnt(0)
	v_cvt_pk_bf16_f32 v10, v0, v10
	ds_read_b32 v0, v14 offset:888
	ds_read_b32 v11, v14 offset:1020
	s_waitcnt lgkmcnt(0)
	v_bfe_u32 v21, v0, 16, 1
	v_add3_u32 v0, v0, v21, s26
	v_bfe_u32 v21, v11, 16, 1
	v_lshrrev_b32_e32 v0, 16, v0
	v_add3_u32 v11, v11, v21, s26
	v_and_or_b32 v11, v11, s24, v0
	v_or_b32_e32 v0, v20, v17
	v_mul_u32_u24_e32 v0, 0xc00, v0
	v_lshlrev_b32_e32 v0, 1, v0
	v_lshl_add_u64 v[6:7], v[6:7], 0, v[0:1]
	global_store_dwordx4 v[6:7], v[8:11], off
	s_waitcnt lgkmcnt(0)
.LBB0_277:
	s_andn2_saveexec_b64 s[40:41], s[40:41]
	s_cbranch_execz .LBB0_274
;     if (ldw == 0) ldw = K;
;     const int nblk = N / 32, kb = item / nblk, nb = item % nblk, k0 = 64 * kb, n0 = 32 * nb;
;     float tv_[32];
; #pragma unroll
;     for (int i = 0; i < 32; ++i) tv_[i] = W[(size_t)(k0 + 2 * i + (lane >> 5)) * N + n0 + (lane & 31)];
; #pragma unroll
;     for (int i = 0; i < 32; ++i) scr[(2 * i + (lane >> 5)) * 33 + (lane & 31)] = tv_[i];
; __device__ __forceinline__ void convert_range(LAS unsigned char* lds, const Params& p, const int lo, const int hi, const int gw, const int NGW) {
;     ...
;         if (r < 2 * I_IN) { const int l = r / I_IN; r -= l * I_IN; p0_transpose_item(p.in[5] + (size_t)l * DM * NC, DM, NC, (bf16*)(ws + WS_WIN + l * SZ_WIN), scr, r, lane); continue; } r -= 2 * I_IN;
	v_mul_hi_i32 v6, v5, s5
	v_lshrrev_b32_e32 v7, 31, v6
	v_ashrrev_i32_e32 v6, 12, v6
	v_add_u32_e32 v11, v6, v7
	v_readlane_b32 s60, v251, 21
	v_mul_i32_i24_e32 v6, 0xffffd800, v11
	v_readlane_b32 s70, v251, 31
	v_readlane_b32 s71, v251, 32
	v_add_u32_e32 v10, v6, v5
	s_mov_b32 s6, 0x5000000
	v_mov_b64_e32 v[6:7], s[70:71]
	v_mad_i64_i32 v[28:29], s[6:7], v11, s6, v[6:7]
	v_mul_hi_i32 v6, v10, s5
	v_lshrrev_b32_e32 v7, 31, v6
	v_ashrrev_i32_e32 v6, 7, v6
	v_add_u32_e32 v6, v6, v7
	v_mul_i32_i24_e32 v7, 0x140, v6
	v_sub_u32_e32 v7, v10, v7
	v_lshlrev_b32_e32 v10, 6, v6
	v_lshlrev_b32_e32 v6, 5, v7
	v_ashrrev_i32_e32 v7, 31, v6
	v_lshl_add_u64 v[28:29], v[6:7], 2, v[28:29]
	v_or_b32_e32 v20, v10, v12
	v_lshl_add_u64 v[28:29], v[28:29], 0, v[0:1]
	v_mad_i64_i32 v[30:31], s[6:7], v20, s23, v[28:29]
	v_or_b32_e32 v7, 2, v20
	global_load_dword v0, v[30:31], off
	v_mad_i64_i32 v[30:31], s[6:7], v7, s23, v[28:29]
	v_or_b32_e32 v27, 4, v20
	global_load_dword v7, v[30:31], off
	v_mad_i64_i32 v[30:31], s[6:7], v27, s23, v[28:29]
	global_load_dword v27, v[30:31], off
	v_or_b32_e32 v30, 6, v20
	v_mad_i64_i32 v[30:31], s[6:7], v30, s23, v[28:29]
	global_load_dword v32, v[30:31], off
	v_or_b32_e32 v30, 8, v20
	v_mad_i64_i32 v[30:31], s[6:7], v30, s23, v[28:29]
	global_load_dword v33, v[30:31], off
	v_or_b32_e32 v30, 10, v20
	v_mad_i64_i32 v[30:31], s[6:7], v30, s23, v[28:29]
	global_load_dword v34, v[30:31], off
	v_or_b32_e32 v30, 12, v20
	v_mad_i64_i32 v[30:31], s[6:7], v30, s23, v[28:29]
	global_load_dword v35, v[30:31], off
	v_or_b32_e32 v30, 14, v20
	v_mad_i64_i32 v[30:31], s[6:7], v30, s23, v[28:29]
	global_load_dword v36, v[30:31], off
	v_or_b32_e32 v30, 16, v20
	v_mad_i64_i32 v[30:31], s[6:7], v30, s23, v[28:29]
	global_load_dword v37, v[30:31], off
	v_or_b32_e32 v30, 18, v20
	v_mad_i64_i32 v[30:31], s[6:7], v30, s23, v[28:29]
	global_load_dword v38, v[30:31], off
	v_or_b32_e32 v30, 20, v20
	v_mad_i64_i32 v[30:31], s[6:7], v30, s23, v[28:29]
	global_load_dword v39, v[30:31], off
	v_or_b32_e32 v30, 22, v20
	v_mad_i64_i32 v[30:31], s[6:7], v30, s23, v[28:29]
	global_load_dword v40, v[30:31], off
	v_or_b32_e32 v30, 24, v20
	v_mad_i64_i32 v[30:31], s[6:7], v30, s23, v[28:29]
	global_load_dword v41, v[30:31], off
	v_or_b32_e32 v30, 26, v20
	v_mad_i64_i32 v[30:31], s[6:7], v30, s23, v[28:29]
	global_load_dword v42, v[30:31], off
	v_or_b32_e32 v30, 28, v20
	v_mad_i64_i32 v[30:31], s[6:7], v30, s23, v[28:29]
	global_load_dword v43, v[30:31], off
	v_or_b32_e32 v30, 30, v20
	v_mad_i64_i32 v[30:31], s[6:7], v30, s23, v[28:29]
	global_load_dword v44, v[30:31], off
	v_or_b32_e32 v30, 32, v20
	v_mad_i64_i32 v[30:31], s[6:7], v30, s23, v[28:29]
	global_load_dword v45, v[30:31], off
	v_or_b32_e32 v30, 34, v20
	v_mad_i64_i32 v[30:31], s[6:7], v30, s23, v[28:29]
	global_load_dword v46, v[30:31], off
	v_or_b32_e32 v30, 36, v20
	v_mad_i64_i32 v[30:31], s[6:7], v30, s23, v[28:29]
	global_load_dword v47, v[30:31], off
	v_or_b32_e32 v30, 38, v20
	v_mad_i64_i32 v[30:31], s[6:7], v30, s23, v[28:29]
	global_load_dword v48, v[30:31], off
	v_or_b32_e32 v30, 40, v20
	v_mad_i64_i32 v[30:31], s[6:7], v30, s23, v[28:29]
	global_load_dword v49, v[30:31], off
	v_or_b32_e32 v30, 42, v20
	v_mad_i64_i32 v[30:31], s[6:7], v30, s23, v[28:29]
	global_load_dword v50, v[30:31], off
	v_or_b32_e32 v30, 44, v20
	v_mad_i64_i32 v[30:31], s[6:7], v30, s23, v[28:29]
	global_load_dword v51, v[30:31], off
	v_or_b32_e32 v30, 46, v20
	v_mad_i64_i32 v[30:31], s[6:7], v30, s23, v[28:29]
	global_load_dword v52, v[30:31], off
	v_or_b32_e32 v30, 48, v20
	v_mad_i64_i32 v[30:31], s[6:7], v30, s23, v[28:29]
	global_load_dword v53, v[30:31], off
	v_or_b32_e32 v30, 50, v20
	v_mad_i64_i32 v[30:31], s[6:7], v30, s23, v[28:29]
	global_load_dword v54, v[30:31], off
	v_or_b32_e32 v30, 52, v20
	v_mad_i64_i32 v[30:31], s[6:7], v30, s23, v[28:29]
	global_load_dword v55, v[30:31], off
	v_or_b32_e32 v30, 54, v20
	v_mad_i64_i32 v[30:31], s[6:7], v30, s23, v[28:29]
	global_load_dword v56, v[30:31], off
	v_or_b32_e32 v30, 56, v20
	v_mad_i64_i32 v[30:31], s[6:7], v30, s23, v[28:29]
	global_load_dword v57, v[30:31], off
	v_or_b32_e32 v30, 58, v20
	v_mad_i64_i32 v[30:31], s[6:7], v30, s23, v[28:29]
	global_load_dword v58, v[30:31], off
	v_or_b32_e32 v30, 60, v20
	v_or_b32_e32 v20, 62, v20
	v_mad_i64_i32 v[30:31], s[6:7], v30, s23, v[28:29]
	v_mad_i64_i32 v[28:29], s[6:7], v20, s23, v[28:29]
	global_load_dword v30, v[30:31], off
	s_mov_b32 s6, 0x2800000
	global_load_dword v20, v[28:29], off
	s_waitcnt vmcnt(30)
	ds_write2_b32 v19, v0, v7 offset1:66
	s_waitcnt vmcnt(28)
	ds_write2_b32 v19, v27, v32 offset0:132 offset1:198
	s_waitcnt vmcnt(26)
	ds_write2_b32 v26, v33, v34 offset0:8 offset1:74
	s_waitcnt vmcnt(24)
	ds_write2_b32 v26, v35, v36 offset0:140 offset1:206
	s_waitcnt vmcnt(22)
	ds_write2_b32 v25, v37, v38 offset0:16 offset1:82
	s_waitcnt vmcnt(20)
	ds_write2_b32 v25, v39, v40 offset0:148 offset1:214
	s_waitcnt vmcnt(18)
	ds_write2_b32 v24, v41, v42 offset0:24 offset1:90
	s_waitcnt vmcnt(16)
	ds_write2_b32 v24, v43, v44 offset0:156 offset1:222
	s_waitcnt vmcnt(14)
	ds_write2_b32 v23, v45, v46 offset0:32 offset1:98
	s_waitcnt vmcnt(12)
	ds_write2_b32 v23, v47, v48 offset0:164 offset1:230
	s_waitcnt vmcnt(10)
	ds_write2_b32 v22, v49, v50 offset0:40 offset1:106
	s_waitcnt vmcnt(8)
	ds_write2_b32 v22, v51, v52 offset0:172 offset1:238
	s_waitcnt vmcnt(6)
	ds_write2_b32 v21, v53, v54 offset0:48 offset1:114
	s_waitcnt vmcnt(4)
	ds_write2_b32 v21, v55, v56 offset0:180 offset1:246
	s_waitcnt vmcnt(2)
	ds_write2_b32 v9, v57, v58 offset0:56 offset1:122
	s_waitcnt vmcnt(0)
; #define LAS __attribute__((address_space(3)))
; #define LDS_WAIT() asm volatile("s_waitcnt lgkmcnt(0)" ::: "memory")
; __device__ __forceinline__ unsigned pk2(float lo, float hi) { return f2bf(lo) | (f2bf(hi) << 16); }
;     ...
;     for (int i = 0; i < 32; ++i) scr[(2 * i + (lane >> 5)) * 33 + (lane & 31)] = tv_[i];
;     LDS_WAIT(); asm volatile("" ::: "memory");
;     const int c = lane & 7;
; #pragma unroll
;     for (int j = 0; j < 4; ++j) { const int n = (lane >> 3) + 8 * j; const LAS float* s = scr + (8 * c) * 33 + n;
;         v4u o; o.x = pk2(s[0 * 33], s[1 * 33]); o.y = pk2(s[2 * 33], s[3 * 33]); o.z = pk2(s[4 * 33], s[5 * 33]); o.w = pk2(s[6 * 33], s[7 * 33]);
;         *(v4u*)(WT + (size_t)(n0 + n) * ldw + koff + k0 + 8 * c) = o; }
;     LDS_WAIT(); asm volatile("" ::: "memory");
	ds_write2_b32 v9, v30, v20 offset0:188 offset1:254
	s_waitcnt lgkmcnt(0)
	ds_read_b32 v0, v14
	ds_read_b32 v7, v14 offset:132
	v_mov_b64_e32 v[28:29], s[0:1]
	v_mad_i64_i32 v[28:29], s[6:7], v11, s6, v[28:29]
	v_ashrrev_i32_e32 v11, 31, v10
	v_lshl_add_u64 v[10:11], v[10:11], 1, v[28:29]
	v_mov_b32_e32 v9, v1
	v_lshl_add_u64 v[8:9], v[10:11], 0, v[8:9]
	s_waitcnt lgkmcnt(0)
	v_bfe_u32 v10, v0, 16, 1
	v_add3_u32 v0, v0, v10, s26
	v_bfe_u32 v11, v7, 16, 1
	v_lshrrev_b32_e32 v0, 16, v0
	ds_read_b32 v10, v14 offset:264
	v_add3_u32 v7, v7, v11, s26
	v_and_or_b32 v20, v7, s24, v0
	ds_read_b32 v0, v14 offset:396
	v_readlane_b32 s72, v251, 33
	s_waitcnt lgkmcnt(1)
	v_bfe_u32 v7, v10, 16, 1
	v_add3_u32 v7, v10, v7, s26
	v_lshrrev_b32_e32 v7, 16, v7
	s_waitcnt lgkmcnt(0)
	v_bfe_u32 v11, v0, 16, 1
	ds_read_b32 v10, v14 offset:528
	v_add3_u32 v0, v0, v11, s26
	v_and_or_b32 v21, v0, s24, v7
	ds_read_b32 v0, v14 offset:660
	v_readlane_b32 s73, v251, 34
	s_waitcnt lgkmcnt(1)
	v_bfe_u32 v7, v10, 16, 1
	v_add3_u32 v7, v10, v7, s26
	ds_read_b32 v10, v14 offset:792
	s_waitcnt lgkmcnt(1)
	v_bfe_u32 v11, v0, 16, 1
	v_add3_u32 v0, v0, v11, s26
	ds_read_b32 v11, v14 offset:924
	v_lshrrev_b32_e32 v7, 16, v7
	v_and_or_b32 v22, v0, s24, v7
	s_waitcnt lgkmcnt(1)
	v_bfe_u32 v0, v10, 16, 1
	v_add3_u32 v0, v10, v0, s26
	s_waitcnt lgkmcnt(0)
	v_bfe_u32 v7, v11, 16, 1
	v_or_b32_e32 v10, v6, v13
	v_add3_u32 v7, v11, v7, s26
	v_ashrrev_i32_e32 v11, 31, v10
	v_lshrrev_b32_e32 v0, 16, v0
	v_lshlrev_b64 v[10:11], 12, v[10:11]
	v_and_or_b32 v23, v7, s24, v0
	v_lshl_add_u64 v[10:11], v[8:9], 0, v[10:11]
	global_store_dwordx4 v[10:11], v[20:23], off
	ds_read_b32 v0, v14 offset:32
	ds_read_b32 v7, v14 offset:164
	v_readlane_b32 s72, v248, 24
	v_readlane_b32 s73, v248, 25
	v_readlane_b32 s61, v251, 22
	s_waitcnt lgkmcnt(0)
	v_bfe_u32 v10, v0, 16, 1
	v_add3_u32 v0, v0, v10, s26
	v_bfe_u32 v11, v7, 16, 1
	v_lshrrev_b32_e32 v0, 16, v0
	ds_read_b32 v10, v14 offset:296
	v_add3_u32 v7, v7, v11, s26
	v_and_or_b32 v20, v7, s24, v0
	ds_read_b32 v0, v14 offset:428
	v_readlane_b32 s62, v251, 23
	s_waitcnt lgkmcnt(0)
	v_bfe_u32 v7, v10, 16, 1
	v_add3_u32 v7, v10, v7, s26
	v_lshrrev_b32_e32 v7, 16, v7
	v_bfe_u32 v11, v0, 16, 1
	ds_read_b32 v10, v14 offset:560
	v_add3_u32 v0, v0, v11, s26
	v_and_or_b32 v21, v0, s24, v7
	ds_read_b32 v0, v14 offset:692
	v_readlane_b32 s63, v251, 24
	s_waitcnt lgkmcnt(0)
	v_bfe_u32 v7, v10, 16, 1
	v_add3_u32 v7, v10, v7, s26
	ds_read_b32 v10, v14 offset:824
	v_bfe_u32 v11, v0, 16, 1
	v_add3_u32 v0, v0, v11, s26
	ds_read_b32 v11, v14 offset:956
	v_lshrrev_b32_e32 v7, 16, v7
	v_and_or_b32 v22, v0, s24, v7
	s_waitcnt lgkmcnt(0)
	v_bfe_u32 v0, v10, 16, 1
	v_add3_u32 v0, v10, v0, s26
	v_bfe_u32 v7, v11, 16, 1
	v_or_b32_e32 v10, v6, v15
	v_add3_u32 v7, v11, v7, s26
	v_ashrrev_i32_e32 v11, 31, v10
	v_lshrrev_b32_e32 v0, 16, v0
	v_lshlrev_b64 v[10:11], 12, v[10:11]
	v_and_or_b32 v23, v7, s24, v0
	v_lshl_add_u64 v[10:11], v[8:9], 0, v[10:11]
	global_store_dwordx4 v[10:11], v[20:23], off
	ds_read_b32 v0, v14 offset:64
	ds_read_b32 v7, v14 offset:196
	v_readlane_b32 s64, v251, 25
	v_readlane_b32 s65, v251, 26
	v_readlane_b32 s66, v251, 27
	s_waitcnt lgkmcnt(0)
	v_bfe_u32 v10, v0, 16, 1
	v_add3_u32 v0, v0, v10, s26
	v_bfe_u32 v11, v7, 16, 1
	v_lshrrev_b32_e32 v0, 16, v0
	ds_read_b32 v10, v14 offset:328
	v_add3_u32 v7, v7, v11, s26
	v_and_or_b32 v20, v7, s24, v0
	ds_read_b32 v0, v14 offset:460
	v_readlane_b32 s67, v251, 28
	s_waitcnt lgkmcnt(0)
	v_bfe_u32 v7, v10, 16, 1
	v_add3_u32 v7, v10, v7, s26
	v_lshrrev_b32_e32 v7, 16, v7
	v_bfe_u32 v11, v0, 16, 1
	ds_read_b32 v10, v14 offset:592
	v_add3_u32 v0, v0, v11, s26
	v_and_or_b32 v21, v0, s24, v7
	ds_read_b32 v0, v14 offset:724
	v_readlane_b32 s68, v251, 29
	s_waitcnt lgkmcnt(0)
	v_bfe_u32 v7, v10, 16, 1
	v_add3_u32 v7, v10, v7, s26
	ds_read_b32 v10, v14 offset:856
	v_bfe_u32 v11, v0, 16, 1
	v_add3_u32 v0, v0, v11, s26
	ds_read_b32 v11, v14 offset:988
	v_lshrrev_b32_e32 v7, 16, v7
	v_and_or_b32 v22, v0, s24, v7
	s_waitcnt lgkmcnt(0)
	v_bfe_u32 v0, v10, 16, 1
	v_add3_u32 v0, v10, v0, s26
	v_bfe_u32 v7, v11, 16, 1
	v_or_b32_e32 v10, v6, v16
	v_add3_u32 v7, v11, v7, s26
	v_ashrrev_i32_e32 v11, 31, v10
	v_lshrrev_b32_e32 v0, 16, v0
	v_lshlrev_b64 v[10:11], 12, v[10:11]
	v_and_or_b32 v23, v7, s24, v0
	v_lshl_add_u64 v[10:11], v[8:9], 0, v[10:11]
	global_store_dwordx4 v[10:11], v[20:23], off
	ds_read_b32 v0, v14 offset:96
	ds_read_b32 v7, v14 offset:228
	v_or_b32_e32 v6, v6, v17
	v_readlane_b32 s69, v251, 30
	v_readlane_b32 s74, v251, 35
	s_waitcnt lgkmcnt(0)
	v_bfe_u32 v10, v0, 16, 1
	v_add3_u32 v0, v0, v10, s26
	v_bfe_u32 v11, v7, 16, 1
	v_lshrrev_b32_e32 v0, 16, v0
	ds_read_b32 v10, v14 offset:360
	v_add3_u32 v7, v7, v11, s26
	v_and_or_b32 v20, v7, s24, v0
	ds_read_b32 v0, v14 offset:492
	v_readlane_b32 s75, v251, 36
	s_waitcnt lgkmcnt(0)
	v_bfe_u32 v7, v10, 16, 1
	v_add3_u32 v7, v10, v7, s26
	v_lshrrev_b32_e32 v7, 16, v7
	v_bfe_u32 v11, v0, 16, 1
	ds_read_b32 v10, v14 offset:624
	v_add3_u32 v0, v0, v11, s26
	v_and_or_b32 v21, v0, s24, v7
	ds_read_b32 v0, v14 offset:756
	s_waitcnt lgkmcnt(0)
	v_bfe_u32 v7, v10, 16, 1
	v_add3_u32 v7, v10, v7, s26
	ds_read_b32 v10, v14 offset:888
	v_bfe_u32 v11, v0, 16, 1
	v_add3_u32 v0, v0, v11, s26
	ds_read_b32 v11, v14 offset:1020
	v_lshrrev_b32_e32 v7, 16, v7
	v_and_or_b32 v22, v0, s24, v7
	s_waitcnt lgkmcnt(0)
	v_cvt_pk_bf16_f32 v23, v10, v11
	v_ashrrev_i32_e32 v7, 31, v6
	v_lshlrev_b64 v[6:7], 12, v[6:7]
	v_lshl_add_u64 v[6:7], v[8:9], 0, v[6:7]
	global_store_dwordx4 v[6:7], v[20:23], off
	s_waitcnt lgkmcnt(0)
	s_branch .LBB0_274

;     if (ldw == 0) ldw = K;
;     const int nblk = N / 32, kb = item / nblk, nb = item % nblk, k0 = 64 * kb, n0 = 32 * nb;
;     float tv_[32];
; #pragma unroll
;     for (int i = 0; i < 32; ++i) tv_[i] = W[(size_t)(k0 + 2 * i + (lane >> 5)) * N + n0 + (lane & 31)];
; #pragma unroll
;     for (int i = 0; i < 32; ++i) scr[(2 * i + (lane >> 5)) * 33 + (lane & 31)] = tv_[i];
; __device__ __forceinline__ void convert_range(LAS unsigned char* lds, const Params& p, const int lo, const int hi, const int gw, const int NGW) {
;     ...
;         if (r < 2 * I_PB) { const int l = r / I_PB; r -= l * I_PB; p0_transpose_item(p.in[17] + (size_t)l * LW * DM, LW, DM, (bf16*)(ws + WS_WCAT + l * SZ_WCAT), scr, r, lane, KCAT, PW); continue; } r -= 2 * I_PB;
.LBB0_282:
	v_add_u32_e32 v8, 0x5800, v18
	s_movk_i32 s6, 0x4fff
	v_cmp_lt_i32_e32 vcc, s6, v8
	s_and_saveexec_b64 s[6:7], vcc
	s_xor_b64 s[40:41], exec, s[6:7]
	s_cbranch_execz .LBB0_288
	s_movk_i32 s6, 0x57ff
	v_cmp_lt_u32_e32 vcc, s6, v8
	v_and_b32_e32 v19, 0x7e0, v17
	s_and_saveexec_b64 s[6:7], vcc
	s_xor_b64 s[42:43], exec, s[6:7]
	s_cbranch_execz .LBB0_285
	v_lshrrev_b32_e32 v0, 11, v18
	v_readlane_b32 s44, v251, 9
	v_lshlrev_b64 v[6:7], 24, v[0:1]
	v_readlane_b32 s46, v251, 11
	v_readlane_b32 s47, v251, 12
	s_mov_b32 s6, 0xc00000
	v_and_b32_e32 v22, 0x7c0, v8
	v_lshl_add_u64 v[20:21], s[46:47], 0, v[6:7]
	v_mov_b64_e32 v[6:7], s[0:1]
	v_mad_u64_u32 v[6:7], s[6:7], v0, s6, v[6:7]
	v_lshlrev_b32_e32 v0, 2, v19
	v_or_b32_e32 v23, v22, v10
	v_lshl_add_u64 v[8:9], v[20:21], 0, v[0:1]
	v_lshlrev_b32_e32 v0, 2, v2
	v_lshl_add_u64 v[8:9], v[8:9], 0, v[0:1]
	v_lshlrev_b32_e32 v0, 13, v23
	v_lshl_add_u64 v[8:9], v[8:9], 0, v[0:1]
	v_add_co_u32_e32 v20, vcc, s22, v8
	s_mov_b32 s6, 0x8000
	s_nop 0
	v_addc_co_u32_e32 v21, vcc, 0, v9, vcc
	global_load_dword v0, v[8:9], off
	global_load_dword v23, v[20:21], off
	v_add_co_u32_e32 v20, vcc, s6, v8
	s_mov_b32 s6, 0xc000
	s_nop 0
	v_addc_co_u32_e32 v21, vcc, 0, v9, vcc
	s_waitcnt lgkmcnt(0)
	global_load_dword v24, v[20:21], off
	v_add_co_u32_e32 v20, vcc, s6, v8
	s_mov_b32 s6, 0x14000
	s_nop 0
	v_addc_co_u32_e32 v21, vcc, 0, v9, vcc
	global_load_dword v25, v[20:21], off
	v_add_co_u32_e32 v20, vcc, s20, v8
	v_readlane_b32 s45, v251, 10
	s_nop 0
	v_addc_co_u32_e32 v21, vcc, 0, v9, vcc
	global_load_dword v26, v[20:21], off
	v_add_co_u32_e32 v20, vcc, s6, v8
	s_mov_b32 s6, 0x18000
	s_nop 0
	v_addc_co_u32_e32 v21, vcc, 0, v9, vcc
	global_load_dword v27, v[20:21], off
	v_add_co_u32_e32 v20, vcc, s6, v8
	s_mov_b32 s6, 0x1c000
	s_nop 0
	v_addc_co_u32_e32 v21, vcc, 0, v9, vcc
	global_load_dword v28, v[20:21], off
	v_add_co_u32_e32 v20, vcc, s6, v8
	s_mov_b32 s6, 0x20000
	s_nop 0
	v_addc_co_u32_e32 v21, vcc, 0, v9, vcc
	global_load_dword v29, v[20:21], off
	v_add_co_u32_e32 v20, vcc, s6, v8
	s_mov_b32 s6, 0x24000
	s_nop 0
	v_addc_co_u32_e32 v21, vcc, 0, v9, vcc
	global_load_dword v30, v[20:21], off
	v_add_co_u32_e32 v20, vcc, s6, v8
	s_mov_b32 s6, 0x28000
	s_nop 0
	v_addc_co_u32_e32 v21, vcc, 0, v9, vcc
	global_load_dword v31, v[20:21], off
	v_add_co_u32_e32 v20, vcc, s6, v8
	s_mov_b32 s6, 0x2c000
	s_nop 0
	v_addc_co_u32_e32 v21, vcc, 0, v9, vcc
	global_load_dword v32, v[20:21], off
	v_add_co_u32_e32 v20, vcc, s6, v8
	s_mov_b32 s6, 0x30000
	s_nop 0
	v_addc_co_u32_e32 v21, vcc, 0, v9, vcc
	global_load_dword v33, v[20:21], off
	v_add_co_u32_e32 v20, vcc, s6, v8
	s_mov_b32 s6, 0x34000
	s_nop 0
	v_addc_co_u32_e32 v21, vcc, 0, v9, vcc
	global_load_dword v34, v[20:21], off
	v_add_co_u32_e32 v20, vcc, s6, v8
	s_mov_b32 s6, 0x38000
	s_nop 0
	v_addc_co_u32_e32 v21, vcc, 0, v9, vcc
	global_load_dword v35, v[20:21], off
	v_add_co_u32_e32 v20, vcc, s6, v8
	s_mov_b32 s6, 0x3c000
	s_nop 0
	v_addc_co_u32_e32 v21, vcc, 0, v9, vcc
	global_load_dword v36, v[20:21], off
	v_add_co_u32_e32 v20, vcc, s6, v8
	s_mov_b32 s6, 0x44000
	s_nop 0
	v_addc_co_u32_e32 v21, vcc, 0, v9, vcc
	global_load_dword v37, v[20:21], off
	v_add_co_u32_e32 v20, vcc, s15, v8
	v_readlane_b32 s48, v251, 13
	s_nop 0
	v_addc_co_u32_e32 v21, vcc, 0, v9, vcc
	global_load_dword v38, v[20:21], off
	v_add_co_u32_e32 v20, vcc, s6, v8
	s_mov_b32 s6, 0x48000
	s_nop 0
	v_addc_co_u32_e32 v21, vcc, 0, v9, vcc
	global_load_dword v39, v[20:21], off
	v_add_co_u32_e32 v20, vcc, s6, v8
	s_mov_b32 s6, 0x4c000
	s_nop 0
	v_addc_co_u32_e32 v21, vcc, 0, v9, vcc
	global_load_dword v40, v[20:21], off
	v_add_co_u32_e32 v20, vcc, s6, v8
	s_mov_b32 s6, 0x50000
	s_nop 0
	v_addc_co_u32_e32 v21, vcc, 0, v9, vcc
	global_load_dword v41, v[20:21], off
	v_add_co_u32_e32 v20, vcc, s6, v8
	s_mov_b32 s6, 0x54000
	s_nop 0
	v_addc_co_u32_e32 v21, vcc, 0, v9, vcc
	global_load_dword v42, v[20:21], off
	v_add_co_u32_e32 v20, vcc, s6, v8
	s_mov_b32 s6, 0x58000
	s_nop 0
	v_addc_co_u32_e32 v21, vcc, 0, v9, vcc
	global_load_dword v43, v[20:21], off
	v_add_co_u32_e32 v20, vcc, s6, v8
	s_mov_b32 s6, 0x5c000
	s_nop 0
	v_addc_co_u32_e32 v21, vcc, 0, v9, vcc
	global_load_dword v44, v[20:21], off
	v_add_co_u32_e32 v20, vcc, s6, v8
	s_mov_b32 s6, 0x60000
	s_nop 0
	v_addc_co_u32_e32 v21, vcc, 0, v9, vcc
	global_load_dword v45, v[20:21], off
	v_add_co_u32_e32 v20, vcc, s6, v8
	s_mov_b32 s6, 0x64000
	s_nop 0
	v_addc_co_u32_e32 v21, vcc, 0, v9, vcc
	global_load_dword v46, v[20:21], off
	v_add_co_u32_e32 v20, vcc, s6, v8
	s_mov_b32 s6, 0x68000
	s_nop 0
	v_addc_co_u32_e32 v21, vcc, 0, v9, vcc
	global_load_dword v47, v[20:21], off
	v_add_co_u32_e32 v20, vcc, s6, v8
	s_mov_b32 s6, 0x6c000
	s_nop 0
	v_addc_co_u32_e32 v21, vcc, 0, v9, vcc
	global_load_dword v48, v[20:21], off
	v_add_co_u32_e32 v20, vcc, s6, v8
	s_mov_b32 s6, 0x70000
	s_nop 0
	v_addc_co_u32_e32 v21, vcc, 0, v9, vcc
	global_load_dword v49, v[20:21], off
	v_add_co_u32_e32 v20, vcc, s6, v8
	s_mov_b32 s6, 0x74000
	s_nop 0
	v_addc_co_u32_e32 v21, vcc, 0, v9, vcc
	global_load_dword v50, v[20:21], off
	v_add_co_u32_e32 v20, vcc, s6, v8
	s_mov_b32 s6, 0x78000
	s_nop 0
	v_addc_co_u32_e32 v21, vcc, 0, v9, vcc
	global_load_dword v51, v[20:21], off
	v_add_co_u32_e32 v20, vcc, s6, v8
	s_mov_b32 s6, 0x7c000
	s_nop 0
	v_addc_co_u32_e32 v21, vcc, 0, v9, vcc
	v_add_co_u32_e32 v8, vcc, s6, v8
	global_load_dword v20, v[20:21], off
	s_nop 0
	v_addc_co_u32_e32 v9, vcc, 0, v9, vcc
	global_load_dword v8, v[8:9], off
	s_waitcnt vmcnt(30)
	ds_write2_b32 v11, v0, v23 offset1:66
	s_waitcnt vmcnt(28)
	ds_write2_b32 v11, v24, v25 offset0:132 offset1:198
	v_add_u32_e32 v0, 0x400, v11
	s_waitcnt vmcnt(26)
; #define LAS __attribute__((address_space(3)))
; #define LDS_WAIT() asm volatile("s_waitcnt lgkmcnt(0)" ::: "memory")
; __device__ __forceinline__ unsigned pk2(float lo, float hi) { return f2bf(lo) | (f2bf(hi) << 16); }
;     ...
;     for (int i = 0; i < 32; ++i) scr[(2 * i + (lane >> 5)) * 33 + (lane & 31)] = tv_[i];
;     LDS_WAIT(); asm volatile("" ::: "memory");
;     const int c = lane & 7;
; #pragma unroll
;     for (int j = 0; j < 4; ++j) { const int n = (lane >> 3) + 8 * j; const LAS float* s = scr + (8 * c) * 33 + n;
;         v4u o; o.x = pk2(s[0 * 33], s[1 * 33]); o.y = pk2(s[2 * 33], s[3 * 33]); o.z = pk2(s[4 * 33], s[5 * 33]); o.w = pk2(s[6 * 33], s[7 * 33]);
;         *(v4u*)(WT + (size_t)(n0 + n) * ldw + koff + k0 + 8 * c) = o; }
;     LDS_WAIT(); asm volatile("" ::: "memory");
; __device__ __forceinline__ void convert_range(LAS unsigned char* lds, const Params& p, const int lo, const int hi, const int gw, const int NGW) {
;     ...
;         if (r < 2 * I_PA) { const int l = r / I_PA; r -= l * I_PA; p0_transpose_item(p.in[16] + (size_t)l * PW * DM, PW, DM, (bf16*)(ws + WS_WCAT + l * SZ_WCAT), scr, r, lane, KCAT, 0); continue; } r -= 2 * I_PA;
	ds_write2_b32 v0, v26, v27 offset0:8 offset1:74
	s_waitcnt vmcnt(24)
	ds_write2_b32 v0, v28, v29 offset0:140 offset1:206
	v_add_u32_e32 v0, 0x800, v11
	s_waitcnt vmcnt(22)
	ds_write2_b32 v0, v30, v31 offset0:16 offset1:82
	s_waitcnt vmcnt(20)
	ds_write2_b32 v0, v32, v33 offset0:148 offset1:214
	v_add_u32_e32 v0, 0xc00, v11
	s_waitcnt vmcnt(18)
	ds_write2_b32 v0, v34, v35 offset0:24 offset1:90
	s_waitcnt vmcnt(16)
	ds_write2_b32 v0, v36, v37 offset0:156 offset1:222
	v_add_u32_e32 v0, 0x1000, v11
	s_waitcnt vmcnt(14)
	ds_write2_b32 v0, v38, v39 offset0:32 offset1:98
	s_waitcnt vmcnt(12)
	ds_write2_b32 v0, v40, v41 offset0:164 offset1:230
	v_add_u32_e32 v0, 0x1400, v11
	s_waitcnt vmcnt(10)
	ds_write2_b32 v0, v42, v43 offset0:40 offset1:106
	s_waitcnt vmcnt(8)
	ds_write2_b32 v0, v44, v45 offset0:172 offset1:238
	v_add_u32_e32 v0, 0x1800, v11
	s_waitcnt vmcnt(6)
	ds_write2_b32 v0, v46, v47 offset0:48 offset1:114
	s_waitcnt vmcnt(4)
	ds_write2_b32 v0, v48, v49 offset0:180 offset1:246
	v_add_u32_e32 v0, 0x1c00, v11
	s_waitcnt vmcnt(2)
	ds_write2_b32 v0, v50, v51 offset0:56 offset1:122
	s_waitcnt vmcnt(0)
	ds_write2_b32 v0, v20, v8 offset0:188 offset1:254
	s_waitcnt lgkmcnt(0)
	v_lshlrev_b32_e32 v0, 1, v22
	v_lshl_add_u64 v[6:7], v[6:7], 0, v[0:1]
	v_lshlrev_b32_e32 v0, 1, v4
	v_lshl_add_u64 v[6:7], v[6:7], 0, v[0:1]
	ds_read_b32 v0, v13
	ds_read_b32 v8, v13 offset:132
	s_mov_b64 s[6:7], 0x5000800
	v_lshl_add_u64 v[6:7], v[6:7], 0, s[6:7]
	v_readlane_b32 s49, v251, 14
	s_waitcnt lgkmcnt(0)
	v_cvt_pk_bf16_f32 v20, v0, v8
	ds_read_b32 v0, v13 offset:264
	ds_read_b32 v8, v13 offset:396
	v_readlane_b32 s50, v251, 15
	v_readlane_b32 s51, v251, 16
	s_waitcnt lgkmcnt(1)
	s_waitcnt lgkmcnt(0)
	v_cvt_pk_bf16_f32 v21, v0, v8
	ds_read_b32 v0, v13 offset:528
	ds_read_b32 v8, v13 offset:660
	s_waitcnt lgkmcnt(1)
	s_waitcnt lgkmcnt(0)
	v_cvt_pk_bf16_f32 v22, v0, v8
	ds_read_b32 v0, v13 offset:792
	ds_read_b32 v8, v13 offset:924
	s_waitcnt lgkmcnt(1)
	s_waitcnt lgkmcnt(0)
	v_cvt_pk_bf16_f32 v23, v0, v8
	v_or_b32_e32 v0, v19, v12
	v_mul_u32_u24_e32 v0, 0xc00, v0
	v_lshlrev_b32_e32 v0, 1, v0
	v_lshl_add_u64 v[8:9], v[6:7], 0, v[0:1]
	global_store_dwordx4 v[8:9], v[20:23], off
	ds_read_b32 v0, v13 offset:32
	ds_read_b32 v8, v13 offset:164
	s_waitcnt lgkmcnt(0)
	v_cvt_pk_bf16_f32 v20, v0, v8
	ds_read_b32 v0, v13 offset:296
	ds_read_b32 v8, v13 offset:428
	s_waitcnt lgkmcnt(0)
	v_cvt_pk_bf16_f32 v21, v0, v8
	ds_read_b32 v0, v13 offset:560
	ds_read_b32 v8, v13 offset:692
	s_waitcnt lgkmcnt(0)
	v_cvt_pk_bf16_f32 v22, v0, v8
	ds_read_b32 v0, v13 offset:824
	ds_read_b32 v8, v13 offset:956
	s_waitcnt lgkmcnt(0)
	v_cvt_pk_bf16_f32 v23, v0, v8
	v_or_b32_e32 v0, v19, v14
	v_mul_u32_u24_e32 v0, 0xc00, v0
	v_lshlrev_b32_e32 v0, 1, v0
	v_lshl_add_u64 v[8:9], v[6:7], 0, v[0:1]
	global_store_dwordx4 v[8:9], v[20:23], off
	ds_read_b32 v0, v13 offset:64
	ds_read_b32 v8, v13 offset:196
	s_waitcnt lgkmcnt(0)
	v_cvt_pk_bf16_f32 v20, v0, v8
	ds_read_b32 v0, v13 offset:328
	ds_read_b32 v8, v13 offset:460
	s_waitcnt lgkmcnt(0)
	v_cvt_pk_bf16_f32 v21, v0, v8
	ds_read_b32 v0, v13 offset:592
	ds_read_b32 v8, v13 offset:724
	s_waitcnt lgkmcnt(0)
	v_cvt_pk_bf16_f32 v22, v0, v8
	ds_read_b32 v0, v13 offset:856
	ds_read_b32 v8, v13 offset:988
	s_waitcnt lgkmcnt(0)
	v_cvt_pk_bf16_f32 v23, v0, v8
	v_or_b32_e32 v0, v19, v15
	v_mul_u32_u24_e32 v0, 0xc00, v0
	v_lshlrev_b32_e32 v0, 1, v0
	v_lshl_add_u64 v[8:9], v[6:7], 0, v[0:1]
	global_store_dwordx4 v[8:9], v[20:23], off
	ds_read_b32 v0, v13 offset:96
	ds_read_b32 v8, v13 offset:228
	s_waitcnt lgkmcnt(0)
	v_cvt_pk_bf16_f32 v20, v0, v8
	ds_read_b32 v0, v13 offset:360
	ds_read_b32 v8, v13 offset:492
	s_waitcnt lgkmcnt(0)
	v_cvt_pk_bf16_f32 v21, v0, v8
	ds_read_b32 v0, v13 offset:624
	ds_read_b32 v8, v13 offset:756
	s_waitcnt lgkmcnt(0)
	v_cvt_pk_bf16_f32 v22, v0, v8
	ds_read_b32 v0, v13 offset:888
	ds_read_b32 v8, v13 offset:1020
	s_waitcnt lgkmcnt(0)
	v_cvt_pk_bf16_f32 v23, v0, v8
	v_or_b32_e32 v0, v19, v16
	v_mul_u32_u24_e32 v0, 0xc00, v0
	v_lshlrev_b32_e32 v0, 1, v0
	v_lshl_add_u64 v[6:7], v[6:7], 0, v[0:1]
	global_store_dwordx4 v[6:7], v[20:23], off
	s_waitcnt lgkmcnt(0)
.LBB0_285:
	s_andn2_saveexec_b64 s[42:43], s[42:43]
	s_cbranch_execz .LBB0_287
	v_add_u32_e32 v0, 0x800, v18
	v_lshrrev_b32_e32 v0, 10, v0
	v_readlane_b32 s44, v251, 9
	v_lshlrev_b64 v[6:7], 23, v[0:1]
	v_readlane_b32 s45, v251, 10
	s_mov_b32 s6, 0xc00000
	v_and_b32_e32 v22, 0x3c0, v8
	v_lshl_add_u64 v[20:21], s[44:45], 0, v[6:7]
	v_mov_b64_e32 v[6:7], s[18:19]
	v_mad_u64_u32 v[6:7], s[6:7], v0, s6, v[6:7]
	v_lshlrev_b32_e32 v0, 2, v19
	v_or_b32_e32 v23, v22, v10
	v_lshl_add_u64 v[8:9], v[20:21], 0, v[0:1]
	v_lshlrev_b32_e32 v0, 2, v2
	v_lshl_add_u64 v[8:9], v[8:9], 0, v[0:1]
	v_lshlrev_b32_e32 v0, 13, v23
	v_lshl_add_u64 v[8:9], v[8:9], 0, v[0:1]
	v_add_co_u32_e32 v20, vcc, s22, v8
	s_mov_b32 s6, 0x8000
	s_nop 0
	v_addc_co_u32_e32 v21, vcc, 0, v9, vcc
	global_load_dword v0, v[8:9], off
	global_load_dword v23, v[20:21], off
	v_add_co_u32_e32 v20, vcc, s6, v8
	s_mov_b32 s6, 0xc000
	s_nop 0
	v_addc_co_u32_e32 v21, vcc, 0, v9, vcc
	s_waitcnt lgkmcnt(0)
;     if (ldw == 0) ldw = K;
;     const int nblk = N / 32, kb = item / nblk, nb = item % nblk, k0 = 64 * kb, n0 = 32 * nb;
;     float tv_[32];
; #pragma unroll
;     for (int i = 0; i < 32; ++i) tv_[i] = W[(size_t)(k0 + 2 * i + (lane >> 5)) * N + n0 + (lane & 31)];
; #pragma unroll
;     for (int i = 0; i < 32; ++i) scr[(2 * i + (lane >> 5)) * 33 + (lane & 31)] = tv_[i];
	global_load_dword v24, v[20:21], off
	v_add_co_u32_e32 v20, vcc, s6, v8
	s_mov_b32 s6, 0x14000
	s_nop 0
	v_addc_co_u32_e32 v21, vcc, 0, v9, vcc
	global_load_dword v25, v[20:21], off
	v_add_co_u32_e32 v20, vcc, s20, v8
	v_readlane_b32 s46, v251, 11
	s_nop 0
	v_addc_co_u32_e32 v21, vcc, 0, v9, vcc
	global_load_dword v26, v[20:21], off
	v_add_co_u32_e32 v20, vcc, s6, v8
	s_mov_b32 s6, 0x18000
	s_nop 0
	v_addc_co_u32_e32 v21, vcc, 0, v9, vcc
	global_load_dword v27, v[20:21], off
	v_add_co_u32_e32 v20, vcc, s6, v8
	s_mov_b32 s6, 0x1c000
	s_nop 0
	v_addc_co_u32_e32 v21, vcc, 0, v9, vcc
	global_load_dword v28, v[20:21], off
	v_add_co_u32_e32 v20, vcc, s6, v8
	s_mov_b32 s6, 0x20000
	s_nop 0
	v_addc_co_u32_e32 v21, vcc, 0, v9, vcc
	global_load_dword v29, v[20:21], off
	v_add_co_u32_e32 v20, vcc, s6, v8
	s_mov_b32 s6, 0x24000
	s_nop 0
	v_addc_co_u32_e32 v21, vcc, 0, v9, vcc
	global_load_dword v30, v[20:21], off
	v_add_co_u32_e32 v20, vcc, s6, v8
	s_mov_b32 s6, 0x28000
	s_nop 0
	v_addc_co_u32_e32 v21, vcc, 0, v9, vcc
	global_load_dword v31, v[20:21], off
	v_add_co_u32_e32 v20, vcc, s6, v8
	s_mov_b32 s6, 0x2c000
	s_nop 0
	v_addc_co_u32_e32 v21, vcc, 0, v9, vcc
	global_load_dword v32, v[20:21], off
	v_add_co_u32_e32 v20, vcc, s6, v8
	s_mov_b32 s6, 0x30000
	s_nop 0
	v_addc_co_u32_e32 v21, vcc, 0, v9, vcc
	global_load_dword v33, v[20:21], off
	v_add_co_u32_e32 v20, vcc, s6, v8
	s_mov_b32 s6, 0x34000
	s_nop 0
	v_addc_co_u32_e32 v21, vcc, 0, v9, vcc
	global_load_dword v34, v[20:21], off
	v_add_co_u32_e32 v20, vcc, s6, v8
	s_mov_b32 s6, 0x38000
	s_nop 0
	v_addc_co_u32_e32 v21, vcc, 0, v9, vcc
	global_load_dword v35, v[20:21], off
	v_add_co_u32_e32 v20, vcc, s6, v8
	s_mov_b32 s6, 0x3c000
	s_nop 0
	v_addc_co_u32_e32 v21, vcc, 0, v9, vcc
	global_load_dword v36, v[20:21], off
	v_add_co_u32_e32 v20, vcc, s6, v8
	s_mov_b32 s6, 0x44000
	s_nop 0
	v_addc_co_u32_e32 v21, vcc, 0, v9, vcc
	global_load_dword v37, v[20:21], off
	v_add_co_u32_e32 v20, vcc, s15, v8
	v_readlane_b32 s47, v251, 12
	s_nop 0
	v_addc_co_u32_e32 v21, vcc, 0, v9, vcc
	global_load_dword v38, v[20:21], off
	v_add_co_u32_e32 v20, vcc, s6, v8
	s_mov_b32 s6, 0x48000
	s_nop 0
	v_addc_co_u32_e32 v21, vcc, 0, v9, vcc
	global_load_dword v39, v[20:21], off
	v_add_co_u32_e32 v20, vcc, s6, v8
	s_mov_b32 s6, 0x4c000
	s_nop 0
	v_addc_co_u32_e32 v21, vcc, 0, v9, vcc
	global_load_dword v40, v[20:21], off
	v_add_co_u32_e32 v20, vcc, s6, v8
	s_mov_b32 s6, 0x50000
	s_nop 0
	v_addc_co_u32_e32 v21, vcc, 0, v9, vcc
	global_load_dword v41, v[20:21], off
	v_add_co_u32_e32 v20, vcc, s6, v8
	s_mov_b32 s6, 0x54000
	s_nop 0
	v_addc_co_u32_e32 v21, vcc, 0, v9, vcc
	global_load_dword v42, v[20:21], off
	v_add_co_u32_e32 v20, vcc, s6, v8
	s_mov_b32 s6, 0x58000
	s_nop 0
	v_addc_co_u32_e32 v21, vcc, 0, v9, vcc
	global_load_dword v43, v[20:21], off
	v_add_co_u32_e32 v20, vcc, s6, v8
	s_mov_b32 s6, 0x5c000
	s_nop 0
	v_addc_co_u32_e32 v21, vcc, 0, v9, vcc
	global_load_dword v44, v[20:21], off
	v_add_co_u32_e32 v20, vcc, s6, v8
	s_mov_b32 s6, 0x60000
	s_nop 0
	v_addc_co_u32_e32 v21, vcc, 0, v9, vcc
	global_load_dword v45, v[20:21], off
	v_add_co_u32_e32 v20, vcc, s6, v8
	s_mov_b32 s6, 0x64000
	s_nop 0
	v_addc_co_u32_e32 v21, vcc, 0, v9, vcc
	global_load_dword v46, v[20:21], off
	v_add_co_u32_e32 v20, vcc, s6, v8
	s_mov_b32 s6, 0x68000
	s_nop 0
	v_addc_co_u32_e32 v21, vcc, 0, v9, vcc
	global_load_dword v47, v[20:21], off
	v_add_co_u32_e32 v20, vcc, s6, v8
	s_mov_b32 s6, 0x6c000
	s_nop 0
	v_addc_co_u32_e32 v21, vcc, 0, v9, vcc
	global_load_dword v48, v[20:21], off
	v_add_co_u32_e32 v20, vcc, s6, v8
	s_mov_b32 s6, 0x70000
	s_nop 0
	v_addc_co_u32_e32 v21, vcc, 0, v9, vcc
	global_load_dword v49, v[20:21], off
	v_add_co_u32_e32 v20, vcc, s6, v8
	s_mov_b32 s6, 0x74000
	s_nop 0
	v_addc_co_u32_e32 v21, vcc, 0, v9, vcc
	global_load_dword v50, v[20:21], off
	v_add_co_u32_e32 v20, vcc, s6, v8
	s_mov_b32 s6, 0x78000
	s_nop 0
	v_addc_co_u32_e32 v21, vcc, 0, v9, vcc
	global_load_dword v51, v[20:21], off
	v_add_co_u32_e32 v20, vcc, s6, v8
	s_mov_b32 s6, 0x7c000
	s_nop 0
	v_addc_co_u32_e32 v21, vcc, 0, v9, vcc
	v_add_co_u32_e32 v8, vcc, s6, v8
	global_load_dword v20, v[20:21], off
	s_nop 0
	v_addc_co_u32_e32 v9, vcc, 0, v9, vcc
	global_load_dword v8, v[8:9], off
	s_waitcnt vmcnt(30)
; #define LAS __attribute__((address_space(3)))
; #define LDS_WAIT() asm volatile("s_waitcnt lgkmcnt(0)" ::: "memory")
; __device__ __forceinline__ unsigned pk2(float lo, float hi) { return f2bf(lo) | (f2bf(hi) << 16); }
;     ...
;     for (int i = 0; i < 32; ++i) scr[(2 * i + (lane >> 5)) * 33 + (lane & 31)] = tv_[i];
;     LDS_WAIT(); asm volatile("" ::: "memory");
;     const int c = lane & 7;
; #pragma unroll
;     for (int j = 0; j < 4; ++j) { const int n = (lane >> 3) + 8 * j; const LAS float* s = scr + (8 * c) * 33 + n;
;         v4u o; o.x = pk2(s[0 * 33], s[1 * 33]); o.y = pk2(s[2 * 33], s[3 * 33]); o.z = pk2(s[4 * 33], s[5 * 33]); o.w = pk2(s[6 * 33], s[7 * 33]);
;         *(v4u*)(WT + (size_t)(n0 + n) * ldw + koff + k0 + 8 * c) = o; }
;     LDS_WAIT(); asm volatile("" ::: "memory");
	ds_write2_b32 v11, v0, v23 offset1:66
	s_waitcnt vmcnt(28)
	ds_write2_b32 v11, v24, v25 offset0:132 offset1:198
	v_add_u32_e32 v0, 0x400, v11
	s_waitcnt vmcnt(26)
	ds_write2_b32 v0, v26, v27 offset0:8 offset1:74
	s_waitcnt vmcnt(24)
	ds_write2_b32 v0, v28, v29 offset0:140 offset1:206
	v_add_u32_e32 v0, 0x800, v11
	s_waitcnt vmcnt(22)
	ds_write2_b32 v0, v30, v31 offset0:16 offset1:82
	s_waitcnt vmcnt(20)
	ds_write2_b32 v0, v32, v33 offset0:148 offset1:214
	v_add_u32_e32 v0, 0xc00, v11
	s_waitcnt vmcnt(18)
	ds_write2_b32 v0, v34, v35 offset0:24 offset1:90
	s_waitcnt vmcnt(16)
	ds_write2_b32 v0, v36, v37 offset0:156 offset1:222
	v_add_u32_e32 v0, 0x1000, v11
	s_waitcnt vmcnt(14)
	ds_write2_b32 v0, v38, v39 offset0:32 offset1:98
	s_waitcnt vmcnt(12)
	ds_write2_b32 v0, v40, v41 offset0:164 offset1:230
	v_add_u32_e32 v0, 0x1400, v11
	s_waitcnt vmcnt(10)
	ds_write2_b32 v0, v42, v43 offset0:40 offset1:106
	s_waitcnt vmcnt(8)
	ds_write2_b32 v0, v44, v45 offset0:172 offset1:238
	v_add_u32_e32 v0, 0x1800, v11
	s_waitcnt vmcnt(6)
	ds_write2_b32 v0, v46, v47 offset0:48 offset1:114
	s_waitcnt vmcnt(4)
	ds_write2_b32 v0, v48, v49 offset0:180 offset1:246
	v_add_u32_e32 v0, 0x1c00, v11
	s_waitcnt vmcnt(2)
	ds_write2_b32 v0, v50, v51 offset0:56 offset1:122
	s_waitcnt vmcnt(0)
	ds_write2_b32 v0, v20, v8 offset0:188 offset1:254
	s_waitcnt lgkmcnt(0)
	v_lshlrev_b32_e32 v0, 1, v22
	v_lshl_add_u64 v[6:7], v[6:7], 0, v[0:1]
	v_lshlrev_b32_e32 v0, 1, v4
	v_lshl_add_u64 v[6:7], v[6:7], 0, v[0:1]
	ds_read_b32 v0, v13
	ds_read_b32 v8, v13 offset:132
	v_readlane_b32 s48, v251, 13
	v_readlane_b32 s49, v251, 14
	v_readlane_b32 s50, v251, 15
	s_waitcnt lgkmcnt(0)
	v_cvt_pk_bf16_f32 v20, v0, v8
	ds_read_b32 v0, v13 offset:264
	ds_read_b32 v8, v13 offset:396
	v_readlane_b32 s51, v251, 16
	s_waitcnt lgkmcnt(1)
	s_waitcnt lgkmcnt(0)
	v_cvt_pk_bf16_f32 v21, v0, v8
	ds_read_b32 v0, v13 offset:528
	ds_read_b32 v8, v13 offset:660
	s_waitcnt lgkmcnt(1)
	s_waitcnt lgkmcnt(0)
	v_cvt_pk_bf16_f32 v22, v0, v8
	ds_read_b32 v0, v13 offset:792
	ds_read_b32 v8, v13 offset:924
	s_waitcnt lgkmcnt(1)
	s_waitcnt lgkmcnt(0)
	v_cvt_pk_bf16_f32 v23, v0, v8
	v_or_b32_e32 v0, v19, v12
	v_mul_u32_u24_e32 v0, 0xc00, v0
	v_lshlrev_b32_e32 v0, 1, v0
	v_lshl_add_u64 v[8:9], v[6:7], 0, v[0:1]
	global_store_dwordx4 v[8:9], v[20:23], off
	ds_read_b32 v0, v13 offset:32
	ds_read_b32 v8, v13 offset:164
	s_waitcnt lgkmcnt(0)
	v_cvt_pk_bf16_f32 v20, v0, v8
	ds_read_b32 v0, v13 offset:296
	ds_read_b32 v8, v13 offset:428
	s_waitcnt lgkmcnt(0)
	v_cvt_pk_bf16_f32 v21, v0, v8
	ds_read_b32 v0, v13 offset:560
	ds_read_b32 v8, v13 offset:692
	s_waitcnt lgkmcnt(0)
	v_cvt_pk_bf16_f32 v22, v0, v8
	ds_read_b32 v0, v13 offset:824
	ds_read_b32 v8, v13 offset:956
	s_waitcnt lgkmcnt(0)
	v_cvt_pk_bf16_f32 v23, v0, v8
	v_or_b32_e32 v0, v19, v14
	v_mul_u32_u24_e32 v0, 0xc00, v0
	v_lshlrev_b32_e32 v0, 1, v0
	v_lshl_add_u64 v[8:9], v[6:7], 0, v[0:1]
	global_store_dwordx4 v[8:9], v[20:23], off
	ds_read_b32 v0, v13 offset:64
	ds_read_b32 v8, v13 offset:196
	s_waitcnt lgkmcnt(0)
	v_cvt_pk_bf16_f32 v20, v0, v8
	ds_read_b32 v0, v13 offset:328
	ds_read_b32 v8, v13 offset:460
	s_waitcnt lgkmcnt(0)
	v_cvt_pk_bf16_f32 v21, v0, v8
	ds_read_b32 v0, v13 offset:592
	ds_read_b32 v8, v13 offset:724
	s_waitcnt lgkmcnt(0)
	v_cvt_pk_bf16_f32 v22, v0, v8
	ds_read_b32 v0, v13 offset:856
	ds_read_b32 v8, v13 offset:988
	s_waitcnt lgkmcnt(0)
	v_cvt_pk_bf16_f32 v23, v0, v8
	v_or_b32_e32 v0, v19, v15
	v_mul_u32_u24_e32 v0, 0xc00, v0
	v_lshlrev_b32_e32 v0, 1, v0
	v_lshl_add_u64 v[8:9], v[6:7], 0, v[0:1]
	global_store_dwordx4 v[8:9], v[20:23], off
	ds_read_b32 v0, v13 offset:96
	ds_read_b32 v8, v13 offset:228
	s_waitcnt lgkmcnt(0)
	v_cvt_pk_bf16_f32 v20, v0, v8
	ds_read_b32 v0, v13 offset:360
	ds_read_b32 v8, v13 offset:492
	s_waitcnt lgkmcnt(0)
	v_cvt_pk_bf16_f32 v21, v0, v8
	ds_read_b32 v0, v13 offset:624
	ds_read_b32 v8, v13 offset:756
	s_waitcnt lgkmcnt(0)
	v_cvt_pk_bf16_f32 v22, v0, v8
	ds_read_b32 v0, v13 offset:888
	ds_read_b32 v8, v13 offset:1020
	s_waitcnt lgkmcnt(0)
	v_cvt_pk_bf16_f32 v23, v0, v8
	v_or_b32_e32 v0, v19, v16
	v_mul_u32_u24_e32 v0, 0xc00, v0
	v_lshlrev_b32_e32 v0, 1, v0
	v_lshl_add_u64 v[6:7], v[6:7], 0, v[0:1]
	global_store_dwordx4 v[6:7], v[20:23], off
	s_waitcnt lgkmcnt(0)

;     ...
;     const int nblk = N / 32, kb = item / nblk, nb = item % nblk, k0 = 64 * kb, n0 = 32 * nb;
;     float tv_[32];
; #pragma unroll
;     for (int i = 0; i < 32; ++i) tv_[i] = W[(size_t)(k0 + 2 * i + (lane >> 5)) * N + n0 + (lane & 31)];
; #pragma unroll
;     for (int i = 0; i < 32; ++i) scr[(2 * i + (lane >> 5)) * 33 + (lane & 31)] = tv_[i];
; __device__ __forceinline__ void convert_range(LAS unsigned char* lds, const Params& p, const int lo, const int hi, const int gw, const int NGW) {
;     ...
;     for (int it = lo + gw; it < hi; it += NGW) {
;         int r = it;
;         if (r < 2 * I_IN) { const int l = r / I_IN; r -= l * I_IN; p0_transpose_item(p.in[5] + (size_t)l * DM * NC, DM, NC, (bf16*)(ws + WS_WIN + l * SZ_WIN), scr, r, lane); continue; } r -= 2 * I_IN;
.LBB0_288:
	s_andn2_saveexec_b64 s[40:41], s[40:41]
	s_cbranch_execz .LBB0_281
	v_mul_hi_i32 v0, v8, s14
	v_lshrrev_b32_e32 v6, 31, v0
	v_ashrrev_i32_e32 v0, 12, v0
	v_add_u32_e32 v9, v0, v6
	v_readlane_b32 s60, v251, 21
	v_mul_i32_i24_e32 v0, 0xffffd800, v9
	s_movk_i32 s6, 0x5800
	v_readlane_b32 s70, v251, 31
	v_readlane_b32 s71, v251, 32
	v_add3_u32 v0, v0, v18, s6
	s_mov_b32 s6, 0x5000000
	v_mov_b64_e32 v[6:7], s[70:71]
	v_mad_i64_i32 v[20:21], s[6:7], v9, s6, v[6:7]
	v_mul_hi_i32 v6, v0, s14
	v_lshrrev_b32_e32 v7, 31, v6
	v_ashrrev_i32_e32 v6, 7, v6
	v_add_u32_e32 v6, v6, v7
	v_mul_i32_i24_e32 v7, 0x140, v6
	v_sub_u32_e32 v0, v0, v7
	v_lshlrev_b32_e32 v8, 6, v6
	v_lshlrev_b32_e32 v6, 5, v0
	v_ashrrev_i32_e32 v7, 31, v6
	v_lshl_add_u64 v[20:21], v[6:7], 2, v[20:21]
	v_lshlrev_b32_e32 v0, 2, v2
	v_or_b32_e32 v19, v8, v10
	v_lshl_add_u64 v[20:21], v[20:21], 0, v[0:1]
	v_mad_i64_i32 v[22:23], s[6:7], v19, s23, v[20:21]
	v_or_b32_e32 v7, 2, v19
	global_load_dword v0, v[22:23], off
	v_mad_i64_i32 v[22:23], s[6:7], v7, s23, v[20:21]
	global_load_dword v7, v[22:23], off
	v_or_b32_e32 v22, 4, v19
	v_mad_i64_i32 v[22:23], s[6:7], v22, s23, v[20:21]
	s_waitcnt lgkmcnt(0)
	global_load_dword v24, v[22:23], off
	v_or_b32_e32 v22, 6, v19
	v_mad_i64_i32 v[22:23], s[6:7], v22, s23, v[20:21]
	global_load_dword v25, v[22:23], off
	v_or_b32_e32 v22, 8, v19
	v_mad_i64_i32 v[22:23], s[6:7], v22, s23, v[20:21]
	global_load_dword v26, v[22:23], off
	v_or_b32_e32 v22, 10, v19
	v_mad_i64_i32 v[22:23], s[6:7], v22, s23, v[20:21]
	global_load_dword v27, v[22:23], off
	v_or_b32_e32 v22, 12, v19
	v_mad_i64_i32 v[22:23], s[6:7], v22, s23, v[20:21]
	global_load_dword v28, v[22:23], off
	v_or_b32_e32 v22, 14, v19
	v_mad_i64_i32 v[22:23], s[6:7], v22, s23, v[20:21]
	global_load_dword v29, v[22:23], off
	v_or_b32_e32 v22, 16, v19
	v_mad_i64_i32 v[22:23], s[6:7], v22, s23, v[20:21]
	global_load_dword v30, v[22:23], off
	v_or_b32_e32 v22, 18, v19
	v_mad_i64_i32 v[22:23], s[6:7], v22, s23, v[20:21]
	global_load_dword v31, v[22:23], off
	v_or_b32_e32 v22, 20, v19
	v_mad_i64_i32 v[22:23], s[6:7], v22, s23, v[20:21]
	global_load_dword v32, v[22:23], off
	v_or_b32_e32 v22, 22, v19
	v_mad_i64_i32 v[22:23], s[6:7], v22, s23, v[20:21]
	global_load_dword v33, v[22:23], off
	v_or_b32_e32 v22, 24, v19
	v_mad_i64_i32 v[22:23], s[6:7], v22, s23, v[20:21]
	global_load_dword v34, v[22:23], off
	v_or_b32_e32 v22, 26, v19
	v_mad_i64_i32 v[22:23], s[6:7], v22, s23, v[20:21]
	global_load_dword v35, v[22:23], off
	v_or_b32_e32 v22, 28, v19
	v_mad_i64_i32 v[22:23], s[6:7], v22, s23, v[20:21]
	global_load_dword v36, v[22:23], off
	v_or_b32_e32 v22, 30, v19
	v_mad_i64_i32 v[22:23], s[6:7], v22, s23, v[20:21]
	global_load_dword v37, v[22:23], off
	v_or_b32_e32 v22, 32, v19
	v_mad_i64_i32 v[22:23], s[6:7], v22, s23, v[20:21]
	global_load_dword v38, v[22:23], off
	v_or_b32_e32 v22, 34, v19
	v_mad_i64_i32 v[22:23], s[6:7], v22, s23, v[20:21]
	global_load_dword v39, v[22:23], off
	v_or_b32_e32 v22, 36, v19
	v_mad_i64_i32 v[22:23], s[6:7], v22, s23, v[20:21]
	global_load_dword v40, v[22:23], off
	v_or_b32_e32 v22, 38, v19
	v_mad_i64_i32 v[22:23], s[6:7], v22, s23, v[20:21]
	global_load_dword v41, v[22:23], off
	v_or_b32_e32 v22, 40, v19
	v_mad_i64_i32 v[22:23], s[6:7], v22, s23, v[20:21]
	global_load_dword v42, v[22:23], off
	v_or_b32_e32 v22, 42, v19
	v_mad_i64_i32 v[22:23], s[6:7], v22, s23, v[20:21]
	global_load_dword v43, v[22:23], off
	v_or_b32_e32 v22, 44, v19
	v_mad_i64_i32 v[22:23], s[6:7], v22, s23, v[20:21]
	global_load_dword v44, v[22:23], off
	v_or_b32_e32 v22, 46, v19
	v_mad_i64_i32 v[22:23], s[6:7], v22, s23, v[20:21]
	global_load_dword v45, v[22:23], off
	v_or_b32_e32 v22, 48, v19
	v_mad_i64_i32 v[22:23], s[6:7], v22, s23, v[20:21]
	global_load_dword v46, v[22:23], off
	v_or_b32_e32 v22, 50, v19
	v_mad_i64_i32 v[22:23], s[6:7], v22, s23, v[20:21]
	global_load_dword v47, v[22:23], off
	v_or_b32_e32 v22, 52, v19
	v_mad_i64_i32 v[22:23], s[6:7], v22, s23, v[20:21]
	global_load_dword v48, v[22:23], off
	v_or_b32_e32 v22, 54, v19
	v_mad_i64_i32 v[22:23], s[6:7], v22, s23, v[20:21]
	global_load_dword v49, v[22:23], off
	v_or_b32_e32 v22, 56, v19
	v_mad_i64_i32 v[22:23], s[6:7], v22, s23, v[20:21]
	global_load_dword v50, v[22:23], off
	v_or_b32_e32 v22, 58, v19
	v_mad_i64_i32 v[22:23], s[6:7], v22, s23, v[20:21]
	global_load_dword v51, v[22:23], off
	v_or_b32_e32 v22, 60, v19
	v_or_b32_e32 v19, 62, v19
	v_mad_i64_i32 v[22:23], s[6:7], v22, s23, v[20:21]
	v_mad_i64_i32 v[20:21], s[6:7], v19, s23, v[20:21]
	global_load_dword v22, v[22:23], off
	s_mov_b32 s6, 0x2800000
	global_load_dword v19, v[20:21], off
	s_waitcnt vmcnt(30)
	ds_write2_b32 v11, v0, v7 offset1:66
	s_waitcnt vmcnt(28)
	ds_write2_b32 v11, v24, v25 offset0:132 offset1:198
	v_add_u32_e32 v0, 0x400, v11
	s_waitcnt vmcnt(26)
	ds_write2_b32 v0, v26, v27 offset0:8 offset1:74
	s_waitcnt vmcnt(24)
	ds_write2_b32 v0, v28, v29 offset0:140 offset1:206
	v_add_u32_e32 v0, 0x800, v11
	s_waitcnt vmcnt(22)
	ds_write2_b32 v0, v30, v31 offset0:16 offset1:82
	s_waitcnt vmcnt(20)
	ds_write2_b32 v0, v32, v33 offset0:148 offset1:214
	v_add_u32_e32 v0, 0xc00, v11
	s_waitcnt vmcnt(18)
	ds_write2_b32 v0, v34, v35 offset0:24 offset1:90
	s_waitcnt vmcnt(16)
	ds_write2_b32 v0, v36, v37 offset0:156 offset1:222
	v_add_u32_e32 v0, 0x1000, v11
	s_waitcnt vmcnt(14)
	ds_write2_b32 v0, v38, v39 offset0:32 offset1:98
	s_waitcnt vmcnt(12)
	ds_write2_b32 v0, v40, v41 offset0:164 offset1:230
	v_add_u32_e32 v0, 0x1400, v11
	s_waitcnt vmcnt(10)
; #define LAS __attribute__((address_space(3)))
; #define LDS_WAIT() asm volatile("s_waitcnt lgkmcnt(0)" ::: "memory")
; __device__ __forceinline__ unsigned pk2(float lo, float hi) { return f2bf(lo) | (f2bf(hi) << 16); }
;     ...
;     for (int i = 0; i < 32; ++i) scr[(2 * i + (lane >> 5)) * 33 + (lane & 31)] = tv_[i];
;     LDS_WAIT(); asm volatile("" ::: "memory");
;     const int c = lane & 7;
; #pragma unroll
;     for (int j = 0; j < 4; ++j) { const int n = (lane >> 3) + 8 * j; const LAS float* s = scr + (8 * c) * 33 + n;
;         v4u o; o.x = pk2(s[0 * 33], s[1 * 33]); o.y = pk2(s[2 * 33], s[3 * 33]); o.z = pk2(s[4 * 33], s[5 * 33]); o.w = pk2(s[6 * 33], s[7 * 33]);
;         *(v4u*)(WT + (size_t)(n0 + n) * ldw + koff + k0 + 8 * c) = o; }
;     LDS_WAIT(); asm volatile("" ::: "memory");
	ds_write2_b32 v0, v42, v43 offset0:40 offset1:106
	s_waitcnt vmcnt(8)
	ds_write2_b32 v0, v44, v45 offset0:172 offset1:238
	v_add_u32_e32 v0, 0x1800, v11
	s_waitcnt vmcnt(6)
	ds_write2_b32 v0, v46, v47 offset0:48 offset1:114
	s_waitcnt vmcnt(4)
	ds_write2_b32 v0, v48, v49 offset0:180 offset1:246
	v_add_u32_e32 v0, 0x1c00, v11
	s_waitcnt vmcnt(2)
	ds_write2_b32 v0, v50, v51 offset0:56 offset1:122
	s_waitcnt vmcnt(0)
	ds_write2_b32 v0, v22, v19 offset0:188 offset1:254
	s_waitcnt lgkmcnt(0)
	v_mov_b64_e32 v[20:21], s[0:1]
	v_mad_i64_i32 v[20:21], s[6:7], v9, s6, v[20:21]
	v_ashrrev_i32_e32 v9, 31, v8
	ds_read_b32 v7, v13
	ds_read_b32 v23, v13 offset:924
	v_lshl_add_u64 v[8:9], v[8:9], 1, v[20:21]
	v_lshlrev_b32_e32 v0, 1, v4
	v_lshl_add_u64 v[8:9], v[8:9], 0, v[0:1]
	ds_read_b32 v0, v13 offset:132
	s_waitcnt lgkmcnt(0)
	v_bfe_u32 v19, v7, 16, 1
	v_add3_u32 v7, v7, v19, s26
	ds_read_b32 v19, v13 offset:264
	v_lshrrev_b32_e32 v7, 16, v7
	v_bfe_u32 v20, v0, 16, 1
	v_add3_u32 v0, v0, v20, s26
	v_and_or_b32 v20, v0, s24, v7
	ds_read_b32 v0, v13 offset:396
	s_waitcnt lgkmcnt(1)
	v_bfe_u32 v7, v19, 16, 1
	v_add3_u32 v7, v19, v7, s26
	ds_read_b32 v19, v13 offset:528
	v_lshrrev_b32_e32 v7, 16, v7
	s_waitcnt lgkmcnt(1)
	v_bfe_u32 v21, v0, 16, 1
	v_add3_u32 v0, v0, v21, s26
	v_and_or_b32 v21, v0, s24, v7
	ds_read_b32 v0, v13 offset:660
	s_waitcnt lgkmcnt(1)
	v_bfe_u32 v7, v19, 16, 1
	v_add3_u32 v7, v19, v7, s26
	ds_read_b32 v19, v13 offset:792
	v_lshrrev_b32_e32 v7, 16, v7
	s_waitcnt lgkmcnt(1)
	v_bfe_u32 v22, v0, 16, 1
	v_add3_u32 v0, v0, v22, s26
	v_and_or_b32 v22, v0, s24, v7
	s_waitcnt lgkmcnt(0)
	v_or_b32_e32 v24, v6, v12
	v_ashrrev_i32_e32 v25, 31, v24
	v_cvt_pk_bf16_f32 v23, v19, v23
	v_lshlrev_b64 v[24:25], 12, v[24:25]
	v_lshl_add_u64 v[24:25], v[8:9], 0, v[24:25]
	global_store_dwordx4 v[24:25], v[20:23], off
	ds_read_b32 v0, v13 offset:32
	ds_read_b32 v7, v13 offset:164
	ds_read_b32 v23, v13 offset:956
	v_or_b32_e32 v24, v6, v14
	v_ashrrev_i32_e32 v25, 31, v24
	s_waitcnt lgkmcnt(0)
	v_bfe_u32 v19, v0, 16, 1
	v_add3_u32 v0, v0, v19, s26
	ds_read_b32 v19, v13 offset:296
	v_bfe_u32 v20, v7, 16, 1
	v_lshrrev_b32_e32 v0, 16, v0
	v_add3_u32 v7, v7, v20, s26
	v_and_or_b32 v20, v7, s24, v0
	ds_read_b32 v0, v13 offset:428
	s_waitcnt lgkmcnt(0)
	v_bfe_u32 v7, v19, 16, 1
	v_add3_u32 v7, v19, v7, s26
	ds_read_b32 v19, v13 offset:560
	v_lshrrev_b32_e32 v7, 16, v7
	v_bfe_u32 v21, v0, 16, 1
	v_add3_u32 v0, v0, v21, s26
	v_and_or_b32 v21, v0, s24, v7
	ds_read_b32 v0, v13 offset:692
	s_waitcnt lgkmcnt(0)
	v_bfe_u32 v7, v19, 16, 1
	v_add3_u32 v7, v19, v7, s26
	ds_read_b32 v19, v13 offset:824
	v_lshrrev_b32_e32 v7, 16, v7
	v_bfe_u32 v22, v0, 16, 1
	v_add3_u32 v0, v0, v22, s26
	v_and_or_b32 v22, v0, s24, v7
	s_waitcnt lgkmcnt(0)
	v_cvt_pk_bf16_f32 v23, v19, v23
	v_lshlrev_b64 v[24:25], 12, v[24:25]
	v_lshl_add_u64 v[24:25], v[8:9], 0, v[24:25]
	global_store_dwordx4 v[24:25], v[20:23], off
	ds_read_b32 v0, v13 offset:64
	ds_read_b32 v7, v13 offset:196
	ds_read_b32 v23, v13 offset:988
	v_or_b32_e32 v24, v6, v15
	v_ashrrev_i32_e32 v25, 31, v24
	s_waitcnt lgkmcnt(0)
	v_bfe_u32 v19, v0, 16, 1
	v_add3_u32 v0, v0, v19, s26
	ds_read_b32 v19, v13 offset:328
	v_bfe_u32 v20, v7, 16, 1
	v_lshrrev_b32_e32 v0, 16, v0
	v_add3_u32 v7, v7, v20, s26
	v_and_or_b32 v20, v7, s24, v0
	ds_read_b32 v0, v13 offset:460
	s_waitcnt lgkmcnt(0)
	v_bfe_u32 v7, v19, 16, 1
	v_add3_u32 v7, v19, v7, s26
	ds_read_b32 v19, v13 offset:592
	v_lshrrev_b32_e32 v7, 16, v7
	v_bfe_u32 v21, v0, 16, 1
	v_add3_u32 v0, v0, v21, s26
	v_and_or_b32 v21, v0, s24, v7
	ds_read_b32 v0, v13 offset:724
	s_waitcnt lgkmcnt(0)
	v_bfe_u32 v7, v19, 16, 1
	v_add3_u32 v7, v19, v7, s26
	ds_read_b32 v19, v13 offset:856
	v_lshrrev_b32_e32 v7, 16, v7
	v_bfe_u32 v22, v0, 16, 1
	v_add3_u32 v0, v0, v22, s26
	v_and_or_b32 v22, v0, s24, v7
	s_waitcnt lgkmcnt(0)
	v_cvt_pk_bf16_f32 v23, v19, v23
	v_lshlrev_b64 v[24:25], 12, v[24:25]
	v_lshl_add_u64 v[24:25], v[8:9], 0, v[24:25]
	global_store_dwordx4 v[24:25], v[20:23], off
	ds_read_b32 v0, v13 offset:96
	ds_read_b32 v7, v13 offset:228
	ds_read_b32 v23, v13 offset:1020
	v_or_b32_e32 v6, v6, v16
	v_readlane_b32 s72, v251, 33
	s_waitcnt lgkmcnt(0)
	v_bfe_u32 v19, v0, 16, 1
	v_add3_u32 v0, v0, v19, s26
	ds_read_b32 v19, v13 offset:360
	v_bfe_u32 v20, v7, 16, 1
	v_lshrrev_b32_e32 v0, 16, v0
	v_add3_u32 v7, v7, v20, s26
	v_and_or_b32 v20, v7, s24, v0
	ds_read_b32 v0, v13 offset:492
	s_waitcnt lgkmcnt(0)
	v_bfe_u32 v7, v19, 16, 1
	v_add3_u32 v7, v19, v7, s26
	ds_read_b32 v19, v13 offset:624
	v_lshrrev_b32_e32 v7, 16, v7
	v_bfe_u32 v21, v0, 16, 1
	v_add3_u32 v0, v0, v21, s26
	v_and_or_b32 v21, v0, s24, v7
	ds_read_b32 v0, v13 offset:756
	s_waitcnt lgkmcnt(0)
	v_bfe_u32 v7, v19, 16, 1
	v_add3_u32 v7, v19, v7, s26
	ds_read_b32 v19, v13 offset:888
	v_lshrrev_b32_e32 v7, 16, v7
	v_bfe_u32 v22, v0, 16, 1
	v_add3_u32 v0, v0, v22, s26
	v_and_or_b32 v22, v0, s24, v7
	s_waitcnt lgkmcnt(0)
	v_cvt_pk_bf16_f32 v23, v19, v23
	v_ashrrev_i32_e32 v7, 31, v6
	v_lshlrev_b64 v[6:7], 12, v[6:7]
	v_lshl_add_u64 v[6:7], v[8:9], 0, v[6:7]
	global_store_dwordx4 v[6:7], v[20:23], off
	s_waitcnt lgkmcnt(0)
	v_readlane_b32 s73, v251, 34
	v_readlane_b32 s72, v248, 24
	v_readlane_b32 s73, v248, 25
	v_readlane_b32 s61, v251, 22
	v_readlane_b32 s62, v251, 23
	v_readlane_b32 s63, v251, 24
	v_readlane_b32 s64, v251, 25
	v_readlane_b32 s65, v251, 26
	v_readlane_b32 s66, v251, 27
	v_readlane_b32 s67, v251, 28
	v_readlane_b32 s68, v251, 29
	v_readlane_b32 s69, v251, 30
	v_readlane_b32 s74, v251, 35
	v_readlane_b32 s75, v251, 36
	s_branch .LBB0_281

;     ...
;     const int nblk = N / 32, kb = item / nblk, nb = item % nblk, k0 = 64 * kb, n0 = 32 * nb;
;     float tv_[32];
; #pragma unroll
;     for (int i = 0; i < 32; ++i) tv_[i] = W[(size_t)(k0 + 2 * i + (lane >> 5)) * N + n0 + (lane & 31)];
; __device__ __forceinline__ void convert_range(LAS unsigned char* lds, const Params& p, const int lo, const int hi, const int gw, const int NGW) {
;     ...
;     for (int it = lo + gw; it < hi; it += NGW) {
;         int r = it;
;         if (r < 2 * I_IN) { const int l = r / I_IN; r -= l * I_IN; p0_transpose_item(p.in[5] + (size_t)l * DM * NC, DM, NC, (bf16*)(ws + WS_WIN + l * SZ_WIN), scr, r, lane); continue; } r -= 2 * I_IN;
;         if (r < 2 * I_PA) { const int l = r / I_PA; r -= l * I_PA; p0_transpose_item(p.in[16] + (size_t)l * PW * DM, PW, DM, (bf16*)(ws + WS_WCAT + l * SZ_WCAT), scr, r, lane, KCAT, 0); continue; } r -= 2 * I_PA;
;         if (r < 2 * I_PB) { const int l = r / I_PB; r -= l * I_PB; p0_transpose_item(p.in[17] + (size_t)l * LW * DM, LW, DM, (bf16*)(ws + WS_WCAT + l * SZ_WCAT), scr, r, lane, KCAT, PW); continue; } r -= 2 * I_PB;
;         if (r < 2 * I_OUT) { const int l = r / I_OUT; r -= l * I_OUT; p0_transpose_item(p.in[18] + (size_t)l * DM * DM, DM, DM, (bf16*)(ws + WS_WOUT + l * SZ_WOUT), scr, r, lane); continue; } r -= 2 * I_OUT;
.LBB0_293:
	v_add_u32_e32 v8, 0x6800, v5
	s_movk_i32 s3, 0x4fff
	v_cmp_lt_i32_e32 vcc, s3, v8
	s_and_saveexec_b64 s[6:7], vcc
	s_xor_b64 s[42:43], exec, s[6:7]
	s_cbranch_execz .LBB0_303
	s_movk_i32 s3, 0x57ff
	v_cmp_lt_u32_e32 vcc, s3, v8
	s_and_saveexec_b64 s[6:7], vcc
	s_xor_b64 s[44:45], exec, s[6:7]
	s_cbranch_execz .LBB0_300
	v_and_b32_e32 v0, 0x7c0, v8
	s_movk_i32 s3, 0x67ff
	v_or_b32_e32 v6, v0, v14
	v_cmp_lt_u32_e32 vcc, s3, v8
	v_and_b32_e32 v7, 0x7e0, v21
	v_lshlrev_b32_e32 v8, 11, v6
	v_lshlrev_b32_e32 v6, 1, v0
	v_lshlrev_b32_e32 v12, 2, v7
	v_lshlrev_b32_e32 v10, 2, v8
	s_waitcnt lgkmcnt(0)
	v_or_b32_e32 v25, v7, v16
	v_or_b32_e32 v24, v7, v18
	v_or_b32_e32 v23, v7, v19
	v_or_b32_e32 v22, v7, v20
	s_and_saveexec_b64 s[6:7], vcc
	s_xor_b64 s[46:47], exec, s[6:7]
	s_cbranch_execz .LBB0_297
	v_lshrrev_b32_e32 v0, 11, v5
	v_readlane_b32 s68, v251, 9
	v_lshlrev_b64 v[8:9], 24, v[0:1]
	v_readlane_b32 s72, v251, 13
	v_readlane_b32 s73, v251, 14
	v_mov_b32_e32 v13, v1
	v_mov_b32_e32 v11, v1
	v_lshl_add_u64 v[26:27], s[72:73], 0, v[8:9]
	v_lshlrev_b64 v[8:9], 23, v[0:1]
	v_lshl_add_u64 v[12:13], v[26:27], 0, v[12:13]
	v_lshlrev_b32_e32 v0, 2, v2
	v_lshl_add_u64 v[12:13], v[12:13], 0, v[0:1]
	v_lshl_add_u64 v[10:11], v[12:13], 0, v[10:11]
	v_add_co_u32_e32 v12, vcc, s22, v10
	s_mov_b32 s3, 0x8000
	s_nop 0
	v_addc_co_u32_e32 v13, vcc, 0, v11, vcc
	global_load_dword v0, v[10:11], off
	global_load_dword v7, v[12:13], off
	v_add_co_u32_e32 v12, vcc, s3, v10
	s_mov_b32 s3, 0xc000
	s_nop 0
	v_addc_co_u32_e32 v13, vcc, 0, v11, vcc
	global_load_dword v26, v[12:13], off
	v_add_co_u32_e32 v12, vcc, s3, v10
	s_mov_b32 s3, 0x14000
	s_nop 0
	v_addc_co_u32_e32 v13, vcc, 0, v11, vcc
	global_load_dword v27, v[12:13], off
	v_add_co_u32_e32 v12, vcc, s15, v10
	v_lshl_add_u64 v[8:9], s[18:19], 0, v[8:9]
	s_nop 0
	v_addc_co_u32_e32 v13, vcc, 0, v11, vcc
	global_load_dword v28, v[12:13], off
	v_add_co_u32_e32 v12, vcc, s3, v10
	s_mov_b32 s3, 0x18000
	s_nop 0
	v_addc_co_u32_e32 v13, vcc, 0, v11, vcc
	global_load_dword v29, v[12:13], off
	v_add_co_u32_e32 v12, vcc, s3, v10
	s_mov_b32 s3, 0x1c000
	s_nop 0
	v_addc_co_u32_e32 v13, vcc, 0, v11, vcc
	global_load_dword v30, v[12:13], off
	v_add_co_u32_e32 v12, vcc, s3, v10
	s_mov_b32 s3, 0x20000
	s_nop 0
	v_addc_co_u32_e32 v13, vcc, 0, v11, vcc
	global_load_dword v31, v[12:13], off
	v_add_co_u32_e32 v12, vcc, s3, v10
	s_mov_b32 s3, 0x24000
	s_nop 0
	v_addc_co_u32_e32 v13, vcc, 0, v11, vcc
	global_load_dword v32, v[12:13], off
	v_add_co_u32_e32 v12, vcc, s3, v10
	s_mov_b32 s3, 0x28000
	s_nop 0
	v_addc_co_u32_e32 v13, vcc, 0, v11, vcc
	global_load_dword v33, v[12:13], off
	v_add_co_u32_e32 v12, vcc, s3, v10
	s_mov_b32 s3, 0x2c000
	s_nop 0
	v_addc_co_u32_e32 v13, vcc, 0, v11, vcc
	global_load_dword v34, v[12:13], off
	v_add_co_u32_e32 v12, vcc, s3, v10
	s_mov_b32 s3, 0x30000
	s_nop 0
	v_addc_co_u32_e32 v13, vcc, 0, v11, vcc
	global_load_dword v35, v[12:13], off
	v_add_co_u32_e32 v12, vcc, s3, v10
	s_mov_b32 s3, 0x34000
	s_nop 0
	v_addc_co_u32_e32 v13, vcc, 0, v11, vcc
	global_load_dword v36, v[12:13], off
	v_add_co_u32_e32 v12, vcc, s3, v10
	s_mov_b32 s3, 0x38000
	s_nop 0
	v_addc_co_u32_e32 v13, vcc, 0, v11, vcc
	global_load_dword v37, v[12:13], off
	v_add_co_u32_e32 v12, vcc, s3, v10
	s_mov_b32 s3, 0x3c000
	s_nop 0
	v_addc_co_u32_e32 v13, vcc, 0, v11, vcc
	global_load_dword v38, v[12:13], off
	v_add_co_u32_e32 v12, vcc, s3, v10
	s_mov_b32 s3, 0x44000
	s_nop 0
	v_addc_co_u32_e32 v13, vcc, 0, v11, vcc
	global_load_dword v39, v[12:13], off
	v_add_co_u32_e32 v12, vcc, s14, v10
	v_readlane_b32 s72, v248, 24
	s_nop 0
	v_addc_co_u32_e32 v13, vcc, 0, v11, vcc
	global_load_dword v40, v[12:13], off
	v_add_co_u32_e32 v12, vcc, s3, v10
	s_mov_b32 s3, 0x48000
	s_nop 0
	v_addc_co_u32_e32 v13, vcc, 0, v11, vcc
	global_load_dword v41, v[12:13], off
	v_add_co_u32_e32 v12, vcc, s3, v10
	s_mov_b32 s3, 0x4c000
	s_nop 0
	v_addc_co_u32_e32 v13, vcc, 0, v11, vcc
	global_load_dword v42, v[12:13], off
	v_add_co_u32_e32 v12, vcc, s3, v10
	s_mov_b32 s3, 0x50000
	s_nop 0
	v_addc_co_u32_e32 v13, vcc, 0, v11, vcc
	global_load_dword v43, v[12:13], off
	v_add_co_u32_e32 v12, vcc, s3, v10
	s_mov_b32 s3, 0x54000
	s_nop 0
	v_addc_co_u32_e32 v13, vcc, 0, v11, vcc
	global_load_dword v44, v[12:13], off
	v_add_co_u32_e32 v12, vcc, s3, v10
	s_mov_b32 s3, 0x58000
	s_nop 0
	v_addc_co_u32_e32 v13, vcc, 0, v11, vcc
	global_load_dword v45, v[12:13], off
	v_add_co_u32_e32 v12, vcc, s3, v10
	s_mov_b32 s3, 0x5c000
	s_nop 0
	v_addc_co_u32_e32 v13, vcc, 0, v11, vcc
	global_load_dword v46, v[12:13], off
	v_add_co_u32_e32 v12, vcc, s3, v10
	s_mov_b32 s3, 0x60000
	s_nop 0
	v_addc_co_u32_e32 v13, vcc, 0, v11, vcc
	global_load_dword v47, v[12:13], off
	v_add_co_u32_e32 v12, vcc, s3, v10
	s_mov_b32 s3, 0x64000
	s_nop 0
	v_addc_co_u32_e32 v13, vcc, 0, v11, vcc
	global_load_dword v48, v[12:13], off
	v_add_co_u32_e32 v12, vcc, s3, v10
	s_mov_b32 s3, 0x68000
	s_nop 0
	v_addc_co_u32_e32 v13, vcc, 0, v11, vcc
	global_load_dword v49, v[12:13], off
	v_add_co_u32_e32 v12, vcc, s3, v10
	s_mov_b32 s3, 0x6c000
	s_nop 0
	v_addc_co_u32_e32 v13, vcc, 0, v11, vcc
	global_load_dword v50, v[12:13], off
	v_add_co_u32_e32 v12, vcc, s3, v10
	s_mov_b32 s3, 0x70000
	s_nop 0
	v_addc_co_u32_e32 v13, vcc, 0, v11, vcc
	global_load_dword v51, v[12:13], off
	v_add_co_u32_e32 v12, vcc, s3, v10
	s_mov_b32 s3, 0x74000
	s_nop 0
	v_addc_co_u32_e32 v13, vcc, 0, v11, vcc
	global_load_dword v52, v[12:13], off
	v_add_co_u32_e32 v12, vcc, s3, v10
	s_mov_b32 s3, 0x78000
	s_nop 0
	v_addc_co_u32_e32 v13, vcc, 0, v11, vcc
	global_load_dword v53, v[12:13], off
	v_add_co_u32_e32 v12, vcc, s3, v10
	s_mov_b32 s3, 0x7c000
	s_nop 0
	v_addc_co_u32_e32 v13, vcc, 0, v11, vcc
	v_add_co_u32_e32 v10, vcc, s3, v10
	global_load_dword v12, v[12:13], off
	s_nop 0
	v_addc_co_u32_e32 v11, vcc, 0, v11, vcc
	global_load_dword v10, v[10:11], off
	s_waitcnt vmcnt(30)
; #define LAS __attribute__((address_space(3)))
; #define LDS_WAIT() asm volatile("s_waitcnt lgkmcnt(0)" ::: "memory")
; __device__ __forceinline__ unsigned pk2(float lo, float hi) { return f2bf(lo) | (f2bf(hi) << 16); }
;     ...
;     for (int i = 0; i < 32; ++i) scr[(2 * i + (lane >> 5)) * 33 + (lane & 31)] = tv_[i];
;     LDS_WAIT(); asm volatile("" ::: "memory");
;     const int c = lane & 7;
; #pragma unroll
;     for (int j = 0; j < 4; ++j) { const int n = (lane >> 3) + 8 * j; const LAS float* s = scr + (8 * c) * 33 + n;
;         v4u o; o.x = pk2(s[0 * 33], s[1 * 33]); o.y = pk2(s[2 * 33], s[3 * 33]); o.z = pk2(s[4 * 33], s[5 * 33]); o.w = pk2(s[6 * 33], s[7 * 33]);
;         *(v4u*)(WT + (size_t)(n0 + n) * ldw + koff + k0 + 8 * c) = o; }
;     LDS_WAIT(); asm volatile("" ::: "memory");
	ds_write2_b32 v15, v0, v7 offset1:66
	s_waitcnt vmcnt(28)
	ds_write2_b32 v15, v26, v27 offset0:132 offset1:198
	v_add_u32_e32 v0, 0x400, v15
	s_waitcnt vmcnt(26)
	ds_write2_b32 v0, v28, v29 offset0:8 offset1:74
	s_waitcnt vmcnt(24)
	ds_write2_b32 v0, v30, v31 offset0:140 offset1:206
	v_add_u32_e32 v0, 0x800, v15
	s_waitcnt vmcnt(22)
	ds_write2_b32 v0, v32, v33 offset0:16 offset1:82
	s_waitcnt vmcnt(20)
	ds_write2_b32 v0, v34, v35 offset0:148 offset1:214
	v_add_u32_e32 v0, 0xc00, v15
	s_waitcnt vmcnt(18)
	ds_write2_b32 v0, v36, v37 offset0:24 offset1:90
	s_waitcnt vmcnt(16)
	ds_write2_b32 v0, v38, v39 offset0:156 offset1:222
	v_add_u32_e32 v0, 0x1000, v15
	s_waitcnt vmcnt(14)
	ds_write2_b32 v0, v40, v41 offset0:32 offset1:98
	s_waitcnt vmcnt(12)
	ds_write2_b32 v0, v42, v43 offset0:164 offset1:230
	v_add_u32_e32 v0, 0x1400, v15
	s_waitcnt vmcnt(10)
	ds_write2_b32 v0, v44, v45 offset0:40 offset1:106
	s_waitcnt vmcnt(8)
	ds_write2_b32 v0, v46, v47 offset0:172 offset1:238
	v_add_u32_e32 v0, 0x1800, v15
	s_waitcnt vmcnt(6)
	ds_write2_b32 v0, v48, v49 offset0:48 offset1:114
	s_waitcnt vmcnt(4)
	ds_write2_b32 v0, v50, v51 offset0:180 offset1:246
	v_add_u32_e32 v0, 0x1c00, v15
	s_waitcnt vmcnt(2)
	ds_write2_b32 v0, v52, v53 offset0:56 offset1:122
	s_waitcnt vmcnt(0)
	ds_write2_b32 v0, v12, v10 offset0:188 offset1:254
	s_waitcnt lgkmcnt(0)
	v_mov_b32_e32 v7, v1
	v_lshl_add_u64 v[6:7], v[8:9], 0, v[6:7]
	v_lshlrev_b32_e32 v0, 1, v4
	v_lshl_add_u64 v[6:7], v[6:7], 0, v[0:1]
	ds_read_b32 v0, v17
	ds_read_b32 v8, v17 offset:132
	v_readlane_b32 s69, v251, 10
	v_readlane_b32 s70, v251, 11
	v_readlane_b32 s71, v251, 12
	s_waitcnt lgkmcnt(0)
	v_cvt_pk_bf16_f32 v8, v0, v8
	ds_read_b32 v0, v17 offset:264
	ds_read_b32 v9, v17 offset:396
	v_readlane_b32 s74, v251, 15
	v_readlane_b32 s75, v251, 16
	v_readlane_b32 s73, v248, 25
	s_waitcnt lgkmcnt(1)
	s_waitcnt lgkmcnt(0)
	v_cvt_pk_bf16_f32 v9, v0, v9
	ds_read_b32 v0, v17 offset:528
	ds_read_b32 v10, v17 offset:660
	s_waitcnt lgkmcnt(1)
	s_waitcnt lgkmcnt(0)
	v_cvt_pk_bf16_f32 v10, v0, v10
	ds_read_b32 v0, v17 offset:792
	ds_read_b32 v11, v17 offset:924
	s_waitcnt lgkmcnt(1)
	s_waitcnt lgkmcnt(0)
	v_cvt_pk_bf16_f32 v11, v0, v11
	v_lshlrev_b32_e32 v0, 12, v25
	v_lshl_add_u64 v[12:13], v[6:7], 0, v[0:1]
	global_store_dwordx4 v[12:13], v[8:11], off
	ds_read_b32 v0, v17 offset:32
	ds_read_b32 v8, v17 offset:164
	s_waitcnt lgkmcnt(0)
	v_cvt_pk_bf16_f32 v8, v0, v8
	ds_read_b32 v0, v17 offset:296
	ds_read_b32 v9, v17 offset:428
	s_waitcnt lgkmcnt(0)
	v_cvt_pk_bf16_f32 v9, v0, v9
	ds_read_b32 v0, v17 offset:560
	ds_read_b32 v10, v17 offset:692
	s_waitcnt lgkmcnt(0)
	v_cvt_pk_bf16_f32 v10, v0, v10
	ds_read_b32 v0, v17 offset:824
	ds_read_b32 v11, v17 offset:956
	s_waitcnt lgkmcnt(0)
	v_cvt_pk_bf16_f32 v11, v0, v11
	v_lshlrev_b32_e32 v0, 12, v24
	v_lshl_add_u64 v[12:13], v[6:7], 0, v[0:1]
	global_store_dwordx4 v[12:13], v[8:11], off
	ds_read_b32 v0, v17 offset:64
	ds_read_b32 v8, v17 offset:196
	s_waitcnt lgkmcnt(0)
	v_cvt_pk_bf16_f32 v8, v0, v8
	ds_read_b32 v0, v17 offset:328
	ds_read_b32 v9, v17 offset:460
	s_waitcnt lgkmcnt(0)
	v_cvt_pk_bf16_f32 v9, v0, v9
	ds_read_b32 v0, v17 offset:592
	ds_read_b32 v10, v17 offset:724
	s_waitcnt lgkmcnt(0)
	v_cvt_pk_bf16_f32 v10, v0, v10
	ds_read_b32 v0, v17 offset:856
	ds_read_b32 v11, v17 offset:988
	s_waitcnt lgkmcnt(0)
	v_cvt_pk_bf16_f32 v11, v0, v11
	v_lshlrev_b32_e32 v0, 12, v23
	v_lshl_add_u64 v[12:13], v[6:7], 0, v[0:1]
	global_store_dwordx4 v[12:13], v[8:11], off
	ds_read_b32 v0, v17 offset:96
	ds_read_b32 v8, v17 offset:228
	s_waitcnt lgkmcnt(0)
	v_cvt_pk_bf16_f32 v8, v0, v8
	ds_read_b32 v0, v17 offset:360
	ds_read_b32 v9, v17 offset:492
	s_waitcnt lgkmcnt(0)
	v_cvt_pk_bf16_f32 v9, v0, v9
	ds_read_b32 v0, v17 offset:624
	ds_read_b32 v10, v17 offset:756
	s_waitcnt lgkmcnt(0)
	v_cvt_pk_bf16_f32 v10, v0, v10
	ds_read_b32 v0, v17 offset:888
	ds_read_b32 v11, v17 offset:1020
	s_waitcnt lgkmcnt(0)
	v_bfe_u32 v12, v0, 16, 1
	v_add3_u32 v0, v0, v12, s26
	v_bfe_u32 v12, v11, 16, 1
	v_lshrrev_b32_e32 v0, 16, v0
	v_add3_u32 v11, v11, v12, s26
	v_and_or_b32 v11, v11, s24, v0
	v_lshlrev_b32_e32 v0, 12, v22
	v_lshl_add_u64 v[6:7], v[6:7], 0, v[0:1]
	global_store_dwordx4 v[6:7], v[8:11], off
	s_waitcnt lgkmcnt(0)
;     ...
;     const int nblk = N / 32, kb = item / nblk, nb = item % nblk, k0 = 64 * kb, n0 = 32 * nb;
;     float tv_[32];
; #pragma unroll
;     for (int i = 0; i < 32; ++i) tv_[i] = W[(size_t)(k0 + 2 * i + (lane >> 5)) * N + n0 + (lane & 31)];
; __device__ __forceinline__ void convert_range(LAS unsigned char* lds, const Params& p, const int lo, const int hi, const int gw, const int NGW) {
;     ...
;         if (r < 2 * I_PB) { const int l = r / I_PB; r -= l * I_PB; p0_transpose_item(p.in[17] + (size_t)l * LW * DM, LW, DM, (bf16*)(ws + WS_WCAT + l * SZ_WCAT), scr, r, lane, KCAT, PW); continue; } r -= 2 * I_PB;
.LBB0_297:
	s_andn2_saveexec_b64 s[46:47], s[46:47]
	s_cbranch_execz .LBB0_299
	v_add_u32_e32 v0, 0x1000, v5
	v_lshrrev_b32_e32 v0, 11, v0
	v_readlane_b32 s68, v251, 9
	v_lshlrev_b64 v[8:9], 24, v[0:1]
	v_readlane_b32 s70, v251, 11
	v_readlane_b32 s71, v251, 12
	s_mov_b32 s3, 0xc00000
	v_mov_b32_e32 v13, v1
	v_lshl_add_u64 v[26:27], s[70:71], 0, v[8:9]
	v_mov_b64_e32 v[8:9], s[0:1]
	v_mad_u64_u32 v[8:9], s[6:7], v0, s3, v[8:9]
	v_lshl_add_u64 v[12:13], v[26:27], 0, v[12:13]
	v_lshlrev_b32_e32 v0, 2, v2
	v_lshl_add_u64 v[12:13], v[12:13], 0, v[0:1]
	v_mov_b32_e32 v11, v1
	v_lshl_add_u64 v[10:11], v[12:13], 0, v[10:11]
	v_add_co_u32_e32 v12, vcc, s22, v10
	s_mov_b32 s3, 0x8000
	s_nop 0
	v_addc_co_u32_e32 v13, vcc, 0, v11, vcc
	global_load_dword v0, v[10:11], off
	global_load_dword v7, v[12:13], off
	v_add_co_u32_e32 v12, vcc, s3, v10
	s_mov_b32 s3, 0xc000
	s_nop 0
	v_addc_co_u32_e32 v13, vcc, 0, v11, vcc
	global_load_dword v26, v[12:13], off
	v_add_co_u32_e32 v12, vcc, s3, v10
	s_mov_b32 s3, 0x14000
	s_nop 0
	v_addc_co_u32_e32 v13, vcc, 0, v11, vcc
	global_load_dword v27, v[12:13], off
	v_add_co_u32_e32 v12, vcc, s15, v10
	s_mov_b64 s[6:7], 0x5000800
	s_nop 0
	v_addc_co_u32_e32 v13, vcc, 0, v11, vcc
	global_load_dword v28, v[12:13], off
	v_add_co_u32_e32 v12, vcc, s3, v10
	s_mov_b32 s3, 0x18000
	s_nop 0
	v_addc_co_u32_e32 v13, vcc, 0, v11, vcc
	global_load_dword v29, v[12:13], off
	v_add_co_u32_e32 v12, vcc, s3, v10
	s_mov_b32 s3, 0x1c000
	s_nop 0
	v_addc_co_u32_e32 v13, vcc, 0, v11, vcc
	global_load_dword v30, v[12:13], off
	v_add_co_u32_e32 v12, vcc, s3, v10
	s_mov_b32 s3, 0x20000
	s_nop 0
	v_addc_co_u32_e32 v13, vcc, 0, v11, vcc
	global_load_dword v31, v[12:13], off
	v_add_co_u32_e32 v12, vcc, s3, v10
	s_mov_b32 s3, 0x24000
	s_nop 0
	v_addc_co_u32_e32 v13, vcc, 0, v11, vcc
	global_load_dword v32, v[12:13], off
	v_add_co_u32_e32 v12, vcc, s3, v10
	s_mov_b32 s3, 0x28000
	s_nop 0
	v_addc_co_u32_e32 v13, vcc, 0, v11, vcc
	global_load_dword v33, v[12:13], off
	v_add_co_u32_e32 v12, vcc, s3, v10
	s_mov_b32 s3, 0x2c000
	s_nop 0
	v_addc_co_u32_e32 v13, vcc, 0, v11, vcc
	global_load_dword v34, v[12:13], off
	v_add_co_u32_e32 v12, vcc, s3, v10
	s_mov_b32 s3, 0x30000
	s_nop 0
	v_addc_co_u32_e32 v13, vcc, 0, v11, vcc
	global_load_dword v35, v[12:13], off
	v_add_co_u32_e32 v12, vcc, s3, v10
	s_mov_b32 s3, 0x34000
	s_nop 0
	v_addc_co_u32_e32 v13, vcc, 0, v11, vcc
	global_load_dword v36, v[12:13], off
	v_add_co_u32_e32 v12, vcc, s3, v10
	s_mov_b32 s3, 0x38000
	s_nop 0
	v_addc_co_u32_e32 v13, vcc, 0, v11, vcc
	global_load_dword v37, v[12:13], off
	v_add_co_u32_e32 v12, vcc, s3, v10
	s_mov_b32 s3, 0x3c000
	s_nop 0
	v_addc_co_u32_e32 v13, vcc, 0, v11, vcc
	global_load_dword v38, v[12:13], off
	v_add_co_u32_e32 v12, vcc, s3, v10
	s_mov_b32 s3, 0x44000
	s_nop 0
	v_addc_co_u32_e32 v13, vcc, 0, v11, vcc
	global_load_dword v39, v[12:13], off
	v_add_co_u32_e32 v12, vcc, s14, v10
	v_readlane_b32 s72, v251, 13
	s_nop 0
	v_addc_co_u32_e32 v13, vcc, 0, v11, vcc
	global_load_dword v40, v[12:13], off
	v_add_co_u32_e32 v12, vcc, s3, v10
	s_mov_b32 s3, 0x48000
	s_nop 0
	v_addc_co_u32_e32 v13, vcc, 0, v11, vcc
	global_load_dword v41, v[12:13], off
	v_add_co_u32_e32 v12, vcc, s3, v10
	s_mov_b32 s3, 0x4c000
	s_nop 0
	v_addc_co_u32_e32 v13, vcc, 0, v11, vcc
	global_load_dword v42, v[12:13], off
	v_add_co_u32_e32 v12, vcc, s3, v10
	s_mov_b32 s3, 0x50000
	s_nop 0
	v_addc_co_u32_e32 v13, vcc, 0, v11, vcc
	global_load_dword v43, v[12:13], off
	v_add_co_u32_e32 v12, vcc, s3, v10
	s_mov_b32 s3, 0x54000
	s_nop 0
	v_addc_co_u32_e32 v13, vcc, 0, v11, vcc
	global_load_dword v44, v[12:13], off
	v_add_co_u32_e32 v12, vcc, s3, v10
	s_mov_b32 s3, 0x58000
	s_nop 0
	v_addc_co_u32_e32 v13, vcc, 0, v11, vcc
	global_load_dword v45, v[12:13], off
	v_add_co_u32_e32 v12, vcc, s3, v10
	s_mov_b32 s3, 0x5c000
	s_nop 0
	v_addc_co_u32_e32 v13, vcc, 0, v11, vcc
	global_load_dword v46, v[12:13], off
	v_add_co_u32_e32 v12, vcc, s3, v10
	s_mov_b32 s3, 0x60000
	s_nop 0
	v_addc_co_u32_e32 v13, vcc, 0, v11, vcc
	global_load_dword v47, v[12:13], off
	v_add_co_u32_e32 v12, vcc, s3, v10
	s_mov_b32 s3, 0x64000
	s_nop 0
	v_addc_co_u32_e32 v13, vcc, 0, v11, vcc
	global_load_dword v48, v[12:13], off
	v_add_co_u32_e32 v12, vcc, s3, v10
	s_mov_b32 s3, 0x68000
	s_nop 0
	v_addc_co_u32_e32 v13, vcc, 0, v11, vcc
	global_load_dword v49, v[12:13], off
	v_add_co_u32_e32 v12, vcc, s3, v10
	s_mov_b32 s3, 0x6c000
	s_nop 0
	v_addc_co_u32_e32 v13, vcc, 0, v11, vcc
	global_load_dword v50, v[12:13], off
	v_add_co_u32_e32 v12, vcc, s3, v10
	s_mov_b32 s3, 0x70000
	s_nop 0
	v_addc_co_u32_e32 v13, vcc, 0, v11, vcc
	global_load_dword v51, v[12:13], off
	v_add_co_u32_e32 v12, vcc, s3, v10
	s_mov_b32 s3, 0x74000
	s_nop 0
	v_addc_co_u32_e32 v13, vcc, 0, v11, vcc
	global_load_dword v52, v[12:13], off
	v_add_co_u32_e32 v12, vcc, s3, v10
	s_mov_b32 s3, 0x78000
	s_nop 0
	v_addc_co_u32_e32 v13, vcc, 0, v11, vcc
	global_load_dword v53, v[12:13], off
	v_add_co_u32_e32 v12, vcc, s3, v10
	s_mov_b32 s3, 0x7c000
	s_nop 0
	v_addc_co_u32_e32 v13, vcc, 0, v11, vcc
	v_add_co_u32_e32 v10, vcc, s3, v10
	global_load_dword v12, v[12:13], off
	s_nop 0
	v_addc_co_u32_e32 v11, vcc, 0, v11, vcc
	global_load_dword v10, v[10:11], off
	s_waitcnt vmcnt(30)
; #define LAS __attribute__((address_space(3)))
; #define LDS_WAIT() asm volatile("s_waitcnt lgkmcnt(0)" ::: "memory")
; __device__ __forceinline__ unsigned pk2(float lo, float hi) { return f2bf(lo) | (f2bf(hi) << 16); }
;     ...
;     for (int i = 0; i < 32; ++i) scr[(2 * i + (lane >> 5)) * 33 + (lane & 31)] = tv_[i];
;     LDS_WAIT(); asm volatile("" ::: "memory");
;     const int c = lane & 7;
; #pragma unroll
;     for (int j = 0; j < 4; ++j) { const int n = (lane >> 3) + 8 * j; const LAS float* s = scr + (8 * c) * 33 + n;
;         v4u o; o.x = pk2(s[0 * 33], s[1 * 33]); o.y = pk2(s[2 * 33], s[3 * 33]); o.z = pk2(s[4 * 33], s[5 * 33]); o.w = pk2(s[6 * 33], s[7 * 33]);
;         *(v4u*)(WT + (size_t)(n0 + n) * ldw + koff + k0 + 8 * c) = o; }
;     LDS_WAIT(); asm volatile("" ::: "memory");
	ds_write2_b32 v15, v0, v7 offset1:66
	s_waitcnt vmcnt(28)
	ds_write2_b32 v15, v26, v27 offset0:132 offset1:198
	v_add_u32_e32 v0, 0x400, v15
	s_waitcnt vmcnt(26)
	ds_write2_b32 v0, v28, v29 offset0:8 offset1:74
	s_waitcnt vmcnt(24)
	ds_write2_b32 v0, v30, v31 offset0:140 offset1:206
	v_add_u32_e32 v0, 0x800, v15
	s_waitcnt vmcnt(22)
	ds_write2_b32 v0, v32, v33 offset0:16 offset1:82
	s_waitcnt vmcnt(20)
	ds_write2_b32 v0, v34, v35 offset0:148 offset1:214
	v_add_u32_e32 v0, 0xc00, v15
	s_waitcnt vmcnt(18)
	ds_write2_b32 v0, v36, v37 offset0:24 offset1:90
	s_waitcnt vmcnt(16)
	ds_write2_b32 v0, v38, v39 offset0:156 offset1:222
	v_add_u32_e32 v0, 0x1000, v15
	s_waitcnt vmcnt(14)
	ds_write2_b32 v0, v40, v41 offset0:32 offset1:98
	s_waitcnt vmcnt(12)
	ds_write2_b32 v0, v42, v43 offset0:164 offset1:230
	v_add_u32_e32 v0, 0x1400, v15
	s_waitcnt vmcnt(10)
	ds_write2_b32 v0, v44, v45 offset0:40 offset1:106
	s_waitcnt vmcnt(8)
	ds_write2_b32 v0, v46, v47 offset0:172 offset1:238
	v_add_u32_e32 v0, 0x1800, v15
	s_waitcnt vmcnt(6)
	ds_write2_b32 v0, v48, v49 offset0:48 offset1:114
	s_waitcnt vmcnt(4)
	ds_write2_b32 v0, v50, v51 offset0:180 offset1:246
	v_add_u32_e32 v0, 0x1c00, v15
	s_waitcnt vmcnt(2)
	ds_write2_b32 v0, v52, v53 offset0:56 offset1:122
	s_waitcnt vmcnt(0)
	ds_write2_b32 v0, v12, v10 offset0:188 offset1:254
	s_waitcnt lgkmcnt(0)
	v_mov_b32_e32 v7, v1
	v_lshl_add_u64 v[6:7], v[8:9], 0, v[6:7]
	v_lshlrev_b32_e32 v0, 1, v4
	v_lshl_add_u64 v[6:7], v[6:7], 0, v[0:1]
	ds_read_b32 v0, v17
	ds_read_b32 v8, v17 offset:132
	v_lshl_add_u64 v[6:7], v[6:7], 0, s[6:7]
	v_readlane_b32 s73, v251, 14
	v_readlane_b32 s72, v248, 24
	s_waitcnt lgkmcnt(0)
	v_cvt_pk_bf16_f32 v8, v0, v8
	ds_read_b32 v0, v17 offset:264
	ds_read_b32 v9, v17 offset:396
	v_readlane_b32 s73, v248, 25
	v_readlane_b32 s69, v251, 10
	v_readlane_b32 s74, v251, 15
	s_waitcnt lgkmcnt(1)
	s_waitcnt lgkmcnt(0)
	v_cvt_pk_bf16_f32 v9, v0, v9
	ds_read_b32 v0, v17 offset:528
	ds_read_b32 v10, v17 offset:660
	v_readlane_b32 s75, v251, 16
	s_waitcnt lgkmcnt(1)
	s_waitcnt lgkmcnt(0)
	v_cvt_pk_bf16_f32 v10, v0, v10
	ds_read_b32 v0, v17 offset:792
	ds_read_b32 v11, v17 offset:924
	s_waitcnt lgkmcnt(1)
	s_waitcnt lgkmcnt(0)
	v_cvt_pk_bf16_f32 v11, v0, v11
	v_mul_u32_u24_e32 v0, 0xc00, v25
	v_lshlrev_b32_e32 v0, 1, v0
	v_lshl_add_u64 v[12:13], v[6:7], 0, v[0:1]
	global_store_dwordx4 v[12:13], v[8:11], off
	ds_read_b32 v0, v17 offset:32
	ds_read_b32 v8, v17 offset:164
	s_waitcnt lgkmcnt(0)
	v_cvt_pk_bf16_f32 v8, v0, v8
	ds_read_b32 v0, v17 offset:296
	ds_read_b32 v9, v17 offset:428
	s_waitcnt lgkmcnt(0)
	v_cvt_pk_bf16_f32 v9, v0, v9
	ds_read_b32 v0, v17 offset:560
	ds_read_b32 v10, v17 offset:692
	s_waitcnt lgkmcnt(0)
	v_cvt_pk_bf16_f32 v10, v0, v10
	ds_read_b32 v0, v17 offset:824
	ds_read_b32 v11, v17 offset:956
	s_waitcnt lgkmcnt(0)
	v_cvt_pk_bf16_f32 v11, v0, v11
	v_mul_u32_u24_e32 v0, 0xc00, v24
	v_lshlrev_b32_e32 v0, 1, v0
	v_lshl_add_u64 v[12:13], v[6:7], 0, v[0:1]
	global_store_dwordx4 v[12:13], v[8:11], off
	ds_read_b32 v0, v17 offset:64
	ds_read_b32 v8, v17 offset:196
	s_waitcnt lgkmcnt(0)
	v_cvt_pk_bf16_f32 v8, v0, v8
	ds_read_b32 v0, v17 offset:328
	ds_read_b32 v9, v17 offset:460
	s_waitcnt lgkmcnt(0)
	v_cvt_pk_bf16_f32 v9, v0, v9
	ds_read_b32 v0, v17 offset:592
	ds_read_b32 v10, v17 offset:724
	s_waitcnt lgkmcnt(0)
	v_cvt_pk_bf16_f32 v10, v0, v10
	ds_read_b32 v0, v17 offset:856
	ds_read_b32 v11, v17 offset:988
	s_waitcnt lgkmcnt(0)
	v_cvt_pk_bf16_f32 v11, v0, v11
	v_mul_u32_u24_e32 v0, 0xc00, v23
	v_lshlrev_b32_e32 v0, 1, v0
	v_lshl_add_u64 v[12:13], v[6:7], 0, v[0:1]
	global_store_dwordx4 v[12:13], v[8:11], off
	ds_read_b32 v0, v17 offset:96
	ds_read_b32 v8, v17 offset:228
	s_waitcnt lgkmcnt(0)
	v_cvt_pk_bf16_f32 v8, v0, v8
	ds_read_b32 v0, v17 offset:360
	ds_read_b32 v9, v17 offset:492
	s_waitcnt lgkmcnt(0)
	v_cvt_pk_bf16_f32 v9, v0, v9
	ds_read_b32 v0, v17 offset:624
	ds_read_b32 v10, v17 offset:756
	s_waitcnt lgkmcnt(0)
	v_cvt_pk_bf16_f32 v10, v0, v10
	ds_read_b32 v0, v17 offset:888
	ds_read_b32 v11, v17 offset:1020
	s_waitcnt lgkmcnt(0)
	v_cvt_pk_bf16_f32 v11, v0, v11
	v_mul_u32_u24_e32 v0, 0xc00, v22
	v_lshlrev_b32_e32 v0, 1, v0
	v_lshl_add_u64 v[6:7], v[6:7], 0, v[0:1]
	global_store_dwordx4 v[6:7], v[8:11], off
	s_waitcnt lgkmcnt(0)

;     ...
;     const int nblk = N / 32, kb = item / nblk, nb = item % nblk, k0 = 64 * kb, n0 = 32 * nb;
;     float tv_[32];
; #pragma unroll
;     for (int i = 0; i < 32; ++i) tv_[i] = W[(size_t)(k0 + 2 * i + (lane >> 5)) * N + n0 + (lane & 31)];
; __device__ __forceinline__ void convert_range(LAS unsigned char* lds, const Params& p, const int lo, const int hi, const int gw, const int NGW) {
;     ...
;         if (r < 2 * I_PA) { const int l = r / I_PA; r -= l * I_PA; p0_transpose_item(p.in[16] + (size_t)l * PW * DM, PW, DM, (bf16*)(ws + WS_WCAT + l * SZ_WCAT), scr, r, lane, KCAT, 0); continue; } r -= 2 * I_PA;
.LBB0_300:
	s_andn2_saveexec_b64 s[44:45], s[44:45]
	s_cbranch_execz .LBB0_302
	v_add_u32_e32 v0, 0x1800, v5
	v_lshrrev_b32_e32 v0, 10, v0
	v_readlane_b32 s68, v251, 9
	v_lshlrev_b64 v[6:7], 23, v[0:1]
	v_readlane_b32 s69, v251, 10
	s_mov_b32 s3, 0xc00000
	v_and_b32_e32 v10, 0x7e0, v21
	v_lshl_add_u64 v[12:13], s[68:69], 0, v[6:7]
	v_mov_b64_e32 v[6:7], s[38:39]
	v_mad_u64_u32 v[6:7], s[6:7], v0, s3, v[6:7]
	v_and_b32_e32 v11, 0x3c0, v8
	v_lshlrev_b32_e32 v0, 2, v10
	v_or_b32_e32 v22, v11, v14
	v_lshl_add_u64 v[8:9], v[12:13], 0, v[0:1]
	v_lshlrev_b32_e32 v0, 2, v2
	v_lshl_add_u64 v[8:9], v[8:9], 0, v[0:1]
	v_lshlrev_b32_e32 v0, 13, v22
	v_lshl_add_u64 v[8:9], v[8:9], 0, v[0:1]
	v_add_co_u32_e32 v12, vcc, s22, v8
	s_mov_b32 s3, 0x8000
	s_nop 0
	v_addc_co_u32_e32 v13, vcc, 0, v9, vcc
	global_load_dword v0, v[8:9], off
	global_load_dword v22, v[12:13], off
	v_add_co_u32_e32 v12, vcc, s3, v8
	s_mov_b32 s3, 0xc000
	s_nop 0
	v_addc_co_u32_e32 v13, vcc, 0, v9, vcc
	global_load_dword v23, v[12:13], off
	v_add_co_u32_e32 v12, vcc, s3, v8
	s_mov_b32 s3, 0x14000
	s_nop 0
	v_addc_co_u32_e32 v13, vcc, 0, v9, vcc
	s_waitcnt lgkmcnt(0)
	global_load_dword v24, v[12:13], off
	v_add_co_u32_e32 v12, vcc, s15, v8
	v_readlane_b32 s72, v251, 13
	s_nop 0
	v_addc_co_u32_e32 v13, vcc, 0, v9, vcc
	global_load_dword v25, v[12:13], off
	v_add_co_u32_e32 v12, vcc, s3, v8
	s_mov_b32 s3, 0x18000
	s_nop 0
	v_addc_co_u32_e32 v13, vcc, 0, v9, vcc
	global_load_dword v26, v[12:13], off
	v_add_co_u32_e32 v12, vcc, s3, v8
	s_mov_b32 s3, 0x1c000
	s_nop 0
	v_addc_co_u32_e32 v13, vcc, 0, v9, vcc
	global_load_dword v27, v[12:13], off
	v_add_co_u32_e32 v12, vcc, s3, v8
	s_mov_b32 s3, 0x20000
	s_nop 0
	v_addc_co_u32_e32 v13, vcc, 0, v9, vcc
	global_load_dword v28, v[12:13], off
	v_add_co_u32_e32 v12, vcc, s3, v8
	s_mov_b32 s3, 0x24000
	s_nop 0
	v_addc_co_u32_e32 v13, vcc, 0, v9, vcc
	global_load_dword v29, v[12:13], off
	v_add_co_u32_e32 v12, vcc, s3, v8
	s_mov_b32 s3, 0x28000
	s_nop 0
	v_addc_co_u32_e32 v13, vcc, 0, v9, vcc
	global_load_dword v30, v[12:13], off
	v_add_co_u32_e32 v12, vcc, s3, v8
	s_mov_b32 s3, 0x2c000
	s_nop 0
	v_addc_co_u32_e32 v13, vcc, 0, v9, vcc
	global_load_dword v31, v[12:13], off
	v_add_co_u32_e32 v12, vcc, s3, v8
	s_mov_b32 s3, 0x30000
	s_nop 0
	v_addc_co_u32_e32 v13, vcc, 0, v9, vcc
	global_load_dword v32, v[12:13], off
	v_add_co_u32_e32 v12, vcc, s3, v8
	s_mov_b32 s3, 0x34000
	s_nop 0
	v_addc_co_u32_e32 v13, vcc, 0, v9, vcc
	global_load_dword v33, v[12:13], off
	v_add_co_u32_e32 v12, vcc, s3, v8
	s_mov_b32 s3, 0x38000
	s_nop 0
	v_addc_co_u32_e32 v13, vcc, 0, v9, vcc
	global_load_dword v34, v[12:13], off
	v_add_co_u32_e32 v12, vcc, s3, v8
	s_mov_b32 s3, 0x3c000
	s_nop 0
	v_addc_co_u32_e32 v13, vcc, 0, v9, vcc
	global_load_dword v35, v[12:13], off
	v_add_co_u32_e32 v12, vcc, s3, v8
	s_mov_b32 s3, 0x44000
	s_nop 0
	v_addc_co_u32_e32 v13, vcc, 0, v9, vcc
	global_load_dword v36, v[12:13], off
	v_add_co_u32_e32 v12, vcc, s14, v8
	v_readlane_b32 s73, v251, 14
	s_nop 0
	v_addc_co_u32_e32 v13, vcc, 0, v9, vcc
	global_load_dword v37, v[12:13], off
	v_add_co_u32_e32 v12, vcc, s3, v8
	s_mov_b32 s3, 0x48000
	s_nop 0
	v_addc_co_u32_e32 v13, vcc, 0, v9, vcc
	global_load_dword v38, v[12:13], off
	v_add_co_u32_e32 v12, vcc, s3, v8
	s_mov_b32 s3, 0x4c000
	s_nop 0
	v_addc_co_u32_e32 v13, vcc, 0, v9, vcc
	global_load_dword v39, v[12:13], off
	v_add_co_u32_e32 v12, vcc, s3, v8
	s_mov_b32 s3, 0x50000
	s_nop 0
	v_addc_co_u32_e32 v13, vcc, 0, v9, vcc
	global_load_dword v40, v[12:13], off
	v_add_co_u32_e32 v12, vcc, s3, v8
	s_mov_b32 s3, 0x54000
	s_nop 0
	v_addc_co_u32_e32 v13, vcc, 0, v9, vcc
	global_load_dword v41, v[12:13], off
	v_add_co_u32_e32 v12, vcc, s3, v8
	s_mov_b32 s3, 0x58000
	s_nop 0
	v_addc_co_u32_e32 v13, vcc, 0, v9, vcc
	global_load_dword v42, v[12:13], off
	v_add_co_u32_e32 v12, vcc, s3, v8
	s_mov_b32 s3, 0x5c000
	s_nop 0
	v_addc_co_u32_e32 v13, vcc, 0, v9, vcc
	global_load_dword v43, v[12:13], off
	v_add_co_u32_e32 v12, vcc, s3, v8
	s_mov_b32 s3, 0x60000
	s_nop 0
	v_addc_co_u32_e32 v13, vcc, 0, v9, vcc
	global_load_dword v44, v[12:13], off
	v_add_co_u32_e32 v12, vcc, s3, v8
	s_mov_b32 s3, 0x64000
	s_nop 0
	v_addc_co_u32_e32 v13, vcc, 0, v9, vcc
	global_load_dword v45, v[12:13], off
	v_add_co_u32_e32 v12, vcc, s3, v8
	s_mov_b32 s3, 0x68000
	s_nop 0
	v_addc_co_u32_e32 v13, vcc, 0, v9, vcc
	global_load_dword v46, v[12:13], off
	v_add_co_u32_e32 v12, vcc, s3, v8
	s_mov_b32 s3, 0x6c000
	s_nop 0
	v_addc_co_u32_e32 v13, vcc, 0, v9, vcc
	global_load_dword v47, v[12:13], off
	v_add_co_u32_e32 v12, vcc, s3, v8
	s_mov_b32 s3, 0x70000
	s_nop 0
	v_addc_co_u32_e32 v13, vcc, 0, v9, vcc
	global_load_dword v48, v[12:13], off
	v_add_co_u32_e32 v12, vcc, s3, v8
	s_mov_b32 s3, 0x74000
	s_nop 0
	v_addc_co_u32_e32 v13, vcc, 0, v9, vcc
	global_load_dword v49, v[12:13], off
	v_add_co_u32_e32 v12, vcc, s3, v8
	s_mov_b32 s3, 0x78000
	s_nop 0
	v_addc_co_u32_e32 v13, vcc, 0, v9, vcc
	global_load_dword v50, v[12:13], off
	v_add_co_u32_e32 v12, vcc, s3, v8
	s_mov_b32 s3, 0x7c000
	s_nop 0
	v_addc_co_u32_e32 v13, vcc, 0, v9, vcc
	v_add_co_u32_e32 v8, vcc, s3, v8
	global_load_dword v12, v[12:13], off
	s_nop 0
	v_addc_co_u32_e32 v9, vcc, 0, v9, vcc
	global_load_dword v8, v[8:9], off
	s_waitcnt vmcnt(30)
; #define LAS __attribute__((address_space(3)))
; #define LDS_WAIT() asm volatile("s_waitcnt lgkmcnt(0)" ::: "memory")
; __device__ __forceinline__ unsigned pk2(float lo, float hi) { return f2bf(lo) | (f2bf(hi) << 16); }
;     ...
;     for (int i = 0; i < 32; ++i) scr[(2 * i + (lane >> 5)) * 33 + (lane & 31)] = tv_[i];
;     LDS_WAIT(); asm volatile("" ::: "memory");
;     const int c = lane & 7;
; #pragma unroll
;     for (int j = 0; j < 4; ++j) { const int n = (lane >> 3) + 8 * j; const LAS float* s = scr + (8 * c) * 33 + n;
;         v4u o; o.x = pk2(s[0 * 33], s[1 * 33]); o.y = pk2(s[2 * 33], s[3 * 33]); o.z = pk2(s[4 * 33], s[5 * 33]); o.w = pk2(s[6 * 33], s[7 * 33]);
;         *(v4u*)(WT + (size_t)(n0 + n) * ldw + koff + k0 + 8 * c) = o; }
;     LDS_WAIT(); asm volatile("" ::: "memory");
	ds_write2_b32 v15, v0, v22 offset1:66
	s_waitcnt vmcnt(28)
	ds_write2_b32 v15, v23, v24 offset0:132 offset1:198
	v_add_u32_e32 v0, 0x400, v15
	s_waitcnt vmcnt(26)
	ds_write2_b32 v0, v25, v26 offset0:8 offset1:74
	s_waitcnt vmcnt(24)
	ds_write2_b32 v0, v27, v28 offset0:140 offset1:206
	v_add_u32_e32 v0, 0x800, v15
	s_waitcnt vmcnt(22)
	ds_write2_b32 v0, v29, v30 offset0:16 offset1:82
	s_waitcnt vmcnt(20)
	ds_write2_b32 v0, v31, v32 offset0:148 offset1:214
	v_add_u32_e32 v0, 0xc00, v15
	s_waitcnt vmcnt(18)
	ds_write2_b32 v0, v33, v34 offset0:24 offset1:90
	s_waitcnt vmcnt(16)
	ds_write2_b32 v0, v35, v36 offset0:156 offset1:222
	v_add_u32_e32 v0, 0x1000, v15
	s_waitcnt vmcnt(14)
	ds_write2_b32 v0, v37, v38 offset0:32 offset1:98
	s_waitcnt vmcnt(12)
	ds_write2_b32 v0, v39, v40 offset0:164 offset1:230
	v_add_u32_e32 v0, 0x1400, v15
	s_waitcnt vmcnt(10)
	ds_write2_b32 v0, v41, v42 offset0:40 offset1:106
	s_waitcnt vmcnt(8)
	ds_write2_b32 v0, v43, v44 offset0:172 offset1:238
	v_add_u32_e32 v0, 0x1800, v15
	s_waitcnt vmcnt(6)
	ds_write2_b32 v0, v45, v46 offset0:48 offset1:114
	s_waitcnt vmcnt(4)
	ds_write2_b32 v0, v47, v48 offset0:180 offset1:246
	v_add_u32_e32 v0, 0x1c00, v15
	s_waitcnt vmcnt(2)
	ds_write2_b32 v0, v49, v50 offset0:56 offset1:122
	s_waitcnt vmcnt(0)
	ds_write2_b32 v0, v12, v8 offset0:188 offset1:254
	s_waitcnt lgkmcnt(0)
	v_lshlrev_b32_e32 v0, 1, v11
	v_lshl_add_u64 v[6:7], v[6:7], 0, v[0:1]
	v_lshlrev_b32_e32 v0, 1, v4
	v_lshl_add_u64 v[6:7], v[6:7], 0, v[0:1]
	ds_read_b32 v0, v17
	ds_read_b32 v8, v17 offset:132
	v_readlane_b32 s72, v248, 24
	v_readlane_b32 s73, v248, 25
	v_readlane_b32 s70, v251, 11
	s_waitcnt lgkmcnt(0)
	v_cvt_pk_bf16_f32 v22, v0, v8
	ds_read_b32 v0, v17 offset:264
	ds_read_b32 v8, v17 offset:396
	v_readlane_b32 s71, v251, 12
	v_readlane_b32 s74, v251, 15
	v_readlane_b32 s75, v251, 16
	s_waitcnt lgkmcnt(1)
	s_waitcnt lgkmcnt(0)
	v_cvt_pk_bf16_f32 v23, v0, v8
	ds_read_b32 v0, v17 offset:528
	ds_read_b32 v8, v17 offset:660
	s_waitcnt lgkmcnt(1)
	s_waitcnt lgkmcnt(0)
	v_cvt_pk_bf16_f32 v24, v0, v8
	ds_read_b32 v0, v17 offset:792
	ds_read_b32 v8, v17 offset:924
	s_waitcnt lgkmcnt(1)
	s_waitcnt lgkmcnt(0)
	v_cvt_pk_bf16_f32 v25, v0, v8
	v_or_b32_e32 v0, v10, v16
	v_mul_u32_u24_e32 v0, 0xc00, v0
	v_lshlrev_b32_e32 v0, 1, v0
	v_lshl_add_u64 v[8:9], v[6:7], 0, v[0:1]
	global_store_dwordx4 v[8:9], v[22:25], off
	ds_read_b32 v0, v17 offset:32
	ds_read_b32 v8, v17 offset:164
	s_waitcnt lgkmcnt(0)
	v_cvt_pk_bf16_f32 v22, v0, v8
	ds_read_b32 v0, v17 offset:296
	ds_read_b32 v8, v17 offset:428
	s_waitcnt lgkmcnt(0)
	v_cvt_pk_bf16_f32 v23, v0, v8
	ds_read_b32 v0, v17 offset:560
	ds_read_b32 v8, v17 offset:692
	s_waitcnt lgkmcnt(0)
	v_cvt_pk_bf16_f32 v24, v0, v8
	ds_read_b32 v0, v17 offset:824
	ds_read_b32 v8, v17 offset:956
	s_waitcnt lgkmcnt(0)
	v_cvt_pk_bf16_f32 v25, v0, v8
	v_or_b32_e32 v0, v10, v18
	v_mul_u32_u24_e32 v0, 0xc00, v0
	v_lshlrev_b32_e32 v0, 1, v0
	v_lshl_add_u64 v[8:9], v[6:7], 0, v[0:1]
	global_store_dwordx4 v[8:9], v[22:25], off
	ds_read_b32 v0, v17 offset:64
	ds_read_b32 v8, v17 offset:196
	s_waitcnt lgkmcnt(0)
	v_cvt_pk_bf16_f32 v22, v0, v8
	ds_read_b32 v0, v17 offset:328
	ds_read_b32 v8, v17 offset:460
	s_waitcnt lgkmcnt(0)
	v_cvt_pk_bf16_f32 v23, v0, v8
	ds_read_b32 v0, v17 offset:592
	ds_read_b32 v8, v17 offset:724
	s_waitcnt lgkmcnt(0)
	v_cvt_pk_bf16_f32 v24, v0, v8
	ds_read_b32 v0, v17 offset:856
	ds_read_b32 v8, v17 offset:988
	s_waitcnt lgkmcnt(0)
	v_cvt_pk_bf16_f32 v25, v0, v8
	v_or_b32_e32 v0, v10, v19
	v_mul_u32_u24_e32 v0, 0xc00, v0
	v_lshlrev_b32_e32 v0, 1, v0
	v_lshl_add_u64 v[8:9], v[6:7], 0, v[0:1]
	global_store_dwordx4 v[8:9], v[22:25], off
	ds_read_b32 v0, v17 offset:96
	ds_read_b32 v8, v17 offset:228
	s_waitcnt lgkmcnt(0)
	v_cvt_pk_bf16_f32 v22, v0, v8
	ds_read_b32 v0, v17 offset:360
	ds_read_b32 v8, v17 offset:492
	s_waitcnt lgkmcnt(0)
	v_cvt_pk_bf16_f32 v23, v0, v8
	ds_read_b32 v0, v17 offset:624
	ds_read_b32 v8, v17 offset:756
	s_waitcnt lgkmcnt(0)
	v_cvt_pk_bf16_f32 v24, v0, v8
	ds_read_b32 v0, v17 offset:888
	ds_read_b32 v8, v17 offset:1020
	s_waitcnt lgkmcnt(0)
	v_cvt_pk_bf16_f32 v25, v0, v8
	v_or_b32_e32 v0, v10, v20
	v_mul_u32_u24_e32 v0, 0xc00, v0
	v_lshlrev_b32_e32 v0, 1, v0
	v_lshl_add_u64 v[6:7], v[6:7], 0, v[0:1]
	global_store_dwordx4 v[6:7], v[22:25], off
	s_waitcnt lgkmcnt(0)

;     ...
;     const int nblk = N / 32, kb = item / nblk, nb = item % nblk, k0 = 64 * kb, n0 = 32 * nb;
;     float tv_[32];
; #pragma unroll
;     for (int i = 0; i < 32; ++i) tv_[i] = W[(size_t)(k0 + 2 * i + (lane >> 5)) * N + n0 + (lane & 31)];
; #pragma unroll
;     for (int i = 0; i < 32; ++i) scr[(2 * i + (lane >> 5)) * 33 + (lane & 31)] = tv_[i];
; __device__ __forceinline__ void convert_range(LAS unsigned char* lds, const Params& p, const int lo, const int hi, const int gw, const int NGW) {
;     ...
;         if (r < 2 * I_IN) { const int l = r / I_IN; r -= l * I_IN; p0_transpose_item(p.in[5] + (size_t)l * DM * NC, DM, NC, (bf16*)(ws + WS_WIN + l * SZ_WIN), scr, r, lane); continue; } r -= 2 * I_IN;
.LBB0_303:
	s_andn2_saveexec_b64 s[42:43], s[42:43]
	s_cbranch_execz .LBB0_292
	v_mul_hi_i32 v0, v8, s5
	v_lshrrev_b32_e32 v6, 31, v0
	v_ashrrev_i32_e32 v0, 12, v0
	v_add_u32_e32 v9, v0, v6
	v_readlane_b32 s60, v251, 21
	v_mul_i32_i24_e32 v0, 0xffffd800, v9
	s_movk_i32 s3, 0x6800
	v_readlane_b32 s70, v251, 31
	v_readlane_b32 s71, v251, 32
	v_add3_u32 v0, v0, v5, s3
	s_mov_b32 s3, 0x5000000
	v_mov_b64_e32 v[6:7], s[70:71]
	v_mad_i64_i32 v[10:11], s[6:7], v9, s3, v[6:7]
	v_mul_hi_i32 v6, v0, s5
	v_lshrrev_b32_e32 v7, 31, v6
	v_ashrrev_i32_e32 v6, 7, v6
	v_add_u32_e32 v6, v6, v7
	v_mul_i32_i24_e32 v7, 0x140, v6
	v_sub_u32_e32 v0, v0, v7
	v_lshlrev_b32_e32 v8, 6, v6
	v_lshlrev_b32_e32 v6, 5, v0
	v_ashrrev_i32_e32 v7, 31, v6
	v_lshl_add_u64 v[10:11], v[6:7], 2, v[10:11]
	v_lshlrev_b32_e32 v0, 2, v2
	v_or_b32_e32 v22, v8, v14
	v_lshl_add_u64 v[10:11], v[10:11], 0, v[0:1]
	v_mad_i64_i32 v[12:13], s[6:7], v22, s23, v[10:11]
	v_or_b32_e32 v7, 2, v22
	global_load_dword v0, v[12:13], off
	v_mad_i64_i32 v[12:13], s[6:7], v7, s23, v[10:11]
	global_load_dword v7, v[12:13], off
	v_or_b32_e32 v12, 4, v22
	v_mad_i64_i32 v[12:13], s[6:7], v12, s23, v[10:11]
	global_load_dword v23, v[12:13], off
	v_or_b32_e32 v12, 6, v22
	v_mad_i64_i32 v[12:13], s[6:7], v12, s23, v[10:11]
	s_waitcnt lgkmcnt(0)
	global_load_dword v24, v[12:13], off
	v_or_b32_e32 v12, 8, v22
	v_mad_i64_i32 v[12:13], s[6:7], v12, s23, v[10:11]
	global_load_dword v25, v[12:13], off
	v_or_b32_e32 v12, 10, v22
	v_mad_i64_i32 v[12:13], s[6:7], v12, s23, v[10:11]
	global_load_dword v26, v[12:13], off
	v_or_b32_e32 v12, 12, v22
	v_mad_i64_i32 v[12:13], s[6:7], v12, s23, v[10:11]
	global_load_dword v27, v[12:13], off
	v_or_b32_e32 v12, 14, v22
	v_mad_i64_i32 v[12:13], s[6:7], v12, s23, v[10:11]
	global_load_dword v28, v[12:13], off
	v_or_b32_e32 v12, 16, v22
	v_mad_i64_i32 v[12:13], s[6:7], v12, s23, v[10:11]
	global_load_dword v29, v[12:13], off
	v_or_b32_e32 v12, 18, v22
	v_mad_i64_i32 v[12:13], s[6:7], v12, s23, v[10:11]
	global_load_dword v30, v[12:13], off
	v_or_b32_e32 v12, 20, v22
	v_mad_i64_i32 v[12:13], s[6:7], v12, s23, v[10:11]
	global_load_dword v31, v[12:13], off
	v_or_b32_e32 v12, 22, v22
	v_mad_i64_i32 v[12:13], s[6:7], v12, s23, v[10:11]
	global_load_dword v32, v[12:13], off
	v_or_b32_e32 v12, 24, v22
	v_mad_i64_i32 v[12:13], s[6:7], v12, s23, v[10:11]
	global_load_dword v33, v[12:13], off
	v_or_b32_e32 v12, 26, v22
	v_mad_i64_i32 v[12:13], s[6:7], v12, s23, v[10:11]
	global_load_dword v34, v[12:13], off
	v_or_b32_e32 v12, 28, v22
	v_mad_i64_i32 v[12:13], s[6:7], v12, s23, v[10:11]
	global_load_dword v35, v[12:13], off
	v_or_b32_e32 v12, 30, v22
	v_mad_i64_i32 v[12:13], s[6:7], v12, s23, v[10:11]
	global_load_dword v36, v[12:13], off
	v_or_b32_e32 v12, 32, v22
	v_mad_i64_i32 v[12:13], s[6:7], v12, s23, v[10:11]
	global_load_dword v37, v[12:13], off
	v_or_b32_e32 v12, 34, v22
	v_mad_i64_i32 v[12:13], s[6:7], v12, s23, v[10:11]
	global_load_dword v38, v[12:13], off
	v_or_b32_e32 v12, 36, v22
	v_mad_i64_i32 v[12:13], s[6:7], v12, s23, v[10:11]
	global_load_dword v39, v[12:13], off
	v_or_b32_e32 v12, 38, v22
	v_mad_i64_i32 v[12:13], s[6:7], v12, s23, v[10:11]
	global_load_dword v40, v[12:13], off
	v_or_b32_e32 v12, 40, v22
	v_mad_i64_i32 v[12:13], s[6:7], v12, s23, v[10:11]
	global_load_dword v41, v[12:13], off
	v_or_b32_e32 v12, 42, v22
	v_mad_i64_i32 v[12:13], s[6:7], v12, s23, v[10:11]
	global_load_dword v42, v[12:13], off
	v_or_b32_e32 v12, 44, v22
	v_mad_i64_i32 v[12:13], s[6:7], v12, s23, v[10:11]
	global_load_dword v43, v[12:13], off
	v_or_b32_e32 v12, 46, v22
	v_mad_i64_i32 v[12:13], s[6:7], v12, s23, v[10:11]
	global_load_dword v44, v[12:13], off
	v_or_b32_e32 v12, 48, v22
	v_mad_i64_i32 v[12:13], s[6:7], v12, s23, v[10:11]
	global_load_dword v45, v[12:13], off
	v_or_b32_e32 v12, 50, v22
	v_mad_i64_i32 v[12:13], s[6:7], v12, s23, v[10:11]
	global_load_dword v46, v[12:13], off
	v_or_b32_e32 v12, 52, v22
	v_mad_i64_i32 v[12:13], s[6:7], v12, s23, v[10:11]
	global_load_dword v47, v[12:13], off
	v_or_b32_e32 v12, 54, v22
	v_mad_i64_i32 v[12:13], s[6:7], v12, s23, v[10:11]
	global_load_dword v48, v[12:13], off
	v_or_b32_e32 v12, 56, v22
	v_mad_i64_i32 v[12:13], s[6:7], v12, s23, v[10:11]
	global_load_dword v49, v[12:13], off
	v_or_b32_e32 v12, 58, v22
	v_mad_i64_i32 v[12:13], s[6:7], v12, s23, v[10:11]
	global_load_dword v50, v[12:13], off
	v_or_b32_e32 v12, 60, v22
	v_mad_i64_i32 v[12:13], s[6:7], v12, s23, v[10:11]
	global_load_dword v12, v[12:13], off
	v_or_b32_e32 v13, 62, v22
	v_mad_i64_i32 v[10:11], s[6:7], v13, s23, v[10:11]
	global_load_dword v13, v[10:11], off
	s_waitcnt vmcnt(30)
	ds_write2_b32 v15, v0, v7 offset1:66
	s_waitcnt vmcnt(28)
	ds_write2_b32 v15, v23, v24 offset0:132 offset1:198
	v_add_u32_e32 v0, 0x400, v15
	s_waitcnt vmcnt(26)
	ds_write2_b32 v0, v25, v26 offset0:8 offset1:74
	s_waitcnt vmcnt(24)
; #define LAS __attribute__((address_space(3)))
; #define LDS_WAIT() asm volatile("s_waitcnt lgkmcnt(0)" ::: "memory")
; __device__ __forceinline__ unsigned pk2(float lo, float hi) { return f2bf(lo) | (f2bf(hi) << 16); }
;     ...
;     for (int i = 0; i < 32; ++i) scr[(2 * i + (lane >> 5)) * 33 + (lane & 31)] = tv_[i];
;     LDS_WAIT(); asm volatile("" ::: "memory");
;     const int c = lane & 7;
; #pragma unroll
;     for (int j = 0; j < 4; ++j) { const int n = (lane >> 3) + 8 * j; const LAS float* s = scr + (8 * c) * 33 + n;
;         v4u o; o.x = pk2(s[0 * 33], s[1 * 33]); o.y = pk2(s[2 * 33], s[3 * 33]); o.z = pk2(s[4 * 33], s[5 * 33]); o.w = pk2(s[6 * 33], s[7 * 33]);
;         *(v4u*)(WT + (size_t)(n0 + n) * ldw + koff + k0 + 8 * c) = o; }
;     LDS_WAIT(); asm volatile("" ::: "memory");
	ds_write2_b32 v0, v27, v28 offset0:140 offset1:206
	v_add_u32_e32 v0, 0x800, v15
	s_waitcnt vmcnt(22)
	ds_write2_b32 v0, v29, v30 offset0:16 offset1:82
	s_waitcnt vmcnt(20)
	ds_write2_b32 v0, v31, v32 offset0:148 offset1:214
	v_add_u32_e32 v0, 0xc00, v15
	s_waitcnt vmcnt(18)
	ds_write2_b32 v0, v33, v34 offset0:24 offset1:90
	s_waitcnt vmcnt(16)
	ds_write2_b32 v0, v35, v36 offset0:156 offset1:222
	v_add_u32_e32 v0, 0x1000, v15
	s_waitcnt vmcnt(14)
	ds_write2_b32 v0, v37, v38 offset0:32 offset1:98
	s_waitcnt vmcnt(12)
	ds_write2_b32 v0, v39, v40 offset0:164 offset1:230
	v_add_u32_e32 v0, 0x1400, v15
	s_waitcnt vmcnt(10)
	ds_write2_b32 v0, v41, v42 offset0:40 offset1:106
	s_waitcnt vmcnt(8)
	ds_write2_b32 v0, v43, v44 offset0:172 offset1:238
	v_add_u32_e32 v0, 0x1800, v15
	s_waitcnt vmcnt(6)
	ds_write2_b32 v0, v45, v46 offset0:48 offset1:114
	s_waitcnt vmcnt(4)
	ds_write2_b32 v0, v47, v48 offset0:180 offset1:246
	v_add_u32_e32 v0, 0x1c00, v15
	s_waitcnt vmcnt(2)
	ds_write2_b32 v0, v49, v50 offset0:56 offset1:122
	s_waitcnt vmcnt(0)
	ds_write2_b32 v0, v12, v13 offset0:188 offset1:254
	v_mov_b64_e32 v[10:11], s[0:1]
	s_mov_b32 s3, 0x2800000
	s_waitcnt lgkmcnt(0)
	v_mad_i64_i32 v[10:11], s[6:7], v9, s3, v[10:11]
	v_ashrrev_i32_e32 v9, 31, v8
	ds_read_b32 v7, v17
	ds_read_b32 v12, v17 offset:528
	ds_read_b32 v22, v17 offset:924
	v_lshl_add_u64 v[8:9], v[8:9], 1, v[10:11]
	v_lshlrev_b32_e32 v0, 1, v4
	v_lshl_add_u64 v[8:9], v[8:9], 0, v[0:1]
	ds_read_b32 v0, v17 offset:132
	ds_read_b32 v11, v17 offset:264
	s_waitcnt lgkmcnt(0)
	v_cvt_pk_bf16_f32 v10, v7, v0
	ds_read_b32 v0, v17 offset:396
	ds_read_b32 v13, v17 offset:792
	s_waitcnt lgkmcnt(1)
	v_cvt_pk_bf16_f32 v11, v11, v0
	ds_read_b32 v0, v17 offset:660
	v_readlane_b32 s72, v251, 33
	s_waitcnt lgkmcnt(0)
	v_cvt_pk_bf16_f32 v12, v12, v0
	v_bfe_u32 v7, v22, 16, 1
	v_bfe_u32 v0, v13, 16, 1
	v_add3_u32 v7, v22, v7, s26
	v_or_b32_e32 v22, v6, v16
	v_add3_u32 v0, v13, v0, s26
	v_ashrrev_i32_e32 v23, 31, v22
	v_lshrrev_b32_e32 v0, 16, v0
	v_lshlrev_b64 v[22:23], 12, v[22:23]
	v_and_or_b32 v13, v7, s24, v0
	v_lshl_add_u64 v[22:23], v[8:9], 0, v[22:23]
	global_store_dwordx4 v[22:23], v[10:13], off
	ds_read_b32 v0, v17 offset:32
	ds_read_b32 v7, v17 offset:164
	ds_read_b32 v11, v17 offset:296
	ds_read_b32 v12, v17 offset:560
	ds_read_b32 v13, v17 offset:824
	s_waitcnt lgkmcnt(0)
	v_cvt_pk_bf16_f32 v10, v0, v7
	ds_read_b32 v0, v17 offset:428
	ds_read_b32 v22, v17 offset:956
	s_waitcnt lgkmcnt(0)
	v_cvt_pk_bf16_f32 v11, v11, v0
	ds_read_b32 v0, v17 offset:692
	v_readlane_b32 s73, v251, 34
	s_waitcnt lgkmcnt(0)
	v_cvt_pk_bf16_f32 v12, v12, v0
	v_bfe_u32 v7, v22, 16, 1
	v_bfe_u32 v0, v13, 16, 1
	v_add3_u32 v7, v22, v7, s26
	v_or_b32_e32 v22, v6, v18
	v_add3_u32 v0, v13, v0, s26
	v_ashrrev_i32_e32 v23, 31, v22
	v_lshrrev_b32_e32 v0, 16, v0
	v_lshlrev_b64 v[22:23], 12, v[22:23]
	v_and_or_b32 v13, v7, s24, v0
	v_lshl_add_u64 v[22:23], v[8:9], 0, v[22:23]
	global_store_dwordx4 v[22:23], v[10:13], off
	ds_read_b32 v0, v17 offset:64
	ds_read_b32 v7, v17 offset:196
	ds_read_b32 v11, v17 offset:328
	ds_read_b32 v12, v17 offset:592
	ds_read_b32 v13, v17 offset:856
	s_waitcnt lgkmcnt(0)
	v_cvt_pk_bf16_f32 v10, v0, v7
	ds_read_b32 v0, v17 offset:460
	ds_read_b32 v22, v17 offset:988
	s_waitcnt lgkmcnt(0)
	v_cvt_pk_bf16_f32 v11, v11, v0
	ds_read_b32 v0, v17 offset:724
	v_readlane_b32 s72, v248, 24
	s_waitcnt lgkmcnt(0)
	v_cvt_pk_bf16_f32 v12, v12, v0
	v_bfe_u32 v7, v22, 16, 1
	v_bfe_u32 v0, v13, 16, 1
	v_add3_u32 v7, v22, v7, s26
	v_or_b32_e32 v22, v6, v19
	v_add3_u32 v0, v13, v0, s26
	v_ashrrev_i32_e32 v23, 31, v22
	v_lshrrev_b32_e32 v0, 16, v0
	v_lshlrev_b64 v[22:23], 12, v[22:23]
	v_and_or_b32 v13, v7, s24, v0
	v_lshl_add_u64 v[22:23], v[8:9], 0, v[22:23]
	global_store_dwordx4 v[22:23], v[10:13], off
	ds_read_b32 v0, v17 offset:96
	ds_read_b32 v7, v17 offset:228
	ds_read_b32 v11, v17 offset:360
	ds_read_b32 v12, v17 offset:624
	ds_read_b32 v13, v17 offset:888
	s_waitcnt lgkmcnt(0)
	v_cvt_pk_bf16_f32 v10, v0, v7
	ds_read_b32 v0, v17 offset:492
	ds_read_b32 v22, v17 offset:1020
	s_waitcnt lgkmcnt(0)
	v_cvt_pk_bf16_f32 v11, v11, v0
	ds_read_b32 v0, v17 offset:756
	v_or_b32_e32 v6, v6, v20
	s_waitcnt lgkmcnt(0)
	v_cvt_pk_bf16_f32 v12, v12, v0
	v_cvt_pk_bf16_f32 v13, v13, v22
	v_ashrrev_i32_e32 v7, 31, v6
	v_lshlrev_b64 v[6:7], 12, v[6:7]
	v_lshl_add_u64 v[6:7], v[8:9], 0, v[6:7]
	global_store_dwordx4 v[6:7], v[10:13], off
	s_waitcnt lgkmcnt(0)
	v_readlane_b32 s73, v248, 25
	v_readlane_b32 s61, v251, 22
	v_readlane_b32 s62, v251, 23
	v_readlane_b32 s63, v251, 24
	v_readlane_b32 s64, v251, 25
	v_readlane_b32 s65, v251, 26
	v_readlane_b32 s66, v251, 27
	v_readlane_b32 s67, v251, 28
	v_readlane_b32 s68, v251, 29
	v_readlane_b32 s69, v251, 30
	v_readlane_b32 s74, v251, 35
	v_readlane_b32 s75, v251, 36
	s_branch .LBB0_292

;     ...
;     const int nblk = N / 32, kb = item / nblk, nb = item % nblk, k0 = 64 * kb, n0 = 32 * nb;
;     float tv_[32];
; #pragma unroll
;     for (int i = 0; i < 32; ++i) tv_[i] = W[(size_t)(k0 + 2 * i + (lane >> 5)) * N + n0 + (lane & 31)];
; #pragma unroll
;     for (int i = 0; i < 32; ++i) scr[(2 * i + (lane >> 5)) * 33 + (lane & 31)] = tv_[i];
; __device__ __forceinline__ void convert_range(LAS unsigned char* lds, const Params& p, const int lo, const int hi, const int gw, const int NGW) {
;     ...
;     for (int it = lo + gw; it < hi; it += NGW) {
;         int r = it;
;         if (r < 2 * I_IN) { const int l = r / I_IN; r -= l * I_IN; p0_transpose_item(p.in[5] + (size_t)l * DM * NC, DM, NC, (bf16*)(ws + WS_WIN + l * SZ_WIN), scr, r, lane); continue; } r -= 2 * I_IN;
.LBB0_308:
	v_mul_hi_i32 v3, v10, s5
	v_lshrrev_b32_e32 v4, 31, v3
	v_ashrrev_i32_e32 v3, 12, v3
	v_add_u32_e32 v3, v3, v4
	v_mul_i32_i24_e32 v4, 0xffffd800, v3
	v_add_u32_e32 v8, v4, v10
	v_mov_b64_e32 v[4:5], s[46:47]
	v_mad_i64_i32 v[18:19], s[2:3], v3, s7, v[4:5]
	v_mov_b64_e32 v[4:5], s[0:1]
	v_mad_i64_i32 v[6:7], s[2:3], v3, s6, v[4:5]
	v_mul_hi_i32 v3, v8, s5
	v_lshrrev_b32_e32 v4, 31, v3
	v_ashrrev_i32_e32 v3, 7, v3
	v_add_u32_e32 v3, v3, v4
	v_mul_i32_i24_e32 v4, 0x140, v3
	v_sub_u32_e32 v4, v8, v4
	v_lshlrev_b32_e32 v4, 5, v4
	v_ashrrev_i32_e32 v5, 31, v4
	v_lshlrev_b32_e32 v8, 6, v3
	v_lshl_add_u64 v[18:19], v[4:5], 2, v[18:19]
	v_or_b32_e32 v46, v8, v11
	v_lshl_add_u64 v[42:43], v[18:19], 0, v[0:1]
	v_mad_i64_i32 v[18:19], s[2:3], v46, s23, v[42:43]
	v_or_b32_e32 v3, 2, v46
	global_load_dword v47, v[18:19], off
	v_mad_i64_i32 v[18:19], s[2:3], v3, s23, v[42:43]
	v_or_b32_e32 v3, 4, v46
	global_load_dword v48, v[18:19], off
	v_mad_i64_i32 v[18:19], s[2:3], v3, s23, v[42:43]
	v_or_b32_e32 v3, 6, v46
	global_load_dword v49, v[18:19], off
	v_mad_i64_i32 v[18:19], s[2:3], v3, s23, v[42:43]
	v_or_b32_e32 v3, 8, v46
	global_load_dword v50, v[18:19], off
	v_mad_i64_i32 v[18:19], s[2:3], v3, s23, v[42:43]
	v_or_b32_e32 v5, 10, v46
	global_load_dword v3, v[18:19], off
	v_mad_i64_i32 v[18:19], s[2:3], v5, s23, v[42:43]
	v_or_b32_e32 v5, 12, v46
	v_mad_i64_i32 v[20:21], s[2:3], v5, s23, v[42:43]
	v_or_b32_e32 v5, 14, v46
	global_load_dword v18, v[18:19], off
	v_or_b32_e32 v9, 18, v46
	global_load_dword v22, v[20:21], off
	v_mad_i64_i32 v[20:21], s[2:3], v5, s23, v[42:43]
	v_or_b32_e32 v5, 16, v46
	global_load_dword v30, v[20:21], off
	v_mad_i64_i32 v[20:21], s[2:3], v5, s23, v[42:43]
	global_load_dword v5, v[20:21], off
	v_mad_i64_i32 v[20:21], s[2:3], v9, s23, v[42:43]
	v_or_b32_e32 v9, 20, v46
	s_waitcnt lgkmcnt(0)
	v_mad_i64_i32 v[24:25], s[2:3], v9, s23, v[42:43]
	v_or_b32_e32 v9, 22, v46
	v_mad_i64_i32 v[26:27], s[2:3], v9, s23, v[42:43]
	v_or_b32_e32 v9, 24, v46
	global_load_dword v20, v[20:21], off
	v_or_b32_e32 v19, 26, v46
	global_load_dword v25, v[24:25], off
	v_or_b32_e32 v39, 60, v46
	global_load_dword v33, v[26:27], off
	v_mad_i64_i32 v[26:27], s[2:3], v9, s23, v[42:43]
	global_load_dword v9, v[26:27], off
	v_mad_i64_i32 v[26:27], s[2:3], v19, s23, v[42:43]
	v_or_b32_e32 v19, 28, v46
	global_load_dword v23, v[26:27], off
	v_mad_i64_i32 v[26:27], s[2:3], v19, s23, v[42:43]
	v_or_b32_e32 v19, 30, v46
	global_load_dword v28, v[26:27], off
	v_mad_i64_i32 v[26:27], s[2:3], v19, s23, v[42:43]
	v_or_b32_e32 v19, 32, v46
	global_load_dword v36, v[26:27], off
	v_mad_i64_i32 v[26:27], s[2:3], v19, s23, v[42:43]
	v_or_b32_e32 v21, 34, v46
	global_load_dword v19, v[26:27], off
	v_mad_i64_i32 v[26:27], s[2:3], v21, s23, v[42:43]
	v_or_b32_e32 v21, 36, v46
	v_mad_i64_i32 v[34:35], s[2:3], v21, s23, v[42:43]
	v_or_b32_e32 v21, 38, v46
	global_load_dword v26, v[26:27], off
	v_or_b32_e32 v24, 42, v46
	global_load_dword v31, v[34:35], off
	v_mad_i64_i32 v[34:35], s[2:3], v21, s23, v[42:43]
	v_or_b32_e32 v21, 40, v46
	global_load_dword v38, v[34:35], off
	v_mad_i64_i32 v[34:35], s[2:3], v21, s23, v[42:43]
	global_load_dword v21, v[34:35], off
	v_mad_i64_i32 v[34:35], s[2:3], v24, s23, v[42:43]
	v_or_b32_e32 v24, 44, v46
	global_load_dword v29, v[34:35], off
	v_mad_i64_i32 v[34:35], s[2:3], v24, s23, v[42:43]
	v_or_b32_e32 v24, 46, v46
	v_mad_i64_i32 v[40:41], s[2:3], v24, s23, v[42:43]
	v_or_b32_e32 v24, 48, v46
	v_mad_i64_i32 v[44:45], s[2:3], v24, s23, v[42:43]
	v_or_b32_e32 v27, 50, v46
	global_load_dword v34, v[34:35], off
	s_nop 0
	global_load_dword v40, v[40:41], off
	s_nop 0
	global_load_dword v24, v[44:45], off
	v_mad_i64_i32 v[44:45], s[2:3], v27, s23, v[42:43]
	v_or_b32_e32 v27, 52, v46
	global_load_dword v32, v[44:45], off
	v_mad_i64_i32 v[44:45], s[2:3], v27, s23, v[42:43]
	v_or_b32_e32 v27, 54, v46
	global_load_dword v37, v[44:45], off
	v_mad_i64_i32 v[44:45], s[2:3], v27, s23, v[42:43]
	v_or_b32_e32 v27, 56, v46
	global_load_dword v41, v[44:45], off
	v_mad_i64_i32 v[44:45], s[2:3], v27, s23, v[42:43]
	v_or_b32_e32 v35, 58, v46
	global_load_dword v27, v[44:45], off
	v_mad_i64_i32 v[44:45], s[2:3], v35, s23, v[42:43]
	global_load_dword v35, v[44:45], off
	v_mad_i64_i32 v[44:45], s[2:3], v39, s23, v[42:43]
	global_load_dword v39, v[44:45], off
	v_or_b32_e32 v44, 62, v46
	v_mad_i64_i32 v[42:43], s[2:3], v44, s23, v[42:43]
	global_load_dword v42, v[42:43], off
	v_add_u32_e32 v43, 0x400, v17
	s_waitcnt vmcnt(30)
; #define LAS __attribute__((address_space(3)))
; #define LDS_WAIT() asm volatile("s_waitcnt lgkmcnt(0)" ::: "memory")
; __device__ __forceinline__ unsigned pk2(float lo, float hi) { return f2bf(lo) | (f2bf(hi) << 16); }
;     ...
;     for (int i = 0; i < 32; ++i) scr[(2 * i + (lane >> 5)) * 33 + (lane & 31)] = tv_[i];
;     LDS_WAIT(); asm volatile("" ::: "memory");
;     const int c = lane & 7;
; #pragma unroll
;     for (int j = 0; j < 4; ++j) { const int n = (lane >> 3) + 8 * j; const LAS float* s = scr + (8 * c) * 33 + n;
;         v4u o; o.x = pk2(s[0 * 33], s[1 * 33]); o.y = pk2(s[2 * 33], s[3 * 33]); o.z = pk2(s[4 * 33], s[5 * 33]); o.w = pk2(s[6 * 33], s[7 * 33]);
;         *(v4u*)(WT + (size_t)(n0 + n) * ldw + koff + k0 + 8 * c) = o; }
;     LDS_WAIT(); asm volatile("" ::: "memory");
	ds_write2_b32 v17, v47, v48 offset1:66
	s_waitcnt vmcnt(28)
	ds_write2_b32 v17, v49, v50 offset0:132 offset1:198
	s_waitcnt vmcnt(26)
	ds_write2_b32 v43, v3, v18 offset0:8 offset1:74
	s_waitcnt vmcnt(24)
	ds_write2_b32 v43, v22, v30 offset0:140 offset1:206
	v_add_u32_e32 v3, 0x800, v17
	s_waitcnt vmcnt(22)
	ds_write2_b32 v3, v5, v20 offset0:16 offset1:82
	s_waitcnt vmcnt(20)
	ds_write2_b32 v3, v25, v33 offset0:148 offset1:214
	v_add_u32_e32 v3, 0xc00, v17
	s_waitcnt vmcnt(18)
	ds_write2_b32 v3, v9, v23 offset0:24 offset1:90
	s_waitcnt vmcnt(16)
	ds_write2_b32 v3, v28, v36 offset0:156 offset1:222
	v_add_u32_e32 v3, 0x1000, v17
	s_waitcnt vmcnt(14)
	ds_write2_b32 v3, v19, v26 offset0:32 offset1:98
	s_waitcnt vmcnt(12)
	ds_write2_b32 v3, v31, v38 offset0:164 offset1:230
	v_add_u32_e32 v3, 0x1400, v17
	s_waitcnt vmcnt(10)
	ds_write2_b32 v3, v21, v29 offset0:40 offset1:106
	s_waitcnt vmcnt(8)
	ds_write2_b32 v3, v34, v40 offset0:172 offset1:238
	v_add_u32_e32 v3, 0x1800, v17
	s_waitcnt vmcnt(6)
	ds_write2_b32 v3, v24, v32 offset0:48 offset1:114
	s_waitcnt vmcnt(4)
	ds_write2_b32 v3, v37, v41 offset0:180 offset1:246
	v_add_u32_e32 v3, 0x1c00, v17
	s_waitcnt vmcnt(2)
	ds_write2_b32 v3, v27, v35 offset0:56 offset1:122
	s_waitcnt vmcnt(0)
	ds_write2_b32 v3, v39, v42 offset0:188 offset1:254
	s_waitcnt lgkmcnt(0)
	v_ashrrev_i32_e32 v9, 31, v8
	v_lshl_add_u64 v[6:7], v[8:9], 1, v[6:7]
	v_mov_b32_e32 v3, v1
	v_lshl_add_u64 v[18:19], v[6:7], 0, v[2:3]
	ds_read_b32 v3, v13
	ds_read_b32 v5, v13 offset:132
	v_or_b32_e32 v20, v4, v12
	v_ashrrev_i32_e32 v21, 31, v20
	v_lshlrev_b64 v[20:21], 12, v[20:21]
	s_waitcnt lgkmcnt(0)
	v_cvt_pk_bf16_f32 v6, v3, v5
	ds_read_b32 v3, v13 offset:264
	ds_read_b32 v5, v13 offset:396
	v_lshl_add_u64 v[20:21], v[18:19], 0, v[20:21]
	s_movk_i32 s2, 0x2aff
	v_cmp_lt_i32_e32 vcc, s2, v10
	s_waitcnt lgkmcnt(1)
	s_waitcnt lgkmcnt(0)
	v_cvt_pk_bf16_f32 v7, v3, v5
	ds_read_b32 v3, v13 offset:528
	ds_read_b32 v5, v13 offset:660
	s_or_b64 s[18:19], vcc, s[18:19]
	s_waitcnt lgkmcnt(1)
	s_waitcnt lgkmcnt(0)
	v_cvt_pk_bf16_f32 v8, v3, v5
	ds_read_b32 v3, v13 offset:792
	ds_read_b32 v5, v13 offset:924
	s_waitcnt lgkmcnt(1)
	s_waitcnt lgkmcnt(0)
	v_cvt_pk_bf16_f32 v9, v3, v5
	global_store_dwordx4 v[20:21], v[6:9], off
	ds_read_b32 v3, v13 offset:32
	ds_read_b32 v5, v13 offset:164
	v_or_b32_e32 v20, v4, v14
	v_ashrrev_i32_e32 v21, 31, v20
	v_lshlrev_b64 v[20:21], 12, v[20:21]
	s_waitcnt lgkmcnt(0)
	v_cvt_pk_bf16_f32 v6, v3, v5
	ds_read_b32 v3, v13 offset:296
	ds_read_b32 v5, v13 offset:428
	v_lshl_add_u64 v[20:21], v[18:19], 0, v[20:21]
	s_waitcnt lgkmcnt(0)
	v_cvt_pk_bf16_f32 v7, v3, v5
	ds_read_b32 v3, v13 offset:560
	ds_read_b32 v5, v13 offset:692
	s_waitcnt lgkmcnt(0)
	v_cvt_pk_bf16_f32 v8, v3, v5
	ds_read_b32 v3, v13 offset:824
	ds_read_b32 v5, v13 offset:956
	s_waitcnt lgkmcnt(0)
	v_cvt_pk_bf16_f32 v9, v3, v5
	global_store_dwordx4 v[20:21], v[6:9], off
	ds_read_b32 v3, v13 offset:64
	ds_read_b32 v5, v13 offset:196
	v_or_b32_e32 v20, v4, v15
	v_ashrrev_i32_e32 v21, 31, v20
	v_lshlrev_b64 v[20:21], 12, v[20:21]
	s_waitcnt lgkmcnt(0)
	v_cvt_pk_bf16_f32 v6, v3, v5
	ds_read_b32 v3, v13 offset:328
	ds_read_b32 v5, v13 offset:460
	v_lshl_add_u64 v[20:21], v[18:19], 0, v[20:21]
	v_or_b32_e32 v4, v4, v16
	s_waitcnt lgkmcnt(0)
	v_cvt_pk_bf16_f32 v7, v3, v5
	ds_read_b32 v3, v13 offset:592
	ds_read_b32 v5, v13 offset:724
	s_waitcnt lgkmcnt(0)
	v_cvt_pk_bf16_f32 v8, v3, v5
	ds_read_b32 v3, v13 offset:856
	ds_read_b32 v5, v13 offset:988
	s_waitcnt lgkmcnt(0)
	v_cvt_pk_bf16_f32 v9, v3, v5
	global_store_dwordx4 v[20:21], v[6:9], off
	ds_read_b32 v3, v13 offset:96
	ds_read_b32 v5, v13 offset:228
	s_waitcnt lgkmcnt(0)
	v_cvt_pk_bf16_f32 v6, v3, v5
	ds_read_b32 v3, v13 offset:360
	ds_read_b32 v5, v13 offset:492
	s_waitcnt lgkmcnt(0)
	v_cvt_pk_bf16_f32 v7, v3, v5
	ds_read_b32 v3, v13 offset:624
	ds_read_b32 v5, v13 offset:756
	s_waitcnt lgkmcnt(0)
	v_cvt_pk_bf16_f32 v8, v3, v5
	ds_read_b32 v3, v13 offset:888
	ds_read_b32 v5, v13 offset:1020
	s_waitcnt lgkmcnt(0)
	v_cvt_pk_bf16_f32 v9, v3, v5
	v_ashrrev_i32_e32 v5, 31, v4
	v_lshlrev_b64 v[4:5], 12, v[4:5]
	v_lshl_add_u64 v[4:5], v[18:19], 0, v[4:5]
	global_store_dwordx4 v[4:5], v[6:9], off
	s_waitcnt lgkmcnt(0)
	v_add_u32_e32 v3, 0x300, v10
	v_mov_b32_e32 v10, v3
	s_andn2_b64 exec, exec, s[18:19]
	s_cbranch_execnz .LBB0_308

; #define LAS __attribute__((address_space(3)))
; __device__ __forceinline__ unsigned pk2(float lo, float hi) { return f2bf(lo) | (f2bf(hi) << 16); }
; __device__ __forceinline__ float bflo(unsigned w) { return __uint_as_float(w << 16); }
; __device__ __forceinline__ float bfhi(unsigned w) { return __uint_as_float(w & 0xffff0000u); }
; __device__ __forceinline__ void mix_phase(LAS unsigned char* lds, const Params& p, const int layer) {
;     ...
;                 for (int m = 0; m < 4; ++m)
; #pragma unroll
;                     for (int jj = 0; jj < 4; ++jj) XC[(m * 16 + fq * 4 + jj) * 132 + cw + fr] = hl[m][jj];
;                 __syncthreads();
;             {
;                 const int row = yrow, c16 = yc16; const size_t r = (size_t)(r0 + row);
;                 const v4u g0 = sgc0, g1 = sgc1;
;                 const f32x4 h0 = *(const LAS f32x4*)(XC + row * 132 + c16), h1 = *(const LAS f32x4*)(XC + row * 132 + c16 + 4),
;                             h2 = *(const LAS f32x4*)(XC + row * 132 + c16 + 8), h3 = *(const LAS f32x4*)(XC + row * 132 + c16 + 12);
;                 v4u o0, o1;
;                 o0.x = pk2(h0[0] * bflo(g0.x), h0[1] * bfhi(g0.x)); o0.y = pk2(h0[2] * bflo(g0.y), h0[3] * bfhi(g0.y)); o0.z = pk2(h1[0] * bflo(g0.z), h1[1] * bfhi(g0.z)); o0.w = pk2(h1[2] * bflo(g0.w), h1[3] * bfhi(g0.w));
;                 o1.x = pk2(h2[0] * bflo(g1.x), h2[1] * bfhi(g1.x)); o1.y = pk2(h2[2] * bflo(g1.y), h2[3] * bfhi(g1.y)); o1.z = pk2(h3[0] * bflo(g1.z), h3[1] * bfhi(g1.z)); o1.w = pk2(h3[2] * bflo(g1.w), h3[3] * bfhi(g1.w));
;                 bf16* yp = (bf16*)(ws + WS_YA) + r * KCAT + PW + c0 + c16;
;                 *(v4u*)yp = o0; *(v4u*)(yp + 8) = o1;
;             }
.Lpf_skip:
	v_add_u32_e32 v0, 0x400, v151
	ds_write2_b32 v0, v156, v157 offset0:8 offset1:140
	v_add_u32_e32 v0, 0x2000, v151
	ds_write2_b32 v0, v78, v79 offset0:64 offset1:196
	v_add_u32_e32 v0, 0x2400, v151
	ds_write2_b32 v0, v168, v169 offset0:72 offset1:204
	v_add_u32_e32 v0, 0x4200, v151
	ds_write2_b32 v0, v76, v77 offset1:132
	v_add_u32_e32 v0, 0x4600, v151
	ds_write2_b32 v0, v180, v181 offset0:8 offset1:140
	v_add_u32_e32 v0, 0x6200, v151
	ds_write2_b32 v0, v74, v75 offset0:64 offset1:196
	v_add_u32_e32 v0, 0x6600, v151
	ds_write2_b32 v0, v190, v191 offset0:72 offset1:204
	v_lshlrev_b32_e32 v0, 2, v140
	v_add3_u32 v0, s6, v234, v0
	ds_write2_b32 v151, v80, v81 offset1:132
	s_waitcnt lgkmcnt(0)
	s_barrier
	ds_read_b128 v[74:77], v0
	ds_read_b128 v[78:81], v0 offset:16
	ds_read_b128 v[82:85], v0 offset:32
	ds_read_b128 v[86:89], v0 offset:48
	v_lshlrev_b32_e32 v91, 16, v71
	v_lshlrev_b32_e32 v90, 16, v70
	s_waitcnt lgkmcnt(0)
	v_mov_b32_e32 v93, v76
	v_and_b32_e32 v71, 0xffff0000, v71
	v_and_b32_e32 v70, 0xffff0000, v70
	v_mov_b32_e32 v76, v75
	v_mov_b32_e32 v92, v74
	v_pk_mul_f32 v[70:71], v[76:77], v[70:71]
	v_lshlrev_b32_e32 v75, 16, v73
	v_lshlrev_b32_e32 v74, 16, v72
	v_mov_b32_e32 v77, v80
	v_and_b32_e32 v73, 0xffff0000, v73
	v_and_b32_e32 v72, 0xffff0000, v72
	v_mov_b32_e32 v80, v79
	v_mov_b32_e32 v76, v78
	v_pk_mul_f32 v[72:73], v[80:81], v[72:73]
	v_pk_mul_f32 v[90:91], v[92:93], v[90:91]
	v_pk_mul_f32 v[74:75], v[76:77], v[74:75]
	v_cvt_pk_bf16_f32 v72, v74, v72
	v_cvt_pk_bf16_f32 v71, v91, v71
	v_cvt_pk_bf16_f32 v70, v90, v70
	v_cvt_pk_bf16_f32 v73, v75, v73
	v_lshlrev_b32_e32 v75, 16, v67
	v_lshlrev_b32_e32 v74, 16, v66
	v_mov_b32_e32 v76, v82
	v_mov_b32_e32 v77, v84
	v_pk_mul_f32 v[74:75], v[76:77], v[74:75]
	v_lshlrev_b32_e32 v77, 16, v69
	v_lshlrev_b32_e32 v76, 16, v68
	v_mov_b32_e32 v79, v88
	v_and_b32_e32 v69, 0xffff0000, v69
	v_and_b32_e32 v68, 0xffff0000, v68
	v_mov_b32_e32 v88, v87
	v_mov_b32_e32 v78, v86
	v_pk_mul_f32 v[68:69], v[88:89], v[68:69]
	v_and_b32_e32 v67, 0xffff0000, v67
	v_and_b32_e32 v66, 0xffff0000, v66
	v_mov_b32_e32 v84, v83
	v_pk_mul_f32 v[76:77], v[78:79], v[76:77]
	v_pk_mul_f32 v[66:67], v[84:85], v[66:67]
	v_cvt_pk_bf16_f32 v68, v76, v68
	v_cvt_pk_bf16_f32 v69, v77, v69
	v_cvt_pk_bf16_f32 v66, v74, v66
	v_cvt_pk_bf16_f32 v67, v75, v67
	v_mov_b64_e32 v[74:75], s[36:37]
	s_movk_i32 s0, 0x1800
	v_mad_i64_i32 v[74:75], s[0:1], v240, s0, v[74:75]
	s_mov_b32 s53, s80
	v_lshl_add_u64 v[74:75], v[74:75], 0, s[52:53]
	v_mov_b32_e32 v151, v1
	v_lshl_add_u64 v[74:75], v[74:75], 0, v[150:151]
	s_mov_b64 s[0:1], 0x15304800
	v_lshl_add_u64 v[76:77], v[74:75], 0, s[0:1]
	v_add_co_u32_e32 v74, vcc, 0x15304000, v74
	s_mov_b32 s12, s13
	s_nop 0
	v_addc_co_u32_e32 v75, vcc, 0, v75, vcc
	s_andn2_b64 vcc, exec, s[82:83]
	global_store_dwordx4 v[74:75], v[70:73], off offset:2048
	global_store_dwordx4 v[76:77], v[66:69], off offset:16
	s_cbranch_vccz .LBB0_545

;     ...
;     const int nblk = N / 32, kb = item / nblk, nb = item % nblk, k0 = 64 * kb, n0 = 32 * nb;
;     float tv_[32];
; #pragma unroll
;     for (int i = 0; i < 32; ++i) tv_[i] = W[(size_t)(k0 + 2 * i + (lane >> 5)) * N + n0 + (lane & 31)];
; #pragma unroll
;     for (int i = 0; i < 32; ++i) scr[(2 * i + (lane >> 5)) * 33 + (lane & 31)] = tv_[i];
; __device__ __forceinline__ void convert_range(LAS unsigned char* lds, const Params& p, const int lo, const int hi, const int gw, const int NGW) {
;     ...
;     for (int it = lo + gw; it < hi; it += NGW) {
;         int r = it;
;         if (r < 2 * I_IN) { const int l = r / I_IN; r -= l * I_IN; p0_transpose_item(p.in[5] + (size_t)l * DM * NC, DM, NC, (bf16*)(ws + WS_WIN + l * SZ_WIN), scr, r, lane); continue; } r -= 2 * I_IN;
.LBB0_785:
	v_mul_hi_i32 v3, v10, s15
	v_lshrrev_b32_e32 v4, 31, v3
	v_ashrrev_i32_e32 v3, 12, v3
	v_add_u32_e32 v3, v3, v4
	v_mul_i32_i24_e32 v4, 0xffffd800, v3
	v_add_u32_e32 v8, v4, v10
	v_mov_b64_e32 v[4:5], s[70:71]
	v_mad_i64_i32 v[18:19], s[2:3], v3, s6, v[4:5]
	v_mov_b64_e32 v[4:5], s[38:39]
	v_mad_i64_i32 v[6:7], s[2:3], v3, s5, v[4:5]
	v_mul_hi_i32 v3, v8, s15
	v_lshrrev_b32_e32 v4, 31, v3
	v_ashrrev_i32_e32 v3, 7, v3
	v_add_u32_e32 v3, v3, v4
	v_mul_i32_i24_e32 v4, 0x140, v3
	v_sub_u32_e32 v4, v8, v4
	v_lshlrev_b32_e32 v4, 5, v4
	v_ashrrev_i32_e32 v5, 31, v4
	v_lshlrev_b32_e32 v8, 6, v3
	v_lshl_add_u64 v[18:19], v[4:5], 2, v[18:19]
	v_or_b32_e32 v46, v8, v11
	v_lshl_add_u64 v[42:43], v[18:19], 0, v[0:1]
	v_mad_i64_i32 v[18:19], s[2:3], v46, s23, v[42:43]
	v_or_b32_e32 v3, 2, v46
	global_load_dword v47, v[18:19], off
	v_mad_i64_i32 v[18:19], s[2:3], v3, s23, v[42:43]
	v_or_b32_e32 v3, 4, v46
	global_load_dword v48, v[18:19], off
	v_mad_i64_i32 v[18:19], s[2:3], v3, s23, v[42:43]
	v_or_b32_e32 v3, 6, v46
	global_load_dword v49, v[18:19], off
	v_mad_i64_i32 v[18:19], s[2:3], v3, s23, v[42:43]
	v_or_b32_e32 v3, 8, v46
	global_load_dword v50, v[18:19], off
	v_mad_i64_i32 v[18:19], s[2:3], v3, s23, v[42:43]
	v_or_b32_e32 v5, 10, v46
	global_load_dword v3, v[18:19], off
	v_mad_i64_i32 v[18:19], s[2:3], v5, s23, v[42:43]
	v_or_b32_e32 v5, 12, v46
	v_mad_i64_i32 v[20:21], s[2:3], v5, s23, v[42:43]
	v_or_b32_e32 v5, 14, v46
	global_load_dword v18, v[18:19], off
	v_or_b32_e32 v9, 18, v46
	global_load_dword v22, v[20:21], off
	v_mad_i64_i32 v[20:21], s[2:3], v5, s23, v[42:43]
	v_or_b32_e32 v5, 16, v46
	global_load_dword v30, v[20:21], off
	v_mad_i64_i32 v[20:21], s[2:3], v5, s23, v[42:43]
	global_load_dword v5, v[20:21], off
	v_mad_i64_i32 v[20:21], s[2:3], v9, s23, v[42:43]
	v_or_b32_e32 v9, 20, v46
	s_waitcnt lgkmcnt(0)
	v_mad_i64_i32 v[24:25], s[2:3], v9, s23, v[42:43]
	v_or_b32_e32 v9, 22, v46
	v_mad_i64_i32 v[26:27], s[2:3], v9, s23, v[42:43]
	v_or_b32_e32 v9, 24, v46
	global_load_dword v20, v[20:21], off
	v_or_b32_e32 v19, 26, v46
	global_load_dword v25, v[24:25], off
	v_or_b32_e32 v39, 60, v46
	global_load_dword v33, v[26:27], off
	v_mad_i64_i32 v[26:27], s[2:3], v9, s23, v[42:43]
	global_load_dword v9, v[26:27], off
	v_mad_i64_i32 v[26:27], s[2:3], v19, s23, v[42:43]
	v_or_b32_e32 v19, 28, v46
	global_load_dword v23, v[26:27], off
	v_mad_i64_i32 v[26:27], s[2:3], v19, s23, v[42:43]
	v_or_b32_e32 v19, 30, v46
	global_load_dword v28, v[26:27], off
	v_mad_i64_i32 v[26:27], s[2:3], v19, s23, v[42:43]
	v_or_b32_e32 v19, 32, v46
	global_load_dword v36, v[26:27], off
	v_mad_i64_i32 v[26:27], s[2:3], v19, s23, v[42:43]
	v_or_b32_e32 v21, 34, v46
	global_load_dword v19, v[26:27], off
	v_mad_i64_i32 v[26:27], s[2:3], v21, s23, v[42:43]
	v_or_b32_e32 v21, 36, v46
	v_mad_i64_i32 v[34:35], s[2:3], v21, s23, v[42:43]
	v_or_b32_e32 v21, 38, v46
	global_load_dword v26, v[26:27], off
	v_or_b32_e32 v24, 42, v46
	global_load_dword v31, v[34:35], off
	v_mad_i64_i32 v[34:35], s[2:3], v21, s23, v[42:43]
	v_or_b32_e32 v21, 40, v46
	global_load_dword v38, v[34:35], off
	v_mad_i64_i32 v[34:35], s[2:3], v21, s23, v[42:43]
	global_load_dword v21, v[34:35], off
	v_mad_i64_i32 v[34:35], s[2:3], v24, s23, v[42:43]
	v_or_b32_e32 v24, 44, v46
	global_load_dword v29, v[34:35], off
	v_mad_i64_i32 v[34:35], s[2:3], v24, s23, v[42:43]
	v_or_b32_e32 v24, 46, v46
	v_mad_i64_i32 v[40:41], s[2:3], v24, s23, v[42:43]
	v_or_b32_e32 v24, 48, v46
	v_mad_i64_i32 v[44:45], s[2:3], v24, s23, v[42:43]
	v_or_b32_e32 v27, 50, v46
	global_load_dword v34, v[34:35], off
	s_nop 0
	global_load_dword v40, v[40:41], off
	s_nop 0
	global_load_dword v24, v[44:45], off
	v_mad_i64_i32 v[44:45], s[2:3], v27, s23, v[42:43]
	v_or_b32_e32 v27, 52, v46
	global_load_dword v32, v[44:45], off
	v_mad_i64_i32 v[44:45], s[2:3], v27, s23, v[42:43]
	v_or_b32_e32 v27, 54, v46
	global_load_dword v37, v[44:45], off
	v_mad_i64_i32 v[44:45], s[2:3], v27, s23, v[42:43]
	v_or_b32_e32 v27, 56, v46
	global_load_dword v41, v[44:45], off
	v_mad_i64_i32 v[44:45], s[2:3], v27, s23, v[42:43]
	v_or_b32_e32 v35, 58, v46
	global_load_dword v27, v[44:45], off
	v_mad_i64_i32 v[44:45], s[2:3], v35, s23, v[42:43]
	global_load_dword v35, v[44:45], off
	v_mad_i64_i32 v[44:45], s[2:3], v39, s23, v[42:43]
	global_load_dword v39, v[44:45], off
	v_or_b32_e32 v44, 62, v46
	v_mad_i64_i32 v[42:43], s[2:3], v44, s23, v[42:43]
	global_load_dword v42, v[42:43], off
	v_add_u32_e32 v43, 0x400, v17
	s_waitcnt vmcnt(30)
; #define LAS __attribute__((address_space(3)))
; #define LDS_WAIT() asm volatile("s_waitcnt lgkmcnt(0)" ::: "memory")
; __device__ __forceinline__ unsigned pk2(float lo, float hi) { return f2bf(lo) | (f2bf(hi) << 16); }
;     ...
;     for (int i = 0; i < 32; ++i) scr[(2 * i + (lane >> 5)) * 33 + (lane & 31)] = tv_[i];
;     LDS_WAIT(); asm volatile("" ::: "memory");
;     const int c = lane & 7;
; #pragma unroll
;     for (int j = 0; j < 4; ++j) { const int n = (lane >> 3) + 8 * j; const LAS float* s = scr + (8 * c) * 33 + n;
;         v4u o; o.x = pk2(s[0 * 33], s[1 * 33]); o.y = pk2(s[2 * 33], s[3 * 33]); o.z = pk2(s[4 * 33], s[5 * 33]); o.w = pk2(s[6 * 33], s[7 * 33]);
;         *(v4u*)(WT + (size_t)(n0 + n) * ldw + koff + k0 + 8 * c) = o; }
;     LDS_WAIT(); asm volatile("" ::: "memory");
	ds_write2_b32 v17, v47, v48 offset1:66
	s_waitcnt vmcnt(28)
	ds_write2_b32 v17, v49, v50 offset0:132 offset1:198
	s_waitcnt vmcnt(26)
	ds_write2_b32 v43, v3, v18 offset0:8 offset1:74
	s_waitcnt vmcnt(24)
	ds_write2_b32 v43, v22, v30 offset0:140 offset1:206
	v_add_u32_e32 v3, 0x800, v17
	s_waitcnt vmcnt(22)
	ds_write2_b32 v3, v5, v20 offset0:16 offset1:82
	s_waitcnt vmcnt(20)
	ds_write2_b32 v3, v25, v33 offset0:148 offset1:214
	v_add_u32_e32 v3, 0xc00, v17
	s_waitcnt vmcnt(18)
	ds_write2_b32 v3, v9, v23 offset0:24 offset1:90
	s_waitcnt vmcnt(16)
	ds_write2_b32 v3, v28, v36 offset0:156 offset1:222
	v_add_u32_e32 v3, 0x1000, v17
	s_waitcnt vmcnt(14)
	ds_write2_b32 v3, v19, v26 offset0:32 offset1:98
	s_waitcnt vmcnt(12)
	ds_write2_b32 v3, v31, v38 offset0:164 offset1:230
	v_add_u32_e32 v3, 0x1400, v17
	s_waitcnt vmcnt(10)
	ds_write2_b32 v3, v21, v29 offset0:40 offset1:106
	s_waitcnt vmcnt(8)
	ds_write2_b32 v3, v34, v40 offset0:172 offset1:238
	v_add_u32_e32 v3, 0x1800, v17
	s_waitcnt vmcnt(6)
	ds_write2_b32 v3, v24, v32 offset0:48 offset1:114
	s_waitcnt vmcnt(4)
	ds_write2_b32 v3, v37, v41 offset0:180 offset1:246
	v_add_u32_e32 v3, 0x1c00, v17
	s_waitcnt vmcnt(2)
	ds_write2_b32 v3, v27, v35 offset0:56 offset1:122
	s_waitcnt vmcnt(0)
	ds_write2_b32 v3, v39, v42 offset0:188 offset1:254
	s_waitcnt lgkmcnt(0)
	v_ashrrev_i32_e32 v9, 31, v8
	v_lshl_add_u64 v[6:7], v[8:9], 1, v[6:7]
	v_mov_b32_e32 v3, v1
	v_lshl_add_u64 v[18:19], v[6:7], 0, v[2:3]
	ds_read_b32 v3, v13
	ds_read_b32 v5, v13 offset:132
	v_or_b32_e32 v20, v4, v12
	v_ashrrev_i32_e32 v21, 31, v20
	v_lshlrev_b64 v[20:21], 12, v[20:21]
	s_waitcnt lgkmcnt(1)
	s_waitcnt lgkmcnt(0)
	v_cvt_pk_bf16_f32 v6, v3, v5
	ds_read_b32 v3, v13 offset:264
	ds_read_b32 v5, v13 offset:396
	v_lshl_add_u64 v[20:21], v[18:19], 0, v[20:21]
	s_movk_i32 s2, 0x4aff
	v_cmp_lt_i32_e32 vcc, s2, v10
	s_waitcnt lgkmcnt(1)
	s_waitcnt lgkmcnt(0)
	v_cvt_pk_bf16_f32 v7, v3, v5
	ds_read_b32 v3, v13 offset:528
	ds_read_b32 v5, v13 offset:660
	s_or_b64 s[48:49], vcc, s[48:49]
	s_waitcnt lgkmcnt(1)
	s_waitcnt lgkmcnt(0)
	v_cvt_pk_bf16_f32 v8, v3, v5
	ds_read_b32 v3, v13 offset:792
	ds_read_b32 v5, v13 offset:924
	s_waitcnt lgkmcnt(1)
	s_waitcnt lgkmcnt(0)
	v_cvt_pk_bf16_f32 v9, v3, v5
	global_store_dwordx4 v[20:21], v[6:9], off
	ds_read_b32 v3, v13 offset:32
	ds_read_b32 v5, v13 offset:164
	v_or_b32_e32 v20, v4, v14
	v_ashrrev_i32_e32 v21, 31, v20
	v_lshlrev_b64 v[20:21], 12, v[20:21]
	s_waitcnt lgkmcnt(0)
	v_cvt_pk_bf16_f32 v6, v3, v5
	ds_read_b32 v3, v13 offset:296
	ds_read_b32 v5, v13 offset:428
	v_lshl_add_u64 v[20:21], v[18:19], 0, v[20:21]
	s_waitcnt lgkmcnt(0)
	v_cvt_pk_bf16_f32 v7, v3, v5
	ds_read_b32 v3, v13 offset:560
	ds_read_b32 v5, v13 offset:692
	s_waitcnt lgkmcnt(0)
	v_cvt_pk_bf16_f32 v8, v3, v5
	ds_read_b32 v3, v13 offset:824
	ds_read_b32 v5, v13 offset:956
	s_waitcnt lgkmcnt(0)
	v_cvt_pk_bf16_f32 v9, v3, v5
	global_store_dwordx4 v[20:21], v[6:9], off
	ds_read_b32 v3, v13 offset:64
	ds_read_b32 v5, v13 offset:196
	v_or_b32_e32 v20, v4, v15
	v_ashrrev_i32_e32 v21, 31, v20
	v_lshlrev_b64 v[20:21], 12, v[20:21]
	s_waitcnt lgkmcnt(0)
	v_cvt_pk_bf16_f32 v6, v3, v5
	ds_read_b32 v3, v13 offset:328
	ds_read_b32 v5, v13 offset:460
	v_lshl_add_u64 v[20:21], v[18:19], 0, v[20:21]
	v_or_b32_e32 v4, v4, v16
	s_waitcnt lgkmcnt(0)
	v_cvt_pk_bf16_f32 v7, v3, v5
	ds_read_b32 v3, v13 offset:592
	ds_read_b32 v5, v13 offset:724
	s_waitcnt lgkmcnt(0)
	v_cvt_pk_bf16_f32 v8, v3, v5
	ds_read_b32 v3, v13 offset:856
	ds_read_b32 v5, v13 offset:988
	s_waitcnt lgkmcnt(0)
	v_cvt_pk_bf16_f32 v9, v3, v5
	global_store_dwordx4 v[20:21], v[6:9], off
	ds_read_b32 v3, v13 offset:96
	ds_read_b32 v5, v13 offset:228
	s_waitcnt lgkmcnt(0)
	v_cvt_pk_bf16_f32 v6, v3, v5
	ds_read_b32 v3, v13 offset:360
	ds_read_b32 v5, v13 offset:492
	s_waitcnt lgkmcnt(0)
	v_cvt_pk_bf16_f32 v7, v3, v5
	ds_read_b32 v3, v13 offset:624
	ds_read_b32 v5, v13 offset:756
	s_waitcnt lgkmcnt(0)
	v_cvt_pk_bf16_f32 v8, v3, v5
	ds_read_b32 v3, v13 offset:888
	ds_read_b32 v5, v13 offset:1020
	s_waitcnt lgkmcnt(0)
	v_cvt_pk_bf16_f32 v9, v3, v5
	v_ashrrev_i32_e32 v5, 31, v4
	v_lshlrev_b64 v[4:5], 12, v[4:5]
	v_lshl_add_u64 v[4:5], v[18:19], 0, v[4:5]
	global_store_dwordx4 v[4:5], v[6:9], off
	s_waitcnt lgkmcnt(0)
	v_add_u32_e32 v3, 0x500, v10
	v_mov_b32_e32 v10, v3
	s_andn2_b64 exec, exec, s[48:49]
	s_cbranch_execnz .LBB0_785

; __device__ __forceinline__ unsigned pk2(float lo, float hi) { return f2bf(lo) | (f2bf(hi) << 16); }
; __device__ __forceinline__ void ln_phase(const Params& p, const int layer, const int row_lo, const int row_hi, const int wg_id, const int n_wg) {
;     ...
;         for (int j = 0; j < 8; ++j) { const f32x4 gv = *((const f32x4*)g + lane + 64 * j), bv = *((const f32x4*)bb + lane + 64 * j);
;             const f32x4 y0 = v0[j] * rstd0 * gv + bv, y1 = v1[j] * rstd1 * gv + bv;
;             if (layer == 0) { o80[64 * j] = (unsigned long long)pk2(y0.x, y0.y) | ((unsigned long long)pk2(y0.z, y0.w) << 32);
;                 if (ok1) o81[64 * j] = (unsigned long long)pk2(y1.x, y1.y) | ((unsigned long long)pk2(y1.z, y1.w) << 32); }
;             else { zr0[64 * j] = y0; if (ok1) zr1[64 * j] = y1; } }
.LBB0_800:
	s_andn2_b64 vcc, exec, s[0:1]
	v_lshl_add_u64 v[102:103], v[70:71], 0, v[102:103]
	s_cbranch_vccnz .LBB0_804
	v_cvt_pk_bf16_f32 v6, v10, v11
	v_cvt_pk_bf16_f32 v7, v12, v13
	v_add_co_u32_e32 v8, vcc, 0xe6000000, v98
	s_nop 1
	v_addc_co_u32_e32 v9, vcc, -1, v99, vcc
	global_store_dwordx2 v[8:9], v[6:7], off
	s_and_saveexec_b64 s[0:1], s[38:39]
	s_cbranch_execz .LBB0_803
	v_cvt_pk_bf16_f32 v2, v2, v3
	v_cvt_pk_bf16_f32 v3, v4, v5
	global_store_dwordx2 v[102:103], v[2:3], off

; __device__ __forceinline__ unsigned pk2(float lo, float hi) { return f2bf(lo) | (f2bf(hi) << 16); }
; __device__ __forceinline__ void ln_phase(const Params& p, const int layer, const int row_lo, const int row_hi, const int wg_id, const int n_wg) {
;     ...
;         for (int j = 0; j < 8; ++j) { const f32x4 gv = *((const f32x4*)g + lane + 64 * j), bv = *((const f32x4*)bb + lane + 64 * j);
;             const f32x4 y0 = v0[j] * rstd0 * gv + bv, y1 = v1[j] * rstd1 * gv + bv;
;             if (layer == 0) { o80[64 * j] = (unsigned long long)pk2(y0.x, y0.y) | ((unsigned long long)pk2(y0.z, y0.w) << 32);
;                 if (ok1) o81[64 * j] = (unsigned long long)pk2(y1.x, y1.y) | ((unsigned long long)pk2(y1.z, y1.w) << 32); }
;             else { zr0[64 * j] = y0; if (ok1) zr1[64 * j] = y1; } }
.LBB0_808:
	s_andn2_b64 vcc, exec, s[0:1]
	s_cbranch_vccnz .LBB0_812
	v_cvt_pk_bf16_f32 v2, v2, v3
	v_cvt_pk_bf16_f32 v3, v4, v5
	v_add_co_u32_e32 v4, vcc, 0xe6000200, v98
	s_nop 1
	v_addc_co_u32_e32 v5, vcc, -1, v99, vcc
	global_store_dwordx2 v[4:5], v[2:3], off
	s_and_saveexec_b64 s[0:1], s[38:39]
	s_cbranch_execz .LBB0_811
	v_cvt_pk_bf16_f32 v2, v6, v7
	v_cvt_pk_bf16_f32 v3, v8, v9
	global_store_dwordx2 v[102:103], v[2:3], off offset:512

; __device__ __forceinline__ unsigned pk2(float lo, float hi) { return f2bf(lo) | (f2bf(hi) << 16); }
; __device__ __forceinline__ void ln_phase(const Params& p, const int layer, const int row_lo, const int row_hi, const int wg_id, const int n_wg) {
;     ...
;         for (int j = 0; j < 8; ++j) { const f32x4 gv = *((const f32x4*)g + lane + 64 * j), bv = *((const f32x4*)bb + lane + 64 * j);
;             const f32x4 y0 = v0[j] * rstd0 * gv + bv, y1 = v1[j] * rstd1 * gv + bv;
;             if (layer == 0) { o80[64 * j] = (unsigned long long)pk2(y0.x, y0.y) | ((unsigned long long)pk2(y0.z, y0.w) << 32);
;                 if (ok1) o81[64 * j] = (unsigned long long)pk2(y1.x, y1.y) | ((unsigned long long)pk2(y1.z, y1.w) << 32); }
;             else { zr0[64 * j] = y0; if (ok1) zr1[64 * j] = y1; } }
.LBB0_816:
	s_andn2_b64 vcc, exec, s[0:1]
	s_cbranch_vccnz .LBB0_820
	v_cvt_pk_bf16_f32 v6, v6, v7
	v_cvt_pk_bf16_f32 v7, v8, v9
	v_add_co_u32_e32 v8, vcc, 0xe6000400, v98
	s_nop 1
	v_addc_co_u32_e32 v9, vcc, -1, v99, vcc
	global_store_dwordx2 v[8:9], v[6:7], off
	s_and_saveexec_b64 s[0:1], s[38:39]
	s_cbranch_execz .LBB0_819
	v_cvt_pk_bf16_f32 v2, v2, v3
	v_cvt_pk_bf16_f32 v3, v4, v5
	global_store_dwordx2 v[102:103], v[2:3], off offset:1024

; __device__ __forceinline__ unsigned pk2(float lo, float hi) { return f2bf(lo) | (f2bf(hi) << 16); }
; __device__ __forceinline__ void ln_phase(const Params& p, const int layer, const int row_lo, const int row_hi, const int wg_id, const int n_wg) {
;     ...
;         for (int j = 0; j < 8; ++j) { const f32x4 gv = *((const f32x4*)g + lane + 64 * j), bv = *((const f32x4*)bb + lane + 64 * j);
;             const f32x4 y0 = v0[j] * rstd0 * gv + bv, y1 = v1[j] * rstd1 * gv + bv;
;             if (layer == 0) { o80[64 * j] = (unsigned long long)pk2(y0.x, y0.y) | ((unsigned long long)pk2(y0.z, y0.w) << 32);
;                 if (ok1) o81[64 * j] = (unsigned long long)pk2(y1.x, y1.y) | ((unsigned long long)pk2(y1.z, y1.w) << 32); }
;             else { zr0[64 * j] = y0; if (ok1) zr1[64 * j] = y1; } }
.LBB0_824:
	s_andn2_b64 vcc, exec, s[0:1]
	s_cbranch_vccnz .LBB0_828
	v_cvt_pk_bf16_f32 v6, v6, v7
	v_cvt_pk_bf16_f32 v7, v8, v9
	v_add_co_u32_e32 v8, vcc, 0xe6000600, v98
	s_nop 1
	v_addc_co_u32_e32 v9, vcc, -1, v99, vcc
	global_store_dwordx2 v[8:9], v[6:7], off
	s_and_saveexec_b64 s[0:1], s[38:39]
	s_cbranch_execz .LBB0_827
	v_cvt_pk_bf16_f32 v2, v2, v3
	v_cvt_pk_bf16_f32 v3, v4, v5
	global_store_dwordx2 v[102:103], v[2:3], off offset:1536

; __device__ __forceinline__ unsigned pk2(float lo, float hi) { return f2bf(lo) | (f2bf(hi) << 16); }
; __device__ __forceinline__ void ln_phase(const Params& p, const int layer, const int row_lo, const int row_hi, const int wg_id, const int n_wg) {
;     ...
;         for (int j = 0; j < 8; ++j) { const f32x4 gv = *((const f32x4*)g + lane + 64 * j), bv = *((const f32x4*)bb + lane + 64 * j);
;             const f32x4 y0 = v0[j] * rstd0 * gv + bv, y1 = v1[j] * rstd1 * gv + bv;
;             if (layer == 0) { o80[64 * j] = (unsigned long long)pk2(y0.x, y0.y) | ((unsigned long long)pk2(y0.z, y0.w) << 32);
;                 if (ok1) o81[64 * j] = (unsigned long long)pk2(y1.x, y1.y) | ((unsigned long long)pk2(y1.z, y1.w) << 32); }
;             else { zr0[64 * j] = y0; if (ok1) zr1[64 * j] = y1; } }
.LBB0_832:
	s_andn2_b64 vcc, exec, s[0:1]
	s_cbranch_vccnz .LBB0_836
	v_cvt_pk_bf16_f32 v6, v6, v7
	v_cvt_pk_bf16_f32 v7, v8, v9
	v_add_co_u32_e32 v8, vcc, 0xe6000800, v98
	s_nop 1
	v_addc_co_u32_e32 v9, vcc, -1, v99, vcc
	global_store_dwordx2 v[8:9], v[6:7], off
	s_and_saveexec_b64 s[0:1], s[38:39]
	s_cbranch_execz .LBB0_835
	v_cvt_pk_bf16_f32 v2, v2, v3
	v_cvt_pk_bf16_f32 v3, v4, v5
	global_store_dwordx2 v[102:103], v[2:3], off offset:2048

; __device__ __forceinline__ unsigned pk2(float lo, float hi) { return f2bf(lo) | (f2bf(hi) << 16); }
; __device__ __forceinline__ void ln_phase(const Params& p, const int layer, const int row_lo, const int row_hi, const int wg_id, const int n_wg) {
;     ...
;         for (int j = 0; j < 8; ++j) { const f32x4 gv = *((const f32x4*)g + lane + 64 * j), bv = *((const f32x4*)bb + lane + 64 * j);
;             const f32x4 y0 = v0[j] * rstd0 * gv + bv, y1 = v1[j] * rstd1 * gv + bv;
;             if (layer == 0) { o80[64 * j] = (unsigned long long)pk2(y0.x, y0.y) | ((unsigned long long)pk2(y0.z, y0.w) << 32);
;                 if (ok1) o81[64 * j] = (unsigned long long)pk2(y1.x, y1.y) | ((unsigned long long)pk2(y1.z, y1.w) << 32); }
;             else { zr0[64 * j] = y0; if (ok1) zr1[64 * j] = y1; } }
.LBB0_840:
	s_andn2_b64 vcc, exec, s[0:1]
	s_cbranch_vccnz .LBB0_844
	v_cvt_pk_bf16_f32 v6, v6, v7
	v_cvt_pk_bf16_f32 v7, v8, v9
	v_add_co_u32_e32 v8, vcc, 0xe6000a00, v98
	s_nop 1
	v_addc_co_u32_e32 v9, vcc, -1, v99, vcc
	global_store_dwordx2 v[8:9], v[6:7], off
	s_and_saveexec_b64 s[0:1], s[38:39]
	s_cbranch_execz .LBB0_843
	v_cvt_pk_bf16_f32 v2, v2, v3
	v_cvt_pk_bf16_f32 v3, v4, v5
	global_store_dwordx2 v[102:103], v[2:3], off offset:2560

; __device__ __forceinline__ unsigned pk2(float lo, float hi) { return f2bf(lo) | (f2bf(hi) << 16); }
; __device__ __forceinline__ void ln_phase(const Params& p, const int layer, const int row_lo, const int row_hi, const int wg_id, const int n_wg) {
;     ...
;         for (int j = 0; j < 8; ++j) { const f32x4 gv = *((const f32x4*)g + lane + 64 * j), bv = *((const f32x4*)bb + lane + 64 * j);
;             const f32x4 y0 = v0[j] * rstd0 * gv + bv, y1 = v1[j] * rstd1 * gv + bv;
;             if (layer == 0) { o80[64 * j] = (unsigned long long)pk2(y0.x, y0.y) | ((unsigned long long)pk2(y0.z, y0.w) << 32);
;                 if (ok1) o81[64 * j] = (unsigned long long)pk2(y1.x, y1.y) | ((unsigned long long)pk2(y1.z, y1.w) << 32); }
;             else { zr0[64 * j] = y0; if (ok1) zr1[64 * j] = y1; } }
.LBB0_848:
	s_andn2_b64 vcc, exec, s[0:1]
	s_cbranch_vccnz .LBB0_852
	v_cvt_pk_bf16_f32 v6, v6, v7
	v_cvt_pk_bf16_f32 v7, v8, v9
	v_add_co_u32_e32 v8, vcc, 0xe6000c00, v98
	s_nop 1
	v_addc_co_u32_e32 v9, vcc, -1, v99, vcc
	global_store_dwordx2 v[8:9], v[6:7], off
	s_and_saveexec_b64 s[0:1], s[38:39]
	s_cbranch_execz .LBB0_851
	v_cvt_pk_bf16_f32 v2, v2, v3
	v_cvt_pk_bf16_f32 v3, v4, v5
	global_store_dwordx2 v[102:103], v[2:3], off offset:3072

; __device__ __forceinline__ unsigned pk2(float lo, float hi) { return f2bf(lo) | (f2bf(hi) << 16); }
; __device__ __forceinline__ void ln_phase(const Params& p, const int layer, const int row_lo, const int row_hi, const int wg_id, const int n_wg) {
;     ...
;         for (int j = 0; j < 8; ++j) { const f32x4 gv = *((const f32x4*)g + lane + 64 * j), bv = *((const f32x4*)bb + lane + 64 * j);
;             const f32x4 y0 = v0[j] * rstd0 * gv + bv, y1 = v1[j] * rstd1 * gv + bv;
;             if (layer == 0) { o80[64 * j] = (unsigned long long)pk2(y0.x, y0.y) | ((unsigned long long)pk2(y0.z, y0.w) << 32);
;                 if (ok1) o81[64 * j] = (unsigned long long)pk2(y1.x, y1.y) | ((unsigned long long)pk2(y1.z, y1.w) << 32); }
;             else { zr0[64 * j] = y0; if (ok1) zr1[64 * j] = y1; } }
.LBB0_856:
	s_andn2_b64 vcc, exec, s[0:1]
	s_cbranch_vccnz .LBB0_791
	v_cvt_pk_bf16_f32 v6, v6, v7
	v_cvt_pk_bf16_f32 v7, v8, v9
	v_add_co_u32_e32 v8, vcc, 0xe6000e00, v98
	s_nop 1
	v_addc_co_u32_e32 v9, vcc, -1, v99, vcc
	global_store_dwordx2 v[8:9], v[6:7], off
	s_and_saveexec_b64 s[0:1], s[38:39]
	s_cbranch_execz .LBB0_790
	v_cvt_pk_bf16_f32 v2, v2, v3
	v_cvt_pk_bf16_f32 v3, v4, v5
	global_store_dwordx2 v[102:103], v[2:3], off offset:3584
	s_branch .LBB0_790

; __device__ __forceinline__ unsigned pk2(float lo, float hi) { return f2bf(lo) | (f2bf(hi) << 16); }
; __device__ __forceinline__ void ln_phase(const Params& p, const int layer, const int row_lo, const int row_hi, const int wg_id, const int n_wg) {
;     ...
;         for (int j = 0; j < 8; ++j) { const f32x4 gv = *((const f32x4*)g + lane + 64 * j), bv = *((const f32x4*)bb + lane + 64 * j);
;             const f32x4 y0 = v0[j] * rstd0 * gv + bv, y1 = v1[j] * rstd1 * gv + bv;
;             if (layer == 0) { o80[64 * j] = (unsigned long long)pk2(y0.x, y0.y) | ((unsigned long long)pk2(y0.z, y0.w) << 32);
;                 if (ok1) o81[64 * j] = (unsigned long long)pk2(y1.x, y1.y) | ((unsigned long long)pk2(y1.z, y1.w) << 32); }
;             else { zr0[64 * j] = y0; if (ok1) zr1[64 * j] = y1; } }
.LBB0_1037:
	s_andn2_b64 vcc, exec, s[0:1]
	v_lshl_add_u64 v[104:105], v[70:71], 0, v[104:105]
	s_cbranch_vccnz .LBB0_1041
	v_cvt_pk_bf16_f32 v6, v10, v11
	v_cvt_pk_bf16_f32 v7, v12, v13
	v_add_co_u32_e32 v8, vcc, 0xe6000000, v96
	s_nop 0
	v_addc_co_u32_e32 v9, vcc, -1, v97, vcc
	global_store_dwordx2 v[8:9], v[6:7], off
	s_and_saveexec_b64 s[0:1], s[38:39]
	s_cbranch_execz .LBB0_1040
	v_cvt_pk_bf16_f32 v2, v2, v3
	v_cvt_pk_bf16_f32 v3, v4, v5
	global_store_dwordx2 v[104:105], v[2:3], off

; __device__ __forceinline__ unsigned pk2(float lo, float hi) { return f2bf(lo) | (f2bf(hi) << 16); }
; __device__ __forceinline__ void ln_phase(const Params& p, const int layer, const int row_lo, const int row_hi, const int wg_id, const int n_wg) {
;     ...
;         for (int j = 0; j < 8; ++j) { const f32x4 gv = *((const f32x4*)g + lane + 64 * j), bv = *((const f32x4*)bb + lane + 64 * j);
;             const f32x4 y0 = v0[j] * rstd0 * gv + bv, y1 = v1[j] * rstd1 * gv + bv;
;             if (layer == 0) { o80[64 * j] = (unsigned long long)pk2(y0.x, y0.y) | ((unsigned long long)pk2(y0.z, y0.w) << 32);
;                 if (ok1) o81[64 * j] = (unsigned long long)pk2(y1.x, y1.y) | ((unsigned long long)pk2(y1.z, y1.w) << 32); }
;             else { zr0[64 * j] = y0; if (ok1) zr1[64 * j] = y1; } }
.LBB0_1045:
	s_andn2_b64 vcc, exec, s[0:1]
	s_cbranch_vccnz .LBB0_1049
	v_cvt_pk_bf16_f32 v2, v2, v3
	v_cvt_pk_bf16_f32 v3, v4, v5
	v_add_co_u32_e32 v4, vcc, 0xe6000200, v96
	s_nop 0
	v_addc_co_u32_e32 v5, vcc, -1, v97, vcc
	global_store_dwordx2 v[4:5], v[2:3], off
	s_and_saveexec_b64 s[0:1], s[38:39]
	s_cbranch_execz .LBB0_1048
	v_cvt_pk_bf16_f32 v2, v6, v7
	v_cvt_pk_bf16_f32 v3, v8, v9
	global_store_dwordx2 v[104:105], v[2:3], off offset:512

; __device__ __forceinline__ unsigned pk2(float lo, float hi) { return f2bf(lo) | (f2bf(hi) << 16); }
; __device__ __forceinline__ void ln_phase(const Params& p, const int layer, const int row_lo, const int row_hi, const int wg_id, const int n_wg) {
;     ...
;         for (int j = 0; j < 8; ++j) { const f32x4 gv = *((const f32x4*)g + lane + 64 * j), bv = *((const f32x4*)bb + lane + 64 * j);
;             const f32x4 y0 = v0[j] * rstd0 * gv + bv, y1 = v1[j] * rstd1 * gv + bv;
;             if (layer == 0) { o80[64 * j] = (unsigned long long)pk2(y0.x, y0.y) | ((unsigned long long)pk2(y0.z, y0.w) << 32);
;                 if (ok1) o81[64 * j] = (unsigned long long)pk2(y1.x, y1.y) | ((unsigned long long)pk2(y1.z, y1.w) << 32); }
;             else { zr0[64 * j] = y0; if (ok1) zr1[64 * j] = y1; } }
.LBB0_1053:
	s_andn2_b64 vcc, exec, s[0:1]
	s_cbranch_vccnz .LBB0_1057
	v_cvt_pk_bf16_f32 v6, v6, v7
	v_cvt_pk_bf16_f32 v7, v8, v9
	v_add_co_u32_e32 v8, vcc, 0xe6000400, v96
	s_nop 0
	v_addc_co_u32_e32 v9, vcc, -1, v97, vcc
	global_store_dwordx2 v[8:9], v[6:7], off
	s_and_saveexec_b64 s[0:1], s[38:39]
	s_cbranch_execz .LBB0_1056
	v_cvt_pk_bf16_f32 v2, v2, v3
	v_cvt_pk_bf16_f32 v3, v4, v5
	global_store_dwordx2 v[104:105], v[2:3], off offset:1024

; __device__ __forceinline__ unsigned pk2(float lo, float hi) { return f2bf(lo) | (f2bf(hi) << 16); }
; __device__ __forceinline__ void ln_phase(const Params& p, const int layer, const int row_lo, const int row_hi, const int wg_id, const int n_wg) {
;     ...
;         for (int j = 0; j < 8; ++j) { const f32x4 gv = *((const f32x4*)g + lane + 64 * j), bv = *((const f32x4*)bb + lane + 64 * j);
;             const f32x4 y0 = v0[j] * rstd0 * gv + bv, y1 = v1[j] * rstd1 * gv + bv;
;             if (layer == 0) { o80[64 * j] = (unsigned long long)pk2(y0.x, y0.y) | ((unsigned long long)pk2(y0.z, y0.w) << 32);
;                 if (ok1) o81[64 * j] = (unsigned long long)pk2(y1.x, y1.y) | ((unsigned long long)pk2(y1.z, y1.w) << 32); }
;             else { zr0[64 * j] = y0; if (ok1) zr1[64 * j] = y1; } }
.LBB0_1061:
	s_andn2_b64 vcc, exec, s[0:1]
	s_cbranch_vccnz .LBB0_1065
	v_cvt_pk_bf16_f32 v6, v6, v7
	v_cvt_pk_bf16_f32 v7, v8, v9
	v_add_co_u32_e32 v8, vcc, 0xe6000600, v96
	s_nop 0
	v_addc_co_u32_e32 v9, vcc, -1, v97, vcc
	global_store_dwordx2 v[8:9], v[6:7], off
	s_and_saveexec_b64 s[0:1], s[38:39]
	s_cbranch_execz .LBB0_1064
	v_cvt_pk_bf16_f32 v2, v2, v3
	v_cvt_pk_bf16_f32 v3, v4, v5
	global_store_dwordx2 v[104:105], v[2:3], off offset:1536

; __device__ __forceinline__ unsigned pk2(float lo, float hi) { return f2bf(lo) | (f2bf(hi) << 16); }
; __device__ __forceinline__ void ln_phase(const Params& p, const int layer, const int row_lo, const int row_hi, const int wg_id, const int n_wg) {
;     ...
;         for (int j = 0; j < 8; ++j) { const f32x4 gv = *((const f32x4*)g + lane + 64 * j), bv = *((const f32x4*)bb + lane + 64 * j);
;             const f32x4 y0 = v0[j] * rstd0 * gv + bv, y1 = v1[j] * rstd1 * gv + bv;
;             if (layer == 0) { o80[64 * j] = (unsigned long long)pk2(y0.x, y0.y) | ((unsigned long long)pk2(y0.z, y0.w) << 32);
;                 if (ok1) o81[64 * j] = (unsigned long long)pk2(y1.x, y1.y) | ((unsigned long long)pk2(y1.z, y1.w) << 32); }
;             else { zr0[64 * j] = y0; if (ok1) zr1[64 * j] = y1; } }
.LBB0_1069:
	s_andn2_b64 vcc, exec, s[0:1]
	s_cbranch_vccnz .LBB0_1073
	v_cvt_pk_bf16_f32 v6, v6, v7
	v_cvt_pk_bf16_f32 v7, v8, v9
	v_add_co_u32_e32 v8, vcc, 0xe6000800, v96
	s_nop 0
	v_addc_co_u32_e32 v9, vcc, -1, v97, vcc
	global_store_dwordx2 v[8:9], v[6:7], off
	s_and_saveexec_b64 s[0:1], s[38:39]
	s_cbranch_execz .LBB0_1072
	v_cvt_pk_bf16_f32 v2, v2, v3
	v_cvt_pk_bf16_f32 v3, v4, v5
	global_store_dwordx2 v[104:105], v[2:3], off offset:2048

; __device__ __forceinline__ unsigned pk2(float lo, float hi) { return f2bf(lo) | (f2bf(hi) << 16); }
; __device__ __forceinline__ void ln_phase(const Params& p, const int layer, const int row_lo, const int row_hi, const int wg_id, const int n_wg) {
;     ...
;         for (int j = 0; j < 8; ++j) { const f32x4 gv = *((const f32x4*)g + lane + 64 * j), bv = *((const f32x4*)bb + lane + 64 * j);
;             const f32x4 y0 = v0[j] * rstd0 * gv + bv, y1 = v1[j] * rstd1 * gv + bv;
;             if (layer == 0) { o80[64 * j] = (unsigned long long)pk2(y0.x, y0.y) | ((unsigned long long)pk2(y0.z, y0.w) << 32);
;                 if (ok1) o81[64 * j] = (unsigned long long)pk2(y1.x, y1.y) | ((unsigned long long)pk2(y1.z, y1.w) << 32); }
;             else { zr0[64 * j] = y0; if (ok1) zr1[64 * j] = y1; } }
.LBB0_1077:
	s_andn2_b64 vcc, exec, s[0:1]
	s_cbranch_vccnz .LBB0_1081
	v_cvt_pk_bf16_f32 v6, v6, v7
	v_cvt_pk_bf16_f32 v7, v8, v9
	v_add_co_u32_e32 v8, vcc, 0xe6000a00, v96
	s_nop 0
	v_addc_co_u32_e32 v9, vcc, -1, v97, vcc
	global_store_dwordx2 v[8:9], v[6:7], off
	s_and_saveexec_b64 s[0:1], s[38:39]
	s_cbranch_execz .LBB0_1080
	v_cvt_pk_bf16_f32 v2, v2, v3
	v_cvt_pk_bf16_f32 v3, v4, v5
	global_store_dwordx2 v[104:105], v[2:3], off offset:2560

; __device__ __forceinline__ unsigned pk2(float lo, float hi) { return f2bf(lo) | (f2bf(hi) << 16); }
; __device__ __forceinline__ void ln_phase(const Params& p, const int layer, const int row_lo, const int row_hi, const int wg_id, const int n_wg) {
;     ...
;         for (int j = 0; j < 8; ++j) { const f32x4 gv = *((const f32x4*)g + lane + 64 * j), bv = *((const f32x4*)bb + lane + 64 * j);
;             const f32x4 y0 = v0[j] * rstd0 * gv + bv, y1 = v1[j] * rstd1 * gv + bv;
;             if (layer == 0) { o80[64 * j] = (unsigned long long)pk2(y0.x, y0.y) | ((unsigned long long)pk2(y0.z, y0.w) << 32);
;                 if (ok1) o81[64 * j] = (unsigned long long)pk2(y1.x, y1.y) | ((unsigned long long)pk2(y1.z, y1.w) << 32); }
;             else { zr0[64 * j] = y0; if (ok1) zr1[64 * j] = y1; } }
.LBB0_1085:
	s_andn2_b64 vcc, exec, s[0:1]
	s_cbranch_vccnz .LBB0_1089
	v_cvt_pk_bf16_f32 v6, v6, v7
	v_cvt_pk_bf16_f32 v7, v8, v9
	v_add_co_u32_e32 v8, vcc, 0xe6000c00, v96
	s_nop 0
	v_addc_co_u32_e32 v9, vcc, -1, v97, vcc
	global_store_dwordx2 v[8:9], v[6:7], off
	s_and_saveexec_b64 s[0:1], s[38:39]
	s_cbranch_execz .LBB0_1088
	v_cvt_pk_bf16_f32 v2, v2, v3
	v_cvt_pk_bf16_f32 v3, v4, v5
	global_store_dwordx2 v[104:105], v[2:3], off offset:3072

; __device__ __forceinline__ unsigned pk2(float lo, float hi) { return f2bf(lo) | (f2bf(hi) << 16); }
; __device__ __forceinline__ void ln_phase(const Params& p, const int layer, const int row_lo, const int row_hi, const int wg_id, const int n_wg) {
;     ...
;         for (int j = 0; j < 8; ++j) { const f32x4 gv = *((const f32x4*)g + lane + 64 * j), bv = *((const f32x4*)bb + lane + 64 * j);
;             const f32x4 y0 = v0[j] * rstd0 * gv + bv, y1 = v1[j] * rstd1 * gv + bv;
;             if (layer == 0) { o80[64 * j] = (unsigned long long)pk2(y0.x, y0.y) | ((unsigned long long)pk2(y0.z, y0.w) << 32);
;                 if (ok1) o81[64 * j] = (unsigned long long)pk2(y1.x, y1.y) | ((unsigned long long)pk2(y1.z, y1.w) << 32); }
;             else { zr0[64 * j] = y0; if (ok1) zr1[64 * j] = y1; } }
.LBB0_1093:
	s_andn2_b64 vcc, exec, s[0:1]
	s_cbranch_vccnz .LBB0_1028
	v_cvt_pk_bf16_f32 v6, v6, v7
	v_cvt_pk_bf16_f32 v7, v8, v9
	v_add_co_u32_e32 v8, vcc, 0xe6000e00, v96
	s_nop 0
	v_addc_co_u32_e32 v9, vcc, -1, v97, vcc
	global_store_dwordx2 v[8:9], v[6:7], off
	s_and_saveexec_b64 s[0:1], s[38:39]
	s_cbranch_execz .LBB0_1027
	v_cvt_pk_bf16_f32 v2, v2, v3
	v_cvt_pk_bf16_f32 v3, v4, v5
	global_store_dwordx2 v[104:105], v[2:3], off offset:3584
	s_branch .LBB0_1027
